# nt policy extended: adaLN weight stream in phase 0, merge-gate loads in the branch-projection epilogue, residual loads in the output-projection epilogue, conv gate loads
# speedup vs baseline: 1.0319x; 1.0052x over previous
.LBB0_38:
	v_lshl_add_u64 v[44:45], v[24:25], 0, s[14:15]
	v_add_co_u32_e32 v46, vcc, s76, v44
	global_load_dwordx4 v[26:29], v[44:45], off
	s_nop 0
	v_addc_co_u32_e32 v47, vcc, 0, v45, vcc
	v_add_co_u32_e32 v48, vcc, s77, v44
	v_add_u32_e32 v21, 0x2000, v16
	s_nop 0
	v_addc_co_u32_e32 v49, vcc, 0, v45, vcc
	v_add_co_u32_e32 v52, vcc, s78, v44
	v_add_u32_e32 v23, 0x4000, v16
	s_nop 0
	v_addc_co_u32_e32 v53, vcc, 0, v45, vcc
	v_add_co_u32_e32 v56, vcc, s79, v44
	s_add_u32 s14, s14, 0x600000
	s_nop 0
	v_addc_co_u32_e32 v57, vcc, 0, v45, vcc
	v_add_co_u32_e32 v60, vcc, s80, v44
	s_addc_u32 s15, s15, 0
	s_nop 0
	v_addc_co_u32_e32 v61, vcc, 0, v45, vcc
	v_add_co_u32_e32 v64, vcc, s81, v44
	s_cmp_lg_u32 s14, 0x3000000
	s_nop 0
	v_addc_co_u32_e32 v65, vcc, 0, v45, vcc
	v_add_co_u32_e32 v68, vcc, s82, v44
	s_nop 1
	v_addc_co_u32_e32 v69, vcc, 0, v45, vcc
	global_load_dwordx4 v[44:47], v[46:47], off nt
	s_nop 0
	global_load_dwordx4 v[48:51], v[48:49], off nt
	s_nop 0
	global_load_dwordx4 v[52:55], v[52:53], off nt
	s_nop 0
	global_load_dwordx4 v[56:59], v[56:57], off nt
	s_nop 0
	global_load_dwordx4 v[60:63], v[60:61], off nt
	s_nop 0
	global_load_dwordx4 v[64:67], v[64:65], off nt
	s_nop 0
	global_load_dwordx4 v[68:71], v[68:69], off nt
	ds_read2_b32 v[72:73], v16 offset1:32
	ds_read2_b32 v[74:75], v16 offset0:64 offset1:96
	ds_read2_b32 v[76:77], v16 offset0:128 offset1:160
	ds_read2_b32 v[78:79], v16 offset0:192 offset1:224
	ds_read2_b32 v[80:81], v21 offset1:32
	ds_read2_b32 v[82:83], v23 offset1:32
	ds_read2_b32 v[84:85], v21 offset0:64 offset1:96
	ds_read2_b32 v[86:87], v23 offset0:64 offset1:96
	ds_read2_b32 v[88:89], v21 offset0:128 offset1:160
	ds_read2_b32 v[90:91], v23 offset0:128 offset1:160
	ds_read2_b32 v[92:93], v21 offset0:192 offset1:224
	ds_read2_b32 v[94:95], v23 offset0:192 offset1:224
	s_waitcnt lgkmcnt(7)
	v_mov_b32_e32 v104, v81
	s_waitcnt lgkmcnt(6)
	v_mov_b32_e32 v106, v83
	v_mov_b32_e32 v96, v73
	v_mov_b32_e32 v98, v75
	s_waitcnt lgkmcnt(5)
	v_mov_b32_e32 v108, v85
	s_waitcnt lgkmcnt(4)
	v_mov_b32_e32 v110, v87
	v_mov_b32_e32 v100, v77
	s_waitcnt lgkmcnt(3)
	v_mov_b32_e32 v112, v89
	s_waitcnt lgkmcnt(2)
	v_mov_b32_e32 v114, v91
	v_mov_b32_e32 v102, v79
	s_waitcnt lgkmcnt(1)
	v_mov_b32_e32 v116, v93
	s_waitcnt lgkmcnt(0)
	v_mov_b32_e32 v118, v95
	v_add_u32_e32 v16, 0x400, v16
	s_waitcnt vmcnt(7)
	v_pk_fma_f32 v[2:3], v[26:27], v[72:73], v[2:3] op_sel_hi:[1,0,1]
	v_pk_fma_f32 v[4:5], v[28:29], v[72:73], v[4:5] op_sel_hi:[1,0,1]
	v_pk_fma_f32 v[10:11], v[26:27], v[80:81], v[10:11] op_sel_hi:[1,0,1]
	v_pk_fma_f32 v[12:13], v[28:29], v[80:81], v[12:13] op_sel_hi:[1,0,1]
	v_pk_fma_f32 v[6:7], v[26:27], v[82:83], v[6:7] op_sel_hi:[1,0,1]
	v_pk_fma_f32 v[8:9], v[28:29], v[82:83], v[8:9] op_sel_hi:[1,0,1]
	s_waitcnt vmcnt(6)
	v_pk_fma_f32 v[2:3], v[44:45], v[96:97], v[2:3] op_sel_hi:[1,0,1]
	v_pk_fma_f32 v[4:5], v[46:47], v[96:97], v[4:5] op_sel_hi:[1,0,1]
	v_pk_fma_f32 v[10:11], v[44:45], v[104:105], v[10:11] op_sel_hi:[1,0,1]
	v_pk_fma_f32 v[12:13], v[46:47], v[104:105], v[12:13] op_sel_hi:[1,0,1]
	v_pk_fma_f32 v[6:7], v[44:45], v[106:107], v[6:7] op_sel_hi:[1,0,1]
	v_pk_fma_f32 v[8:9], v[46:47], v[106:107], v[8:9] op_sel_hi:[1,0,1]
	s_waitcnt vmcnt(5)
	v_pk_fma_f32 v[2:3], v[48:49], v[74:75], v[2:3] op_sel_hi:[1,0,1]
	v_pk_fma_f32 v[4:5], v[50:51], v[74:75], v[4:5] op_sel_hi:[1,0,1]
	v_pk_fma_f32 v[10:11], v[48:49], v[84:85], v[10:11] op_sel_hi:[1,0,1]
	v_pk_fma_f32 v[12:13], v[50:51], v[84:85], v[12:13] op_sel_hi:[1,0,1]
	v_pk_fma_f32 v[6:7], v[48:49], v[86:87], v[6:7] op_sel_hi:[1,0,1]
	v_pk_fma_f32 v[8:9], v[50:51], v[86:87], v[8:9] op_sel_hi:[1,0,1]
	s_waitcnt vmcnt(4)
	v_pk_fma_f32 v[2:3], v[52:53], v[98:99], v[2:3] op_sel_hi:[1,0,1]
	v_pk_fma_f32 v[4:5], v[54:55], v[98:99], v[4:5] op_sel_hi:[1,0,1]
	v_pk_fma_f32 v[10:11], v[52:53], v[108:109], v[10:11] op_sel_hi:[1,0,1]
	v_pk_fma_f32 v[12:13], v[54:55], v[108:109], v[12:13] op_sel_hi:[1,0,1]
	v_pk_fma_f32 v[6:7], v[52:53], v[110:111], v[6:7] op_sel_hi:[1,0,1]
	v_pk_fma_f32 v[8:9], v[54:55], v[110:111], v[8:9] op_sel_hi:[1,0,1]
	s_waitcnt vmcnt(3)
	v_pk_fma_f32 v[2:3], v[56:57], v[76:77], v[2:3] op_sel_hi:[1,0,1]
	v_pk_fma_f32 v[4:5], v[58:59], v[76:77], v[4:5] op_sel_hi:[1,0,1]
	v_pk_fma_f32 v[10:11], v[56:57], v[88:89], v[10:11] op_sel_hi:[1,0,1]
	v_pk_fma_f32 v[12:13], v[58:59], v[88:89], v[12:13] op_sel_hi:[1,0,1]
	v_pk_fma_f32 v[6:7], v[56:57], v[90:91], v[6:7] op_sel_hi:[1,0,1]
	v_pk_fma_f32 v[8:9], v[58:59], v[90:91], v[8:9] op_sel_hi:[1,0,1]
	s_waitcnt vmcnt(2)
	v_pk_fma_f32 v[2:3], v[60:61], v[100:101], v[2:3] op_sel_hi:[1,0,1]
	v_pk_fma_f32 v[4:5], v[62:63], v[100:101], v[4:5] op_sel_hi:[1,0,1]
	v_pk_fma_f32 v[10:11], v[60:61], v[112:113], v[10:11] op_sel_hi:[1,0,1]
	v_pk_fma_f32 v[12:13], v[62:63], v[112:113], v[12:13] op_sel_hi:[1,0,1]
	v_pk_fma_f32 v[6:7], v[60:61], v[114:115], v[6:7] op_sel_hi:[1,0,1]
	v_pk_fma_f32 v[8:9], v[62:63], v[114:115], v[8:9] op_sel_hi:[1,0,1]
	s_waitcnt vmcnt(1)
	v_pk_fma_f32 v[2:3], v[64:65], v[78:79], v[2:3] op_sel_hi:[1,0,1]
	v_pk_fma_f32 v[4:5], v[66:67], v[78:79], v[4:5] op_sel_hi:[1,0,1]
	v_pk_fma_f32 v[10:11], v[64:65], v[92:93], v[10:11] op_sel_hi:[1,0,1]
	v_pk_fma_f32 v[12:13], v[66:67], v[92:93], v[12:13] op_sel_hi:[1,0,1]
	v_pk_fma_f32 v[6:7], v[64:65], v[94:95], v[6:7] op_sel_hi:[1,0,1]
	v_pk_fma_f32 v[8:9], v[66:67], v[94:95], v[8:9] op_sel_hi:[1,0,1]
	s_waitcnt vmcnt(0)
	v_pk_fma_f32 v[2:3], v[68:69], v[102:103], v[2:3] op_sel_hi:[1,0,1]
	v_pk_fma_f32 v[4:5], v[70:71], v[102:103], v[4:5] op_sel_hi:[1,0,1]
	v_pk_fma_f32 v[10:11], v[68:69], v[116:117], v[10:11] op_sel_hi:[1,0,1]
	v_pk_fma_f32 v[12:13], v[70:71], v[116:117], v[12:13] op_sel_hi:[1,0,1]
	v_pk_fma_f32 v[6:7], v[68:69], v[118:119], v[6:7] op_sel_hi:[1,0,1]
	v_pk_fma_f32 v[8:9], v[70:71], v[118:119], v[8:9] op_sel_hi:[1,0,1]
	s_cbranch_scc1 .LBB0_38
	ds_write_b128 v38, v[2:5] offset:24576
	ds_write_b128 v38, v[10:13] offset:24592
	ds_write_b128 v38, v[6:9] offset:24608
	s_waitcnt lgkmcnt(0)
	s_barrier
	s_and_saveexec_b64 s[14:15], s[10:11]
	s_cbranch_execz .LBB0_7
	s_mul_i32 s13, s16, 0x1800
	s_add_i32 s13, s13, s12
	v_or_b32_e32 v2, s13, v15
	v_ashrrev_i32_e32 v3, 31, v2
	v_lshl_add_u64 v[2:3], v[2:3], 2, s[42:43]
	global_load_dword v16, v[2:3], off
	ds_read2st64_b32 v[2:3], v39 offset0:96 offset1:99
	ds_read2st64_b32 v[4:5], v39 offset0:102 offset1:105
	ds_read2st64_b32 v[6:7], v39 offset0:108 offset1:111
	ds_read2st64_b32 v[8:9], v39 offset0:114 offset1:117
	ds_read2st64_b32 v[10:11], v39 offset0:120 offset1:123
	ds_read2st64_b32 v[12:13], v39 offset0:126 offset1:129
	ds_read2st64_b32 v[24:25], v39 offset0:132 offset1:135
	ds_read2st64_b32 v[26:27], v39 offset0:138 offset1:141
	ds_read2st64_b32 v[28:29], v39 offset0:144 offset1:147
	ds_read2st64_b32 v[44:45], v39 offset0:150 offset1:153
	ds_read2st64_b32 v[46:47], v39 offset0:156 offset1:159
	ds_read2st64_b32 v[48:49], v39 offset0:162 offset1:165
	ds_read2st64_b32 v[50:51], v39 offset0:168 offset1:171
	ds_read2st64_b32 v[52:53], v39 offset0:174 offset1:177
	ds_read2st64_b32 v[54:55], v39 offset0:180 offset1:183
	ds_read2st64_b32 v[56:57], v39 offset0:186 offset1:189
	s_waitcnt lgkmcnt(14)
	v_add_f32_e32 v2, 0, v2
	v_add_f32_e32 v2, v2, v3
	v_add_f32_e32 v2, v2, v4
	v_add_f32_e32 v2, v2, v5
	s_waitcnt lgkmcnt(13)
	v_add_f32_e32 v2, v2, v6
	v_add_f32_e32 v2, v2, v7
	s_waitcnt lgkmcnt(12)
	v_add_f32_e32 v2, v2, v8
	v_add_f32_e32 v2, v2, v9
	s_waitcnt lgkmcnt(11)
	v_add_f32_e32 v2, v2, v10
	v_add_f32_e32 v2, v2, v11
	s_waitcnt lgkmcnt(10)
	v_add_f32_e32 v2, v2, v12
	v_add_f32_e32 v2, v2, v13
	s_waitcnt lgkmcnt(9)
	v_add_f32_e32 v2, v2, v24
	v_add_f32_e32 v2, v2, v25
	s_waitcnt lgkmcnt(8)
	v_add_f32_e32 v2, v2, v26
	v_add_f32_e32 v2, v2, v27
	s_waitcnt lgkmcnt(7)
	v_add_f32_e32 v2, v2, v28
	v_add_f32_e32 v2, v2, v29
	s_waitcnt lgkmcnt(6)
	v_add_f32_e32 v2, v2, v44
	v_add_f32_e32 v2, v2, v45
	s_waitcnt lgkmcnt(5)
	v_add_f32_e32 v2, v2, v46
	v_add_f32_e32 v2, v2, v47
	s_waitcnt lgkmcnt(4)
	v_add_f32_e32 v2, v2, v48
	v_add_f32_e32 v2, v2, v49
	s_waitcnt lgkmcnt(3)
	v_add_f32_e32 v2, v2, v50
	v_add_f32_e32 v2, v2, v51
	s_waitcnt lgkmcnt(2)
	v_add_f32_e32 v2, v2, v52
	v_mad_u64_u32 v[58:59], s[16:17], s16, 3, v[14:15]
	v_add_f32_e32 v2, v2, v53
	v_mul_lo_u32 v21, v58, s49
	s_waitcnt lgkmcnt(1)
	v_add_f32_e32 v2, v2, v54
	v_add_u32_e32 v21, s12, v21
	v_add_f32_e32 v2, v2, v55
	v_or_b32_e32 v58, v21, v15
	s_waitcnt lgkmcnt(0)
	v_add_f32_e32 v2, v2, v56
	v_ashrrev_i32_e32 v59, 31, v58
	v_add_f32_e32 v2, v2, v57
	s_waitcnt vmcnt(0)
	v_add_f32_e32 v4, v2, v16
	v_lshl_add_u64 v[2:3], v[58:59], 2, s[30:31]
	global_store_dword v[2:3], v4, off
	s_branch .LBB0_7

.LBB0_361:
	ds_read_b128 v[156:159], v72
	ds_read_b128 v[160:163], v72 offset:2064
	ds_read_b128 v[164:167], v72 offset:4128
	ds_read_b128 v[178:181], v72 offset:6192
	ds_read_b128 v[182:185], v72 offset:1024
	ds_read_b128 v[186:189], v72 offset:3088
	ds_read_b128 v[190:193], v72 offset:5152
	ds_read_b128 v[194:197], v72 offset:7216
	s_cmpk_lg_i32 s4, 0x7c00
	s_cselect_b32 s70, s4, 0x7800
	v_lshl_add_u64 v[70:71], s[70:71], 2, v[10:11]
	v_add_u32_e32 v73, 0x810, v72
	s_addk_i32 s4, 0x400
	s_cmpk_lg_u32 s4, 0x8000
	global_load_dwordx4 v[144:147], v[70:71], off offset:16
	global_load_dwordx4 v[140:143], v[70:71], off
	global_load_dwordx4 v[152:155], v[70:71], off offset:2064
	global_load_dwordx4 v[148:151], v[70:71], off offset:2048
	s_waitcnt lgkmcnt(7)
	v_lshlrev_b32_e32 v86, 16, v156
	v_and_b32_e32 v87, 0xffff0000, v156
	v_lshlrev_b32_e32 v88, 16, v157
	v_and_b32_e32 v89, 0xffff0000, v157
	v_lshlrev_b32_e32 v90, 16, v158
	v_and_b32_e32 v91, 0xffff0000, v158
	v_lshlrev_b32_e32 v92, 16, v159
	v_and_b32_e32 v93, 0xffff0000, v159
	v_pk_fma_f32 v[36:37], v[124:125], v[86:87], v[36:37]
	v_pk_fma_f32 v[34:35], v[126:127], v[88:89], v[34:35]
	v_pk_fma_f32 v[14:15], v[128:129], v[90:91], v[14:15]
	v_pk_fma_f32 v[12:13], v[130:131], v[92:93], v[12:13]
	s_waitcnt lgkmcnt(6)
	v_lshlrev_b32_e32 v94, 16, v160
	v_and_b32_e32 v95, 0xffff0000, v160
	v_lshlrev_b32_e32 v96, 16, v161
	v_and_b32_e32 v97, 0xffff0000, v161
	v_lshlrev_b32_e32 v98, 16, v162
	v_and_b32_e32 v99, 0xffff0000, v162
	v_lshlrev_b32_e32 v100, 16, v163
	v_and_b32_e32 v101, 0xffff0000, v163
	v_pk_fma_f32 v[68:69], v[124:125], v[94:95], v[68:69]
	v_pk_fma_f32 v[66:67], v[126:127], v[96:97], v[66:67]
	v_pk_fma_f32 v[64:65], v[128:129], v[98:99], v[64:65]
	v_pk_fma_f32 v[62:63], v[130:131], v[100:101], v[62:63]
	s_waitcnt lgkmcnt(5)
	v_lshlrev_b32_e32 v86, 16, v164
	v_and_b32_e32 v87, 0xffff0000, v164
	v_lshlrev_b32_e32 v88, 16, v165
	v_and_b32_e32 v89, 0xffff0000, v165
	v_lshlrev_b32_e32 v90, 16, v166
	v_and_b32_e32 v91, 0xffff0000, v166
	v_lshlrev_b32_e32 v92, 16, v167
	v_and_b32_e32 v93, 0xffff0000, v167
	v_pk_fma_f32 v[52:53], v[124:125], v[86:87], v[52:53]
	v_pk_fma_f32 v[50:51], v[126:127], v[88:89], v[50:51]
	v_pk_fma_f32 v[48:49], v[128:129], v[90:91], v[48:49]
	v_pk_fma_f32 v[46:47], v[130:131], v[92:93], v[46:47]
	s_waitcnt lgkmcnt(4)
	v_lshlrev_b32_e32 v94, 16, v178
	v_and_b32_e32 v95, 0xffff0000, v178
	v_lshlrev_b32_e32 v96, 16, v179
	v_and_b32_e32 v97, 0xffff0000, v179
	v_lshlrev_b32_e32 v98, 16, v180
	v_and_b32_e32 v99, 0xffff0000, v180
	v_lshlrev_b32_e32 v100, 16, v181
	v_and_b32_e32 v101, 0xffff0000, v181
	v_pk_fma_f32 v[30:31], v[124:125], v[94:95], v[30:31]
	v_pk_fma_f32 v[28:29], v[126:127], v[96:97], v[28:29]
	v_pk_fma_f32 v[26:27], v[128:129], v[98:99], v[26:27]
	v_pk_fma_f32 v[24:25], v[130:131], v[100:101], v[24:25]
	s_waitcnt lgkmcnt(3)
	v_lshlrev_b32_e32 v86, 16, v182
	v_and_b32_e32 v87, 0xffff0000, v182
	v_lshlrev_b32_e32 v88, 16, v183
	v_and_b32_e32 v89, 0xffff0000, v183
	v_lshlrev_b32_e32 v90, 16, v184
	v_and_b32_e32 v91, 0xffff0000, v184
	v_lshlrev_b32_e32 v92, 16, v185
	v_and_b32_e32 v93, 0xffff0000, v185
	v_pk_fma_f32 v[6:7], v[132:133], v[86:87], v[6:7]
	v_pk_fma_f32 v[4:5], v[134:135], v[88:89], v[4:5]
	v_pk_fma_f32 v[2:3], v[136:137], v[90:91], v[2:3]
	v_pk_fma_f32 v[0:1], v[138:139], v[92:93], v[0:1]
	s_waitcnt lgkmcnt(2)
	v_lshlrev_b32_e32 v94, 16, v186
	v_and_b32_e32 v95, 0xffff0000, v186
	v_lshlrev_b32_e32 v96, 16, v187
	v_and_b32_e32 v97, 0xffff0000, v187
	v_lshlrev_b32_e32 v98, 16, v188
	v_and_b32_e32 v99, 0xffff0000, v188
	v_lshlrev_b32_e32 v100, 16, v189
	v_and_b32_e32 v101, 0xffff0000, v189
	v_pk_fma_f32 v[60:61], v[132:133], v[94:95], v[60:61]
	v_pk_fma_f32 v[58:59], v[134:135], v[96:97], v[58:59]
	v_pk_fma_f32 v[56:57], v[136:137], v[98:99], v[56:57]
	v_pk_fma_f32 v[54:55], v[138:139], v[100:101], v[54:55]
	s_waitcnt lgkmcnt(1)
	v_lshlrev_b32_e32 v86, 16, v190
	v_and_b32_e32 v87, 0xffff0000, v190
	v_lshlrev_b32_e32 v88, 16, v191
	v_and_b32_e32 v89, 0xffff0000, v191
	v_lshlrev_b32_e32 v90, 16, v192
	v_and_b32_e32 v91, 0xffff0000, v192
	v_lshlrev_b32_e32 v92, 16, v193
	v_and_b32_e32 v93, 0xffff0000, v193
	v_pk_fma_f32 v[44:45], v[132:133], v[86:87], v[44:45]
	v_pk_fma_f32 v[42:43], v[134:135], v[88:89], v[42:43]
	v_pk_fma_f32 v[40:41], v[136:137], v[90:91], v[40:41]
	v_pk_fma_f32 v[38:39], v[138:139], v[92:93], v[38:39]
	s_waitcnt lgkmcnt(0)
	v_lshlrev_b32_e32 v94, 16, v194
	v_and_b32_e32 v95, 0xffff0000, v194
	v_lshlrev_b32_e32 v96, 16, v195
	v_and_b32_e32 v97, 0xffff0000, v195
	v_lshlrev_b32_e32 v98, 16, v196
	v_and_b32_e32 v99, 0xffff0000, v196
	v_lshlrev_b32_e32 v100, 16, v197
	v_and_b32_e32 v101, 0xffff0000, v197
	v_pk_fma_f32 v[22:23], v[132:133], v[94:95], v[22:23]
	v_pk_fma_f32 v[20:21], v[134:135], v[96:97], v[20:21]
	v_pk_fma_f32 v[18:19], v[136:137], v[98:99], v[18:19]
	v_pk_fma_f32 v[16:17], v[138:139], v[100:101], v[16:17]
	v_mov_b32_e32 v72, v73
	v_mov_b64_e32 v[32:33], v[70:71]
	s_waitcnt vmcnt(0)
	v_mov_b64_e32 v[124:125], v[140:141]
	v_mov_b64_e32 v[126:127], v[142:143]
	v_mov_b64_e32 v[128:129], v[144:145]
	v_mov_b64_e32 v[130:131], v[146:147]
	v_mov_b64_e32 v[132:133], v[148:149]
	v_mov_b64_e32 v[134:135], v[150:151]
	v_mov_b64_e32 v[136:137], v[152:153]
	v_mov_b64_e32 v[138:139], v[154:155]
	s_cbranch_scc1 .LBB0_361
	v_lshlrev_b32_e32 v82, 2, v8
	global_load_dwordx4 v[70:73], v82, s[58:59] offset:16
	global_load_dwordx4 v[74:77], v82, s[58:59]
	v_and_b32_e32 v9, -4, v9
	v_add_u32_e32 v32, s1, v9
	v_lshlrev_b32_e32 v168, 1, v8
	s_mov_b64 s[6:7], 0x3000
	s_waitcnt vmcnt(1)
	v_add_f32_e32 v89, v14, v70
	s_waitcnt vmcnt(0)
	v_add_f32_e32 v98, v36, v74
	v_add_f32_e32 v9, 0, v98
	v_add_f32_e32 v97, v37, v75
	v_add_f32_e32 v9, v9, v97
	v_add_f32_e32 v96, v34, v76
	v_add_f32_e32 v9, v9, v96
	v_add_f32_e32 v90, v35, v77
	v_add_f32_e32 v9, v9, v90
	v_add_f32_e32 v9, v9, v89
	v_add_f32_e32 v88, v15, v71
	v_add_f32_e32 v9, v9, v88
	v_add_f32_e32 v77, v12, v72
	v_add_f32_e32 v9, v9, v77
	v_add_f32_e32 v76, v13, v73
	v_add_f32_e32 v33, v9, v76
	global_load_dwordx4 v[8:11], v82, s[58:59] offset:2048
	global_load_dwordx4 v[12:15], v82, s[58:59] offset:2064
	v_mov_b64_e32 v[34:35], s[54:55]
	s_waitcnt vmcnt(1)
	v_add_f32_e32 v87, v6, v8
	v_add_f32_e32 v6, v33, v87
	v_add_f32_e32 v86, v7, v9
	v_add_f32_e32 v6, v6, v86
	v_add_f32_e32 v85, v4, v10
	v_add_f32_e32 v4, v6, v85
	v_add_f32_e32 v84, v5, v11
	v_add_f32_e32 v4, v4, v84
	s_waitcnt vmcnt(0)
	v_pk_add_f32 v[2:3], v[2:3], v[12:13]
	v_pk_add_f32 v[0:1], v[0:1], v[14:15]
	v_add_f32_e32 v4, v4, v2
	v_add_f32_e32 v4, v4, v3
	v_add_f32_e32 v4, v4, v0
	v_add_f32_e32 v4, v4, v1
	ds_bpermute_b32 v5, v121, v4
	v_ashrrev_i32_e32 v33, 31, v32
	s_waitcnt lgkmcnt(0)
	v_add_f32_e32 v4, v4, v5
	ds_bpermute_b32 v5, v119, v4
	s_waitcnt lgkmcnt(0)
	v_add_f32_e32 v4, v4, v5
	ds_bpermute_b32 v5, v78, v4
	s_waitcnt lgkmcnt(0)
	v_add_f32_e32 v4, v4, v5
	ds_bpermute_b32 v5, v79, v4
	s_waitcnt lgkmcnt(0)
	v_add_f32_e32 v4, v4, v5
	ds_bpermute_b32 v5, v80, v4
	s_waitcnt lgkmcnt(0)
	v_add_f32_e32 v4, v4, v5
	ds_bpermute_b32 v5, v81, v4
	s_waitcnt lgkmcnt(0)
	v_add_f32_e32 v5, v4, v5
	v_fmac_f32_e32 v97, 0xba800000, v5
	v_fmac_f32_e32 v98, 0xba800000, v5
	v_mul_f32_e32 v6, v97, v97
	v_fmac_f32_e32 v6, v98, v98
	v_fmac_f32_e32 v96, 0xba800000, v5
	v_fmac_f32_e32 v6, v96, v96
	v_fmac_f32_e32 v90, 0xba800000, v5
	v_fmac_f32_e32 v6, v90, v90
	v_fmac_f32_e32 v89, 0xba800000, v5
	v_fmac_f32_e32 v6, v89, v89
	v_fmac_f32_e32 v88, 0xba800000, v5
	v_fmac_f32_e32 v6, v88, v88
	v_fmac_f32_e32 v77, 0xba800000, v5
	v_fmac_f32_e32 v6, v77, v77
	v_fmac_f32_e32 v76, 0xba800000, v5
	v_fmac_f32_e32 v6, v76, v76
	v_fmac_f32_e32 v87, 0xba800000, v5
	v_fmac_f32_e32 v6, v87, v87
	v_fmac_f32_e32 v86, 0xba800000, v5
	v_mul_f32_e32 v4, 0x3a800000, v5
	v_fmac_f32_e32 v6, v86, v86
	v_fmac_f32_e32 v85, 0xba800000, v5
	v_fmac_f32_e32 v6, v85, v85
	v_fmac_f32_e32 v84, 0xba800000, v5
	v_pk_add_f32 v[72:73], v[2:3], v[4:5] op_sel_hi:[1,0] neg_lo:[0,1] neg_hi:[0,1]
	v_fmac_f32_e32 v6, v84, v84
	v_pk_mul_f32 v[2:3], v[72:73], v[72:73]
	v_pk_add_f32 v[70:71], v[0:1], v[4:5] op_sel_hi:[1,0] neg_lo:[0,1] neg_hi:[0,1]
	v_add_f32_e32 v2, v2, v6
	v_add_f32_e32 v2, v3, v2
	v_pk_mul_f32 v[0:1], v[70:71], v[70:71]
	s_nop 0
	v_add_f32_e32 v0, v0, v2
	v_add_f32_e32 v0, v1, v0
	ds_bpermute_b32 v1, v121, v0
	s_waitcnt lgkmcnt(0)
	v_add_f32_e32 v0, v0, v1
	ds_bpermute_b32 v1, v119, v0
	s_waitcnt lgkmcnt(0)
	v_add_f32_e32 v0, v0, v1
	ds_bpermute_b32 v1, v78, v0
	s_waitcnt lgkmcnt(0)
	v_add_f32_e32 v0, v0, v1
	ds_bpermute_b32 v1, v79, v0
	s_waitcnt lgkmcnt(0)
	v_add_f32_e32 v0, v0, v1
	ds_bpermute_b32 v1, v80, v0
	s_waitcnt lgkmcnt(0)
	v_add_f32_e32 v0, v0, v1
	ds_bpermute_b32 v1, v81, v0
	s_waitcnt lgkmcnt(0)
	v_add_f32_e32 v0, v0, v1
	v_fmamk_f32 v0, v0, 0x3a800000, v211
	v_cmp_gt_f32_e32 vcc, s80, v0
	v_mul_f32_e32 v1, 0x4b800000, v0
	s_nop 0
	v_cndmask_b32_e32 v0, v0, v1, vcc
	v_rsq_f32_e32 v0, v0
	s_nop 0
	v_mul_f32_e32 v1, 0x45800000, v0
	v_cndmask_b32_e32 v83, v0, v1, vcc
	v_mad_i64_i32 v[0:1], s[4:5], v32, s82, v[34:35]
	v_lshl_add_u64 v[74:75], v[0:1], 0, s[6:7]
	v_lshlrev_b64 v[0:1], 11, v[32:33]
	v_lshl_add_u64 v[36:37], s[56:57], 0, v[0:1]
	global_load_dwordx4 v[4:7], v82, s[60:61] offset:16
	global_load_dwordx4 v[12:15], v82, s[60:61]
	global_load_dwordx4 v[0:3], v82, s[62:63] offset:16
	global_load_dwordx4 v[8:11], v82, s[62:63]
	v_lshl_add_u64 v[92:93], v[74:75], 0, v[168:169]
	global_load_dwordx4 v[100:103], v[92:93], off nt
	v_mul_f32_e32 v98, v98, v83
	v_mul_f32_e32 v87, v87, v83
	s_waitcnt vmcnt(1)
	v_fma_f32 v8, v12, v98, v8
	v_mul_f32_e32 v12, 0xbfb8aa3b, v8
	v_exp_f32_e32 v12, v12
	s_waitcnt vmcnt(0)
	v_lshlrev_b32_e32 v95, 16, v101
	v_and_b32_e32 v94, 0xffff0000, v101
	v_lshlrev_b32_e32 v93, 16, v102
	v_add_f32_e32 v12, 1.0, v12
	v_and_b32_e32 v92, 0xffff0000, v102
	v_lshlrev_b32_e32 v91, 16, v103
	v_and_b32_e32 v33, 0xffff0000, v103
	v_lshlrev_b32_e32 v99, 16, v100
	v_rcp_f32_e32 v12, v12
	s_nop 0
	s_nop 0
	v_mul_f32_e32 v8, v8, v12
	v_mul_f32_e32 v12, 0xbfb8aa3b, v99
	v_exp_f32_e32 v12, v12
	v_and_b32_e32 v100, 0xffff0000, v100
	v_add_f32_e32 v12, 1.0, v12
	v_div_scale_f32 v98, s[4:5], v12, v12, 1.0
	v_rcp_f32_e32 v101, v98
	s_nop 0
	v_fma_f32 v102, -v98, v101, 1.0
	v_fmac_f32_e32 v101, v102, v101
	v_div_scale_f32 v102, vcc, 1.0, v12, 1.0
	v_mul_f32_e32 v103, v102, v101
	v_fma_f32 v104, -v98, v103, v102
	v_fmac_f32_e32 v103, v104, v101
	v_rcp_f32_e32 v12, v12
	s_nop 0
	s_nop 0
	v_mul_f32_e32 v12, v12, v99
	v_mul_f32_e32 v8, v12, v8
	v_mul_f32_e32 v12, v97, v83
	v_fma_f32 v9, v13, v12, v9
	v_mul_f32_e32 v12, 0xbfb8aa3b, v9
	v_exp_f32_e32 v12, v12
	s_nop 0
	v_add_f32_e32 v12, 1.0, v12
	s_nop 0
	v_rcp_f32_e32 v12, v12
	s_nop 0
	s_nop 0
	v_mul_f32_e32 v9, v9, v12
	v_mul_f32_e32 v12, 0xbfb8aa3b, v100
	v_exp_f32_e32 v12, v12
	s_nop 0
	v_add_f32_e32 v12, 1.0, v12
	v_div_scale_f32 v13, s[4:5], v12, v12, 1.0
	v_rcp_f32_e32 v97, v13
	s_nop 0
	v_fma_f32 v98, -v13, v97, 1.0
	v_fmac_f32_e32 v97, v98, v97
	v_div_scale_f32 v98, vcc, 1.0, v12, 1.0
	v_mul_f32_e32 v99, v98, v97
	v_fma_f32 v101, -v13, v99, v98
	v_fmac_f32_e32 v99, v101, v97
	v_rcp_f32_e32 v12, v12
	s_nop 0
	s_nop 0
	v_mul_f32_e32 v12, v12, v100
	v_mul_f32_e32 v9, v12, v9
	v_mul_f32_e32 v12, v96, v83
	v_fma_f32 v10, v14, v12, v10
	v_mul_f32_e32 v12, 0xbfb8aa3b, v10
	v_exp_f32_e32 v12, v12
	s_nop 0
	v_add_f32_e32 v12, 1.0, v12
	s_nop 0
	v_rcp_f32_e32 v12, v12
	s_nop 0
	s_nop 0
	v_mul_f32_e32 v10, v10, v12
	v_mul_f32_e32 v12, 0xbfb8aa3b, v95
	v_exp_f32_e32 v12, v12
	s_nop 0
	v_add_f32_e32 v12, 1.0, v12
	v_div_scale_f32 v13, s[4:5], v12, v12, 1.0
	v_rcp_f32_e32 v14, v13
	s_nop 0
	v_fma_f32 v96, -v13, v14, 1.0
	v_fmac_f32_e32 v14, v96, v14
	v_div_scale_f32 v96, vcc, 1.0, v12, 1.0
	v_mul_f32_e32 v97, v96, v14
	v_fma_f32 v98, -v13, v97, v96
	v_fmac_f32_e32 v97, v98, v14
	v_rcp_f32_e32 v12, v12
	s_nop 0
	s_nop 0
	v_mul_f32_e32 v12, v12, v95
	v_mul_f32_e32 v10, v12, v10
	v_mul_f32_e32 v12, v90, v83
	v_fmac_f32_e32 v11, v15, v12
	v_mul_f32_e32 v12, 0xbfb8aa3b, v11
	v_exp_f32_e32 v12, v12
	s_nop 0
	v_add_f32_e32 v12, 1.0, v12
	s_nop 0
	v_rcp_f32_e32 v12, v12
	s_nop 0
	s_nop 0
	v_mul_f32_e32 v11, v11, v12
	v_mul_f32_e32 v12, 0xbfb8aa3b, v94
	v_exp_f32_e32 v12, v12
	s_nop 0
	v_add_f32_e32 v12, 1.0, v12
	s_nop 0
	v_rcp_f32_e32 v12, v12
	s_nop 0
	s_nop 0
	v_mul_f32_e32 v12, v12, v94
	v_mul_f32_e32 v11, v12, v11
	v_mul_f32_e32 v12, v89, v83
	v_fma_f32 v0, v4, v12, v0
	v_mul_f32_e32 v4, 0xbfb8aa3b, v0
	v_exp_f32_e32 v4, v4
	s_nop 0
	v_add_f32_e32 v4, 1.0, v4
	s_nop 0
	v_rcp_f32_e32 v4, v4
	s_nop 0
	s_nop 0
	v_mul_f32_e32 v0, v0, v4
	v_mul_f32_e32 v4, 0xbfb8aa3b, v93
	v_exp_f32_e32 v4, v4
	s_nop 0
	v_add_f32_e32 v4, 1.0, v4
	s_nop 0
	v_rcp_f32_e32 v4, v4
	s_nop 0
	s_nop 0
	v_mul_f32_e32 v4, v4, v93
	v_mul_f32_e32 v4, v4, v0
	v_mul_f32_e32 v0, v88, v83
	v_fma_f32 v0, v5, v0, v1
	v_mul_f32_e32 v1, 0xbfb8aa3b, v0
	v_exp_f32_e32 v1, v1
	s_nop 0
	v_add_f32_e32 v1, 1.0, v1
	s_nop 0
	v_rcp_f32_e32 v1, v1
	s_nop 0
	s_nop 0
	v_mul_f32_e32 v0, v0, v1
	v_mul_f32_e32 v1, 0xbfb8aa3b, v92
	v_exp_f32_e32 v1, v1
	s_nop 0
	v_add_f32_e32 v1, 1.0, v1
	s_nop 0
	v_rcp_f32_e32 v1, v1
	s_nop 0
	s_nop 0
	v_mul_f32_e32 v1, v1, v92
	v_mul_f32_e32 v5, v1, v0
	v_mul_f32_e32 v0, v77, v83
	v_fma_f32 v0, v6, v0, v2
	v_mul_f32_e32 v1, 0xbfb8aa3b, v0
	v_exp_f32_e32 v1, v1
	s_nop 0
	v_add_f32_e32 v1, 1.0, v1
	s_nop 0
	v_rcp_f32_e32 v1, v1
	s_nop 0
	s_nop 0
	v_mul_f32_e32 v0, v0, v1
	v_mul_f32_e32 v1, 0xbfb8aa3b, v91
	v_exp_f32_e32 v1, v1
	s_nop 0
	v_add_f32_e32 v1, 1.0, v1
	s_nop 0
	v_rcp_f32_e32 v1, v1
	s_nop 0
	s_nop 0
	v_mul_f32_e32 v1, v1, v91
	v_mul_f32_e32 v6, v1, v0
	v_mul_f32_e32 v0, v76, v83
	v_fmac_f32_e32 v3, v7, v0
	v_mul_f32_e32 v0, 0xbfb8aa3b, v3
	v_exp_f32_e32 v0, v0
	v_lshl_add_u64 v[76:77], v[36:37], 0, v[168:169]
	v_or_b32_e32 v36, 0x400, v168
	v_mov_b32_e32 v37, v169
	v_add_f32_e32 v0, 1.0, v0
	v_lshl_add_u64 v[74:75], v[74:75], 0, v[36:37]
	v_rcp_f32_e32 v0, v0
	s_nop 0
	v_mul_f32_e32 v1, 0xbfb8aa3b, v33
	v_exp_f32_e32 v1, v1
	v_mul_f32_e32 v0, v3, v0
	v_add_f32_e32 v1, 1.0, v1
	s_nop 0
	v_rcp_f32_e32 v1, v1
	s_nop 0
	s_nop 0
	v_mul_f32_e32 v1, v1, v33
	v_mul_f32_e32 v3, v1, v0
	v_cvt_pk_bf16_f32 v0, v8, v9
	v_cvt_pk_bf16_f32 v1, v10, v11
	v_cvt_pk_bf16_f32 v2, v4, v5
	v_cvt_pk_bf16_f32 v3, v6, v3
	global_store_dwordx4 v[76:77], v[0:3], off
	global_load_dwordx4 v[4:7], v82, s[60:61] offset:2064
	global_load_dwordx4 v[12:15], v82, s[60:61] offset:2048
	s_nop 0
	global_load_dwordx4 v[0:3], v82, s[62:63] offset:2064
	global_load_dwordx4 v[8:11], v82, s[62:63] offset:2048
	global_load_dwordx4 v[88:91], v[74:75], off nt
	s_waitcnt vmcnt(1)
	v_fma_f32 v8, v87, v12, v8
	v_mul_f32_e32 v12, 0xbfb8aa3b, v8
	v_exp_f32_e32 v12, v12
	s_waitcnt vmcnt(0)
	v_lshlrev_b32_e32 v92, 16, v88
	v_and_b32_e32 v93, 0xffff0000, v88
	v_lshlrev_b32_e32 v88, 16, v90
	v_add_f32_e32 v12, 1.0, v12
	v_and_b32_e32 v75, 0xffff0000, v90
	v_lshlrev_b32_e32 v74, 16, v91
	v_and_b32_e32 v33, 0xffff0000, v91
	v_lshlrev_b32_e32 v94, 16, v89
	v_rcp_f32_e32 v12, v12
	s_nop 0
	s_nop 0
	v_mul_f32_e32 v8, v8, v12
	v_mul_f32_e32 v12, 0xbfb8aa3b, v92
	v_exp_f32_e32 v12, v12
	v_and_b32_e32 v89, 0xffff0000, v89
	v_add_f32_e32 v12, 1.0, v12
	v_div_scale_f32 v87, s[4:5], v12, v12, 1.0
	v_rcp_f32_e32 v90, v87
	s_nop 0
	v_fma_f32 v91, -v87, v90, 1.0
	v_fmac_f32_e32 v90, v91, v90
	v_div_scale_f32 v91, vcc, 1.0, v12, 1.0
	v_mul_f32_e32 v95, v91, v90
	v_fma_f32 v96, -v87, v95, v91
	v_fmac_f32_e32 v95, v96, v90
	v_rcp_f32_e32 v12, v12
	s_nop 0
	s_nop 0
	v_mul_f32_e32 v12, v12, v92
	v_mul_f32_e32 v8, v8, v12
	v_mul_f32_e32 v12, v86, v83
	v_fma_f32 v9, v12, v13, v9
	v_mul_f32_e32 v12, 0xbfb8aa3b, v9
	v_exp_f32_e32 v12, v12
	s_nop 0
	v_add_f32_e32 v12, 1.0, v12
	s_nop 0
	v_rcp_f32_e32 v12, v12
	s_nop 0
	s_nop 0
	v_mul_f32_e32 v9, v9, v12
	v_mul_f32_e32 v12, 0xbfb8aa3b, v93
	v_exp_f32_e32 v12, v12
	s_nop 0
	v_add_f32_e32 v12, 1.0, v12
	v_div_scale_f32 v13, s[4:5], v12, v12, 1.0
	v_rcp_f32_e32 v86, v13
	s_nop 0
	v_fma_f32 v87, -v13, v86, 1.0
	v_fmac_f32_e32 v86, v87, v86
	v_div_scale_f32 v87, vcc, 1.0, v12, 1.0
	v_mul_f32_e32 v90, v87, v86
	v_fma_f32 v91, -v13, v90, v87
	v_rcp_f32_e32 v12, v12
	s_nop 0
	s_nop 0
	v_mul_f32_e32 v12, v12, v93
	v_mul_f32_e32 v9, v9, v12
	v_mul_f32_e32 v12, v85, v83
	v_fma_f32 v10, v12, v14, v10
	v_mul_f32_e32 v12, 0xbfb8aa3b, v10
	v_exp_f32_e32 v12, v12
	s_nop 0
	v_add_f32_e32 v12, 1.0, v12
	s_nop 0
	v_rcp_f32_e32 v12, v12
	s_nop 0
	s_nop 0
	v_mul_f32_e32 v10, v10, v12
	v_mul_f32_e32 v12, 0xbfb8aa3b, v94
	v_exp_f32_e32 v12, v12
	s_nop 0
	v_add_f32_e32 v12, 1.0, v12
	s_nop 0
	v_rcp_f32_e32 v12, v12
	s_nop 0
	s_nop 0
	v_mul_f32_e32 v12, v12, v94
	v_mul_f32_e32 v10, v10, v12
	v_mul_f32_e32 v12, v84, v83
	v_fmac_f32_e32 v11, v12, v15
	v_mul_f32_e32 v12, 0xbfb8aa3b, v11
	v_exp_f32_e32 v12, v12
	s_nop 0
	v_add_f32_e32 v12, 1.0, v12
	s_nop 0
	v_rcp_f32_e32 v12, v12
	s_nop 0
	s_nop 0
	v_mul_f32_e32 v11, v11, v12
	v_mul_f32_e32 v12, 0xbfb8aa3b, v89
	v_exp_f32_e32 v12, v12
	s_nop 0
	v_add_f32_e32 v12, 1.0, v12
	s_nop 0
	v_rcp_f32_e32 v12, v12
	s_nop 0
	s_nop 0
	v_mul_f32_e32 v12, v12, v89
	v_mul_f32_e32 v11, v11, v12
	v_mul_f32_e32 v12, v72, v83
	v_fma_f32 v0, v12, v4, v0
	v_mul_f32_e32 v4, 0xbfb8aa3b, v0
	v_exp_f32_e32 v4, v4
	s_nop 0
	v_add_f32_e32 v4, 1.0, v4
	s_nop 0
	v_rcp_f32_e32 v4, v4
	s_nop 0
	s_nop 0
	v_mul_f32_e32 v0, v0, v4
	v_mul_f32_e32 v4, 0xbfb8aa3b, v88
	v_exp_f32_e32 v4, v4
	s_nop 0
	v_add_f32_e32 v4, 1.0, v4
	s_nop 0
	v_rcp_f32_e32 v4, v4
	s_nop 0
	s_nop 0
	v_mul_f32_e32 v4, v4, v88
	v_mul_f32_e32 v4, v0, v4
	v_mul_f32_e32 v0, v73, v83
	v_fma_f32 v0, v0, v5, v1
	v_mul_f32_e32 v1, 0xbfb8aa3b, v0
	v_exp_f32_e32 v1, v1
	s_nop 0
	v_add_f32_e32 v1, 1.0, v1
	s_nop 0
	v_rcp_f32_e32 v1, v1
	s_nop 0
	s_nop 0
	v_mul_f32_e32 v0, v0, v1
	v_mul_f32_e32 v1, 0xbfb8aa3b, v75
	v_exp_f32_e32 v1, v1
	s_nop 0
	v_add_f32_e32 v1, 1.0, v1
	s_nop 0
	v_rcp_f32_e32 v1, v1
	s_nop 0
	s_nop 0
	v_mul_f32_e32 v1, v1, v75
	v_mul_f32_e32 v5, v0, v1
	v_mul_f32_e32 v0, v70, v83
	v_fma_f32 v0, v0, v6, v2
	v_mul_f32_e32 v1, 0xbfb8aa3b, v0
	v_exp_f32_e32 v1, v1
	s_nop 0
	v_add_f32_e32 v1, 1.0, v1
	s_nop 0
	v_rcp_f32_e32 v1, v1
	s_nop 0
	s_nop 0
	v_mul_f32_e32 v0, v0, v1
	v_mul_f32_e32 v1, 0xbfb8aa3b, v74
	v_exp_f32_e32 v1, v1
	s_nop 0
	v_add_f32_e32 v1, 1.0, v1
	s_nop 0
	v_rcp_f32_e32 v1, v1
	s_nop 0
	s_nop 0
	v_mul_f32_e32 v1, v1, v74
	v_mul_f32_e32 v6, v0, v1
	v_mul_f32_e32 v0, v71, v83
	v_fmac_f32_e32 v3, v0, v7
	v_mul_f32_e32 v0, 0xbfb8aa3b, v3
	v_exp_f32_e32 v0, v0
	s_nop 0
	v_add_f32_e32 v0, 1.0, v0
	s_nop 0
	v_rcp_f32_e32 v0, v0
	s_nop 0
	v_mul_f32_e32 v1, 0xbfb8aa3b, v33
	v_exp_f32_e32 v1, v1
	v_mul_f32_e32 v0, v3, v0
	v_add_f32_e32 v1, 1.0, v1
	s_nop 0
	v_rcp_f32_e32 v1, v1
	s_nop 0
	s_nop 0
	v_mul_f32_e32 v1, v1, v33
	v_mul_f32_e32 v3, v0, v1
	v_cvt_pk_bf16_f32 v0, v8, v9
	v_cvt_pk_bf16_f32 v1, v10, v11
	v_cvt_pk_bf16_f32 v2, v4, v5
	v_cvt_pk_bf16_f32 v3, v6, v3
	global_store_dwordx4 v[76:77], v[0:3], off offset:1024
	global_load_dwordx4 v[0:3], v82, s[58:59] offset:16
	s_nop 0
	global_load_dwordx4 v[4:7], v82, s[58:59]
	s_waitcnt vmcnt(0)
	v_add_f32_e32 v76, v68, v4
	v_add_f32_e32 v4, 0, v76
	v_add_f32_e32 v74, v69, v5
	v_add_f32_e32 v4, v4, v74
	v_add_f32_e32 v72, v66, v6
	v_add_f32_e32 v4, v4, v72
	v_add_f32_e32 v70, v67, v7
	v_add_f32_e32 v4, v4, v70
	v_add_f32_e32 v69, v64, v0
	v_add_f32_e32 v0, v4, v69
	v_add_f32_e32 v68, v65, v1
	v_add_f32_e32 v0, v0, v68
	v_add_f32_e32 v67, v62, v2
	v_add_f32_e32 v0, v0, v67
	v_add_f32_e32 v66, v63, v3
	v_add_f32_e32 v8, v0, v66
	global_load_dwordx4 v[0:3], v82, s[58:59] offset:2048
	global_load_dwordx4 v[4:7], v82, s[58:59] offset:2064
	s_waitcnt vmcnt(1)
	v_add_f32_e32 v65, v60, v0
	v_add_f32_e32 v0, v8, v65
	v_add_f32_e32 v64, v61, v1
	v_add_f32_e32 v0, v0, v64
	v_add_f32_e32 v63, v58, v2
	v_add_f32_e32 v0, v0, v63
	v_add_f32_e32 v62, v59, v3
	v_add_f32_e32 v8, v0, v62
	s_waitcnt vmcnt(0)
	v_pk_add_f32 v[2:3], v[56:57], v[4:5]
	v_pk_add_f32 v[0:1], v[54:55], v[6:7]
	v_add_f32_e32 v4, v8, v2
	v_add_f32_e32 v4, v4, v3
	v_add_f32_e32 v4, v4, v0
	v_add_f32_e32 v4, v4, v1
	ds_bpermute_b32 v5, v121, v4
	s_waitcnt lgkmcnt(0)
	v_add_f32_e32 v4, v4, v5
	ds_bpermute_b32 v5, v119, v4
	s_waitcnt lgkmcnt(0)
	v_add_f32_e32 v4, v4, v5
	ds_bpermute_b32 v5, v78, v4
	s_waitcnt lgkmcnt(0)
	v_add_f32_e32 v4, v4, v5
	ds_bpermute_b32 v5, v79, v4
	s_waitcnt lgkmcnt(0)
	v_add_f32_e32 v4, v4, v5
	ds_bpermute_b32 v5, v80, v4
	s_waitcnt lgkmcnt(0)
	v_add_f32_e32 v4, v4, v5
	ds_bpermute_b32 v5, v81, v4
	s_waitcnt lgkmcnt(0)
	v_add_f32_e32 v5, v4, v5
	v_fmac_f32_e32 v74, 0xba800000, v5
	v_fmac_f32_e32 v76, 0xba800000, v5
	v_mul_f32_e32 v6, v74, v74
	v_fmac_f32_e32 v6, v76, v76
	v_fmac_f32_e32 v72, 0xba800000, v5
	v_fmac_f32_e32 v6, v72, v72
	v_fmac_f32_e32 v70, 0xba800000, v5
	v_fmac_f32_e32 v6, v70, v70
	v_fmac_f32_e32 v69, 0xba800000, v5
	v_fmac_f32_e32 v6, v69, v69
	v_fmac_f32_e32 v68, 0xba800000, v5
	v_fmac_f32_e32 v6, v68, v68
	v_fmac_f32_e32 v67, 0xba800000, v5
	v_fmac_f32_e32 v6, v67, v67
	v_fmac_f32_e32 v66, 0xba800000, v5
	v_fmac_f32_e32 v6, v66, v66
	v_fmac_f32_e32 v65, 0xba800000, v5
	v_fmac_f32_e32 v6, v65, v65
	v_fmac_f32_e32 v64, 0xba800000, v5
	v_mul_f32_e32 v4, 0x3a800000, v5
	v_fmac_f32_e32 v6, v64, v64
	v_fmac_f32_e32 v63, 0xba800000, v5
	v_fmac_f32_e32 v6, v63, v63
	v_fmac_f32_e32 v62, 0xba800000, v5
	v_pk_add_f32 v[56:57], v[2:3], v[4:5] op_sel_hi:[1,0] neg_lo:[0,1] neg_hi:[0,1]
	v_fmac_f32_e32 v6, v62, v62
	v_pk_mul_f32 v[2:3], v[56:57], v[56:57]
	v_pk_add_f32 v[54:55], v[0:1], v[4:5] op_sel_hi:[1,0] neg_lo:[0,1] neg_hi:[0,1]
	v_add_f32_e32 v2, v2, v6
	v_add_f32_e32 v2, v3, v2
	v_pk_mul_f32 v[0:1], v[54:55], v[54:55]
	s_nop 0
	v_add_f32_e32 v0, v0, v2
	v_add_f32_e32 v1, v1, v0
	ds_bpermute_b32 v2, v121, v1
	v_or_b32_e32 v0, 1, v32
	s_waitcnt lgkmcnt(0)
	v_add_f32_e32 v1, v1, v2
	ds_bpermute_b32 v2, v119, v1
	s_waitcnt lgkmcnt(0)
	v_add_f32_e32 v1, v1, v2
	ds_bpermute_b32 v2, v78, v1
	s_waitcnt lgkmcnt(0)
	v_add_f32_e32 v1, v1, v2
	ds_bpermute_b32 v2, v79, v1
	s_waitcnt lgkmcnt(0)
	v_add_f32_e32 v1, v1, v2
	ds_bpermute_b32 v2, v80, v1
	s_waitcnt lgkmcnt(0)
	v_add_f32_e32 v1, v1, v2
	ds_bpermute_b32 v2, v81, v1
	s_waitcnt lgkmcnt(0)
	v_add_f32_e32 v1, v1, v2
	v_fmamk_f32 v1, v1, 0x3a800000, v211
	v_cmp_gt_f32_e32 vcc, s80, v1
	v_mul_f32_e32 v2, 0x4b800000, v1
	s_nop 0
	v_cndmask_b32_e32 v1, v1, v2, vcc
	v_rsq_f32_e32 v1, v1
	s_nop 0
	v_mul_f32_e32 v2, 0x45800000, v1
	v_cndmask_b32_e32 v33, v1, v2, vcc
	v_ashrrev_i32_e32 v1, 31, v0
	v_mad_i64_i32 v[2:3], s[4:5], v0, s82, v[34:35]
	v_lshlrev_b64 v[0:1], 11, v[0:1]
	v_lshl_add_u64 v[58:59], v[2:3], 0, s[6:7]
	v_lshl_add_u64 v[60:61], s[56:57], 0, v[0:1]
	global_load_dwordx4 v[4:7], v82, s[60:61] offset:16
	global_load_dwordx4 v[12:15], v82, s[60:61]
	global_load_dwordx4 v[0:3], v82, s[62:63] offset:16
	global_load_dwordx4 v[8:11], v82, s[62:63]
	v_lshl_add_u64 v[84:85], v[58:59], 0, v[168:169]
	global_load_dwordx4 v[84:87], v[84:85], off nt
	v_mul_f32_e32 v76, v76, v33
	v_lshl_add_u64 v[60:61], v[60:61], 0, v[168:169]
	v_lshl_add_u64 v[58:59], v[58:59], 0, v[36:37]
	v_mul_f32_e32 v65, v65, v33
	s_waitcnt vmcnt(1)
	v_fma_f32 v8, v12, v76, v8
	v_mul_f32_e32 v12, 0xbfb8aa3b, v8
	v_exp_f32_e32 v12, v12
	s_waitcnt vmcnt(0)
	v_lshlrev_b32_e32 v89, 16, v85
	v_and_b32_e32 v83, 0xffff0000, v85
	v_lshlrev_b32_e32 v77, 16, v86
	v_add_f32_e32 v12, 1.0, v12
	v_and_b32_e32 v75, 0xffff0000, v86
	v_lshlrev_b32_e32 v73, 16, v87
	v_and_b32_e32 v71, 0xffff0000, v87
	v_lshlrev_b32_e32 v88, 16, v84
	v_rcp_f32_e32 v12, v12
	s_nop 0
	s_nop 0
	v_mul_f32_e32 v8, v8, v12
	v_mul_f32_e32 v12, 0xbfb8aa3b, v88
	v_exp_f32_e32 v12, v12
	v_and_b32_e32 v84, 0xffff0000, v84
	v_add_f32_e32 v12, 1.0, v12
	v_div_scale_f32 v76, s[4:5], v12, v12, 1.0
	v_rcp_f32_e32 v85, v76
	s_nop 0
	v_fma_f32 v86, -v76, v85, 1.0
	v_fmac_f32_e32 v85, v86, v85
	v_div_scale_f32 v86, vcc, 1.0, v12, 1.0
	v_mul_f32_e32 v87, v86, v85
	v_fma_f32 v90, -v76, v87, v86
	v_fmac_f32_e32 v87, v90, v85
	v_rcp_f32_e32 v12, v12
	s_nop 0
	s_nop 0
	v_mul_f32_e32 v12, v12, v88
	v_mul_f32_e32 v8, v12, v8
	v_mul_f32_e32 v12, v74, v33
	v_fma_f32 v9, v13, v12, v9
	v_mul_f32_e32 v12, 0xbfb8aa3b, v9
	v_exp_f32_e32 v12, v12
	s_nop 0
	v_add_f32_e32 v12, 1.0, v12
	s_nop 0
	v_rcp_f32_e32 v12, v12
	s_nop 0
	s_nop 0
	v_mul_f32_e32 v9, v9, v12
	v_mul_f32_e32 v12, 0xbfb8aa3b, v84
	v_exp_f32_e32 v12, v12
	s_nop 0
	v_add_f32_e32 v12, 1.0, v12
	v_div_scale_f32 v13, s[4:5], v12, v12, 1.0
	v_rcp_f32_e32 v74, v13
	s_nop 0
	v_fma_f32 v76, -v13, v74, 1.0
	v_fmac_f32_e32 v74, v76, v74
	v_div_scale_f32 v76, vcc, 1.0, v12, 1.0
	v_mul_f32_e32 v85, v76, v74
	v_fma_f32 v86, -v13, v85, v76
	v_fmac_f32_e32 v85, v86, v74
	v_rcp_f32_e32 v12, v12
	s_nop 0
	s_nop 0
	v_mul_f32_e32 v12, v12, v84
	v_mul_f32_e32 v9, v12, v9
	v_mul_f32_e32 v12, v72, v33
	v_fma_f32 v10, v14, v12, v10
	v_mul_f32_e32 v12, 0xbfb8aa3b, v10
	v_exp_f32_e32 v12, v12
	s_nop 0
	v_add_f32_e32 v12, 1.0, v12
	s_nop 0
	v_rcp_f32_e32 v12, v12
	s_nop 0
	s_nop 0
	v_mul_f32_e32 v10, v10, v12
	v_mul_f32_e32 v12, 0xbfb8aa3b, v89
	v_exp_f32_e32 v12, v12
	s_nop 0
	v_add_f32_e32 v12, 1.0, v12
	v_div_scale_f32 v13, s[4:5], v12, v12, 1.0
	v_rcp_f32_e32 v14, v13
	s_nop 0
	v_fma_f32 v72, -v13, v14, 1.0
	v_fmac_f32_e32 v14, v72, v14
	v_div_scale_f32 v72, vcc, 1.0, v12, 1.0
	v_mul_f32_e32 v74, v72, v14
	v_fma_f32 v76, -v13, v74, v72
	v_rcp_f32_e32 v12, v12
	s_nop 0
	s_nop 0
	v_mul_f32_e32 v12, v12, v89
	v_mul_f32_e32 v10, v12, v10
	v_mul_f32_e32 v12, v70, v33
	v_fmac_f32_e32 v11, v15, v12
	v_mul_f32_e32 v12, 0xbfb8aa3b, v11
	v_exp_f32_e32 v12, v12
	s_nop 0
	v_add_f32_e32 v12, 1.0, v12
	s_nop 0
	v_rcp_f32_e32 v12, v12
	s_nop 0
	s_nop 0
	v_mul_f32_e32 v11, v11, v12
	v_mul_f32_e32 v12, 0xbfb8aa3b, v83
	v_exp_f32_e32 v12, v12
	s_nop 0
	v_add_f32_e32 v12, 1.0, v12
	s_nop 0
	v_rcp_f32_e32 v12, v12
	s_nop 0
	s_nop 0
	v_mul_f32_e32 v12, v12, v83
	v_mul_f32_e32 v11, v12, v11
	v_mul_f32_e32 v12, v69, v33
	v_fma_f32 v0, v4, v12, v0
	v_mul_f32_e32 v4, 0xbfb8aa3b, v0
	v_exp_f32_e32 v4, v4
	s_nop 0
	v_add_f32_e32 v4, 1.0, v4
	s_nop 0
	v_rcp_f32_e32 v4, v4
	s_nop 0
	s_nop 0
	v_mul_f32_e32 v0, v0, v4
	v_mul_f32_e32 v4, 0xbfb8aa3b, v77
	v_exp_f32_e32 v4, v4
	s_nop 0
	v_add_f32_e32 v4, 1.0, v4
	s_nop 0
	v_rcp_f32_e32 v4, v4
	s_nop 0
	s_nop 0
	v_mul_f32_e32 v4, v4, v77
	v_mul_f32_e32 v4, v4, v0
	v_mul_f32_e32 v0, v68, v33
	v_fma_f32 v0, v5, v0, v1
	v_mul_f32_e32 v1, 0xbfb8aa3b, v0
	v_exp_f32_e32 v1, v1
	s_nop 0
	v_add_f32_e32 v1, 1.0, v1
	s_nop 0
	v_rcp_f32_e32 v1, v1
	s_nop 0
	s_nop 0
	v_mul_f32_e32 v0, v0, v1
	v_mul_f32_e32 v1, 0xbfb8aa3b, v75
	v_exp_f32_e32 v1, v1
	s_nop 0
	v_add_f32_e32 v1, 1.0, v1
	s_nop 0
	v_rcp_f32_e32 v1, v1
	s_nop 0
	s_nop 0
	v_mul_f32_e32 v1, v1, v75
	v_mul_f32_e32 v5, v1, v0
	v_mul_f32_e32 v0, v67, v33
	v_fma_f32 v0, v6, v0, v2
	v_mul_f32_e32 v1, 0xbfb8aa3b, v0
	v_exp_f32_e32 v1, v1
	s_nop 0
	v_add_f32_e32 v1, 1.0, v1
	s_nop 0
	v_rcp_f32_e32 v1, v1
	s_nop 0
	s_nop 0
	v_mul_f32_e32 v0, v0, v1
	v_mul_f32_e32 v1, 0xbfb8aa3b, v73
	v_exp_f32_e32 v1, v1
	s_nop 0
	v_add_f32_e32 v1, 1.0, v1
	s_nop 0
	v_rcp_f32_e32 v1, v1
	s_nop 0
	s_nop 0
	v_mul_f32_e32 v1, v1, v73
	v_mul_f32_e32 v6, v1, v0
	v_mul_f32_e32 v0, v66, v33
	v_fmac_f32_e32 v3, v7, v0
	v_mul_f32_e32 v0, 0xbfb8aa3b, v3
	v_exp_f32_e32 v0, v0
	s_nop 0
	v_add_f32_e32 v0, 1.0, v0
	s_nop 0
	v_rcp_f32_e32 v0, v0
	s_nop 0
	v_mul_f32_e32 v1, 0xbfb8aa3b, v71
	v_exp_f32_e32 v1, v1
	v_mul_f32_e32 v0, v3, v0
	v_add_f32_e32 v1, 1.0, v1
	s_nop 0
	v_rcp_f32_e32 v1, v1
	s_nop 0
	s_nop 0
	v_mul_f32_e32 v1, v1, v71
	v_mul_f32_e32 v3, v1, v0
	v_cvt_pk_bf16_f32 v0, v8, v9
	v_cvt_pk_bf16_f32 v1, v10, v11
	v_cvt_pk_bf16_f32 v2, v4, v5
	v_cvt_pk_bf16_f32 v3, v6, v3
	global_store_dwordx4 v[60:61], v[0:3], off
	global_load_dwordx4 v[4:7], v82, s[60:61] offset:2064
	global_load_dwordx4 v[12:15], v82, s[60:61] offset:2048
	s_nop 0
	global_load_dwordx4 v[0:3], v82, s[62:63] offset:2064
	global_load_dwordx4 v[8:11], v82, s[62:63] offset:2048
	global_load_dwordx4 v[68:71], v[58:59], off nt
	s_waitcnt vmcnt(1)
	v_fma_f32 v8, v65, v12, v8
	v_mul_f32_e32 v12, 0xbfb8aa3b, v8
	v_exp_f32_e32 v12, v12
	s_waitcnt vmcnt(0)
	v_lshlrev_b32_e32 v72, 16, v68
	v_and_b32_e32 v73, 0xffff0000, v68
	v_lshlrev_b32_e32 v74, 16, v69
	v_add_f32_e32 v12, 1.0, v12
	v_and_b32_e32 v68, 0xffff0000, v69
	v_lshlrev_b32_e32 v67, 16, v70
	v_and_b32_e32 v66, 0xffff0000, v70
	v_lshlrev_b32_e32 v59, 16, v71
	v_and_b32_e32 v58, 0xffff0000, v71
	v_rcp_f32_e32 v12, v12
	s_nop 0
	s_nop 0
	v_mul_f32_e32 v8, v8, v12
	v_mul_f32_e32 v12, 0xbfb8aa3b, v72
	v_exp_f32_e32 v12, v12
	s_nop 0
	v_add_f32_e32 v12, 1.0, v12
	v_div_scale_f32 v65, s[4:5], v12, v12, 1.0
	v_rcp_f32_e32 v69, v65
	s_nop 0
	v_fma_f32 v70, -v65, v69, 1.0
	v_fmac_f32_e32 v69, v70, v69
	v_div_scale_f32 v70, vcc, 1.0, v12, 1.0
	v_mul_f32_e32 v71, v70, v69
	v_fma_f32 v75, -v65, v71, v70
	v_fmac_f32_e32 v71, v75, v69
	v_rcp_f32_e32 v12, v12
	s_nop 0
	s_nop 0
	v_mul_f32_e32 v12, v12, v72
	v_mul_f32_e32 v8, v8, v12
	v_mul_f32_e32 v12, v64, v33
	v_fma_f32 v9, v12, v13, v9
	v_mul_f32_e32 v12, 0xbfb8aa3b, v9
	v_exp_f32_e32 v12, v12
	s_nop 0
	v_add_f32_e32 v12, 1.0, v12
	s_nop 0
	v_rcp_f32_e32 v12, v12
	s_nop 0
	s_nop 0
	v_mul_f32_e32 v9, v9, v12
	v_mul_f32_e32 v12, 0xbfb8aa3b, v73
	v_exp_f32_e32 v12, v12
	s_nop 0
	v_add_f32_e32 v12, 1.0, v12
	v_div_scale_f32 v13, s[4:5], v12, v12, 1.0
	v_rcp_f32_e32 v64, v13
	s_nop 0
	v_fma_f32 v65, -v13, v64, 1.0
	v_fmac_f32_e32 v64, v65, v64
	v_div_scale_f32 v65, vcc, 1.0, v12, 1.0
	v_mul_f32_e32 v69, v65, v64
	v_fma_f32 v70, -v13, v69, v65
	v_rcp_f32_e32 v12, v12
	s_nop 0
	s_nop 0
	v_mul_f32_e32 v12, v12, v73
	v_mul_f32_e32 v9, v9, v12
	v_mul_f32_e32 v12, v63, v33
	v_fma_f32 v10, v12, v14, v10
	v_mul_f32_e32 v12, 0xbfb8aa3b, v10
	v_exp_f32_e32 v12, v12
	s_nop 0
	v_add_f32_e32 v12, 1.0, v12
	s_nop 0
	v_rcp_f32_e32 v12, v12
	s_nop 0
	s_nop 0
	v_mul_f32_e32 v10, v10, v12
	v_mul_f32_e32 v12, 0xbfb8aa3b, v74
	v_exp_f32_e32 v12, v12
	s_nop 0
	v_add_f32_e32 v12, 1.0, v12
	s_nop 0
	v_rcp_f32_e32 v12, v12
	s_nop 0
	s_nop 0
	v_mul_f32_e32 v12, v12, v74
	v_mul_f32_e32 v10, v10, v12
	v_mul_f32_e32 v12, v62, v33
	v_fmac_f32_e32 v11, v12, v15
	v_mul_f32_e32 v12, 0xbfb8aa3b, v11
	v_exp_f32_e32 v12, v12
	s_nop 0
	v_add_f32_e32 v12, 1.0, v12
	s_nop 0
	v_rcp_f32_e32 v12, v12
	s_nop 0
	s_nop 0
	v_mul_f32_e32 v11, v11, v12
	v_mul_f32_e32 v12, 0xbfb8aa3b, v68
	v_exp_f32_e32 v12, v12
	s_nop 0
	v_add_f32_e32 v12, 1.0, v12
	s_nop 0
	v_rcp_f32_e32 v12, v12
	s_nop 0
	s_nop 0
	v_mul_f32_e32 v12, v12, v68
	v_mul_f32_e32 v11, v11, v12
	v_mul_f32_e32 v12, v56, v33
	v_fma_f32 v0, v12, v4, v0
	v_mul_f32_e32 v4, 0xbfb8aa3b, v0
	v_exp_f32_e32 v4, v4
	s_nop 0
	v_add_f32_e32 v4, 1.0, v4
	s_nop 0
	v_rcp_f32_e32 v4, v4
	s_nop 0
	s_nop 0
	v_mul_f32_e32 v0, v0, v4
	v_mul_f32_e32 v4, 0xbfb8aa3b, v67
	v_exp_f32_e32 v4, v4
	s_nop 0
	v_add_f32_e32 v4, 1.0, v4
	s_nop 0
	v_rcp_f32_e32 v4, v4
	s_nop 0
	s_nop 0
	v_mul_f32_e32 v4, v4, v67
	v_mul_f32_e32 v4, v0, v4
	v_mul_f32_e32 v0, v57, v33
	v_fma_f32 v0, v0, v5, v1
	v_mul_f32_e32 v1, 0xbfb8aa3b, v0
	v_exp_f32_e32 v1, v1
	s_nop 0
	v_add_f32_e32 v1, 1.0, v1
	s_nop 0
	v_rcp_f32_e32 v1, v1
	s_nop 0
	s_nop 0
	v_mul_f32_e32 v0, v0, v1
	v_mul_f32_e32 v1, 0xbfb8aa3b, v66
	v_exp_f32_e32 v1, v1
	s_nop 0
	v_add_f32_e32 v1, 1.0, v1
	s_nop 0
	v_rcp_f32_e32 v1, v1
	s_nop 0
	s_nop 0
	v_mul_f32_e32 v1, v1, v66
	v_mul_f32_e32 v5, v0, v1
	v_mul_f32_e32 v0, v54, v33
	v_fma_f32 v0, v0, v6, v2
	v_mul_f32_e32 v1, 0xbfb8aa3b, v0
	v_exp_f32_e32 v1, v1
	s_nop 0
	v_add_f32_e32 v1, 1.0, v1
	s_nop 0
	v_rcp_f32_e32 v1, v1
	s_nop 0
	s_nop 0
	v_mul_f32_e32 v0, v0, v1
	v_mul_f32_e32 v1, 0xbfb8aa3b, v59
	v_exp_f32_e32 v1, v1
	s_nop 0
	v_add_f32_e32 v1, 1.0, v1
	s_nop 0
	v_rcp_f32_e32 v1, v1
	s_nop 0
	s_nop 0
	v_mul_f32_e32 v1, v1, v59
	v_mul_f32_e32 v6, v0, v1
	v_mul_f32_e32 v0, v55, v33
	v_fmac_f32_e32 v3, v0, v7
	v_mul_f32_e32 v0, 0xbfb8aa3b, v3
	v_exp_f32_e32 v0, v0
	s_nop 0
	v_add_f32_e32 v0, 1.0, v0
	s_nop 0
	v_rcp_f32_e32 v0, v0
	s_nop 0
	v_mul_f32_e32 v1, 0xbfb8aa3b, v58
	v_exp_f32_e32 v1, v1
	v_mul_f32_e32 v0, v3, v0
	v_add_f32_e32 v1, 1.0, v1
	s_nop 0
	v_rcp_f32_e32 v1, v1
	s_nop 0
	s_nop 0
	v_mul_f32_e32 v1, v1, v58
	v_mul_f32_e32 v3, v0, v1
	v_cvt_pk_bf16_f32 v0, v8, v9
	v_cvt_pk_bf16_f32 v1, v10, v11
	v_cvt_pk_bf16_f32 v2, v4, v5
	v_cvt_pk_bf16_f32 v3, v6, v3
	global_store_dwordx4 v[60:61], v[0:3], off offset:1024
	global_load_dwordx4 v[0:3], v82, s[58:59] offset:16
	s_nop 0
	global_load_dwordx4 v[4:7], v82, s[58:59]
	s_waitcnt vmcnt(0)
	v_add_f32_e32 v60, v52, v4
	v_add_f32_e32 v4, 0, v60
	v_add_f32_e32 v58, v53, v5
	v_add_f32_e32 v4, v4, v58
	v_add_f32_e32 v56, v50, v6
	v_add_f32_e32 v4, v4, v56
	v_add_f32_e32 v54, v51, v7
	v_add_f32_e32 v4, v4, v54
	v_add_f32_e32 v53, v48, v0
	v_add_f32_e32 v0, v4, v53
	v_add_f32_e32 v52, v49, v1
	v_add_f32_e32 v0, v0, v52
	v_add_f32_e32 v51, v46, v2
	v_add_f32_e32 v0, v0, v51
	v_add_f32_e32 v50, v47, v3
	v_add_f32_e32 v8, v0, v50
	global_load_dwordx4 v[0:3], v82, s[58:59] offset:2048
	global_load_dwordx4 v[4:7], v82, s[58:59] offset:2064
	s_waitcnt vmcnt(1)
	v_add_f32_e32 v49, v44, v0
	v_add_f32_e32 v0, v8, v49
	v_add_f32_e32 v48, v45, v1
	v_add_f32_e32 v0, v0, v48
	v_add_f32_e32 v47, v42, v2
	v_add_f32_e32 v0, v0, v47
	v_add_f32_e32 v46, v43, v3
	v_add_f32_e32 v8, v0, v46
	s_waitcnt vmcnt(0)
	v_pk_add_f32 v[2:3], v[40:41], v[4:5]
	v_pk_add_f32 v[0:1], v[38:39], v[6:7]
	v_add_f32_e32 v4, v8, v2
	v_add_f32_e32 v4, v4, v3
	v_add_f32_e32 v4, v4, v0
	v_add_f32_e32 v4, v4, v1
	ds_bpermute_b32 v5, v121, v4
	s_waitcnt lgkmcnt(0)
	v_add_f32_e32 v4, v4, v5
	ds_bpermute_b32 v5, v119, v4
	s_waitcnt lgkmcnt(0)
	v_add_f32_e32 v4, v4, v5
	ds_bpermute_b32 v5, v78, v4
	s_waitcnt lgkmcnt(0)
	v_add_f32_e32 v4, v4, v5
	ds_bpermute_b32 v5, v79, v4
	s_waitcnt lgkmcnt(0)
	v_add_f32_e32 v4, v4, v5
	ds_bpermute_b32 v5, v80, v4
	s_waitcnt lgkmcnt(0)
	v_add_f32_e32 v4, v4, v5
	ds_bpermute_b32 v5, v81, v4
	s_waitcnt lgkmcnt(0)
	v_add_f32_e32 v5, v4, v5
	v_fmac_f32_e32 v58, 0xba800000, v5
	v_fmac_f32_e32 v60, 0xba800000, v5
	v_mul_f32_e32 v6, v58, v58
	v_fmac_f32_e32 v6, v60, v60
	v_fmac_f32_e32 v56, 0xba800000, v5
	v_fmac_f32_e32 v6, v56, v56
	v_fmac_f32_e32 v54, 0xba800000, v5
	v_fmac_f32_e32 v6, v54, v54
	v_fmac_f32_e32 v53, 0xba800000, v5
	v_fmac_f32_e32 v6, v53, v53
	v_fmac_f32_e32 v52, 0xba800000, v5
	v_fmac_f32_e32 v6, v52, v52
	v_fmac_f32_e32 v51, 0xba800000, v5
	v_fmac_f32_e32 v6, v51, v51
	v_fmac_f32_e32 v50, 0xba800000, v5
	v_fmac_f32_e32 v6, v50, v50
	v_fmac_f32_e32 v49, 0xba800000, v5
	v_fmac_f32_e32 v6, v49, v49
	v_fmac_f32_e32 v48, 0xba800000, v5
	v_mul_f32_e32 v4, 0x3a800000, v5
	v_fmac_f32_e32 v6, v48, v48
	v_fmac_f32_e32 v47, 0xba800000, v5
	v_fmac_f32_e32 v6, v47, v47
	v_fmac_f32_e32 v46, 0xba800000, v5
	v_pk_add_f32 v[40:41], v[2:3], v[4:5] op_sel_hi:[1,0] neg_lo:[0,1] neg_hi:[0,1]
	v_fmac_f32_e32 v6, v46, v46
	v_pk_mul_f32 v[2:3], v[40:41], v[40:41]
	v_pk_add_f32 v[38:39], v[0:1], v[4:5] op_sel_hi:[1,0] neg_lo:[0,1] neg_hi:[0,1]
	v_add_f32_e32 v2, v2, v6
	v_add_f32_e32 v2, v3, v2
	v_pk_mul_f32 v[0:1], v[38:39], v[38:39]
	s_nop 0
	v_add_f32_e32 v0, v0, v2
	v_add_f32_e32 v1, v1, v0
	ds_bpermute_b32 v2, v121, v1
	v_or_b32_e32 v0, 2, v32
	s_waitcnt lgkmcnt(0)
	v_add_f32_e32 v1, v1, v2
	ds_bpermute_b32 v2, v119, v1
	s_waitcnt lgkmcnt(0)
	v_add_f32_e32 v1, v1, v2
	ds_bpermute_b32 v2, v78, v1
	s_waitcnt lgkmcnt(0)
	v_add_f32_e32 v1, v1, v2
	ds_bpermute_b32 v2, v79, v1
	s_waitcnt lgkmcnt(0)
	v_add_f32_e32 v1, v1, v2
	ds_bpermute_b32 v2, v80, v1
	s_waitcnt lgkmcnt(0)
	v_add_f32_e32 v1, v1, v2
	ds_bpermute_b32 v2, v81, v1
	s_waitcnt lgkmcnt(0)
	v_add_f32_e32 v1, v1, v2
	v_fmamk_f32 v1, v1, 0x3a800000, v211
	v_cmp_gt_f32_e32 vcc, s80, v1
	v_mul_f32_e32 v2, 0x4b800000, v1
	s_nop 0
	v_cndmask_b32_e32 v1, v1, v2, vcc
	v_rsq_f32_e32 v1, v1
	s_nop 0
	v_mul_f32_e32 v2, 0x45800000, v1
	v_cndmask_b32_e32 v33, v1, v2, vcc
	v_ashrrev_i32_e32 v1, 31, v0
	v_mad_i64_i32 v[2:3], s[4:5], v0, s82, v[34:35]
	v_lshlrev_b64 v[0:1], 11, v[0:1]
	v_lshl_add_u64 v[42:43], v[2:3], 0, s[6:7]
	v_lshl_add_u64 v[44:45], s[56:57], 0, v[0:1]
	global_load_dwordx4 v[4:7], v82, s[60:61] offset:16
	global_load_dwordx4 v[12:15], v82, s[60:61]
	global_load_dwordx4 v[0:3], v82, s[62:63] offset:16
	global_load_dwordx4 v[8:11], v82, s[62:63]
	v_lshl_add_u64 v[62:63], v[42:43], 0, v[168:169]
	global_load_dwordx4 v[62:65], v[62:63], off nt
	v_mul_f32_e32 v60, v60, v33
	v_lshl_add_u64 v[44:45], v[44:45], 0, v[168:169]
	v_lshl_add_u64 v[42:43], v[42:43], 0, v[36:37]
	v_mul_f32_e32 v49, v49, v33
	s_waitcnt vmcnt(1)
	v_fma_f32 v8, v12, v60, v8
	v_mul_f32_e32 v12, 0xbfb8aa3b, v8
	v_exp_f32_e32 v12, v12
	s_waitcnt vmcnt(0)
	v_lshlrev_b32_e32 v66, 16, v62
	v_and_b32_e32 v67, 0xffff0000, v62
	v_lshlrev_b32_e32 v68, 16, v63
	v_add_f32_e32 v12, 1.0, v12
	v_and_b32_e32 v62, 0xffff0000, v63
	v_lshlrev_b32_e32 v61, 16, v64
	v_and_b32_e32 v59, 0xffff0000, v64
	v_lshlrev_b32_e32 v57, 16, v65
	v_and_b32_e32 v55, 0xffff0000, v65
	v_rcp_f32_e32 v12, v12
	s_nop 0
	s_nop 0
	v_mul_f32_e32 v8, v8, v12
	v_mul_f32_e32 v12, 0xbfb8aa3b, v66
	v_exp_f32_e32 v12, v12
	s_nop 0
	v_add_f32_e32 v12, 1.0, v12
	v_div_scale_f32 v60, s[4:5], v12, v12, 1.0
	v_rcp_f32_e32 v63, v60
	s_nop 0
	v_fma_f32 v64, -v60, v63, 1.0
	v_fmac_f32_e32 v63, v64, v63
	v_div_scale_f32 v64, vcc, 1.0, v12, 1.0
	v_mul_f32_e32 v65, v64, v63
	v_fma_f32 v69, -v60, v65, v64
	v_fmac_f32_e32 v65, v69, v63
	v_rcp_f32_e32 v12, v12
	s_nop 0
	s_nop 0
	v_mul_f32_e32 v12, v12, v66
	v_mul_f32_e32 v8, v12, v8
	v_mul_f32_e32 v12, v58, v33
	v_fma_f32 v9, v13, v12, v9
	v_mul_f32_e32 v12, 0xbfb8aa3b, v9
	v_exp_f32_e32 v12, v12
	s_nop 0
	v_add_f32_e32 v12, 1.0, v12
	s_nop 0
	v_rcp_f32_e32 v12, v12
	s_nop 0
	s_nop 0
	v_mul_f32_e32 v9, v9, v12
	v_mul_f32_e32 v12, 0xbfb8aa3b, v67
	v_exp_f32_e32 v12, v12
	s_nop 0
	v_add_f32_e32 v12, 1.0, v12
	v_div_scale_f32 v13, s[4:5], v12, v12, 1.0
	v_rcp_f32_e32 v58, v13
	s_nop 0
	v_fma_f32 v60, -v13, v58, 1.0
	v_fmac_f32_e32 v58, v60, v58
	v_div_scale_f32 v60, vcc, 1.0, v12, 1.0
	v_mul_f32_e32 v63, v60, v58
	v_fma_f32 v64, -v13, v63, v60
	v_fmac_f32_e32 v63, v64, v58
	v_rcp_f32_e32 v12, v12
	s_nop 0
	s_nop 0
	v_mul_f32_e32 v12, v12, v67
	v_mul_f32_e32 v9, v12, v9
	v_mul_f32_e32 v12, v56, v33
	v_fma_f32 v10, v14, v12, v10
	v_mul_f32_e32 v12, 0xbfb8aa3b, v10
	v_exp_f32_e32 v12, v12
	s_nop 0
	v_add_f32_e32 v12, 1.0, v12
	s_nop 0
	v_rcp_f32_e32 v12, v12
	s_nop 0
	s_nop 0
	v_mul_f32_e32 v10, v10, v12
	v_mul_f32_e32 v12, 0xbfb8aa3b, v68
	v_exp_f32_e32 v12, v12
	s_nop 0
	v_add_f32_e32 v12, 1.0, v12
	v_div_scale_f32 v13, s[4:5], v12, v12, 1.0
	v_rcp_f32_e32 v14, v13
	s_nop 0
	v_fma_f32 v56, -v13, v14, 1.0
	v_fmac_f32_e32 v14, v56, v14
	v_div_scale_f32 v56, vcc, 1.0, v12, 1.0
	v_mul_f32_e32 v58, v56, v14
	v_fma_f32 v60, -v13, v58, v56
	v_rcp_f32_e32 v12, v12
	s_nop 0
	s_nop 0
	v_mul_f32_e32 v12, v12, v68
	v_mul_f32_e32 v10, v12, v10
	v_mul_f32_e32 v12, v54, v33
	v_fmac_f32_e32 v11, v15, v12
	v_mul_f32_e32 v12, 0xbfb8aa3b, v11
	v_exp_f32_e32 v12, v12
	s_nop 0
	v_add_f32_e32 v12, 1.0, v12
	s_nop 0
	v_rcp_f32_e32 v12, v12
	s_nop 0
	s_nop 0
	v_mul_f32_e32 v11, v11, v12
	v_mul_f32_e32 v12, 0xbfb8aa3b, v62
	v_exp_f32_e32 v12, v12
	s_nop 0
	v_add_f32_e32 v12, 1.0, v12
	s_nop 0
	v_rcp_f32_e32 v12, v12
	s_nop 0
	s_nop 0
	v_mul_f32_e32 v12, v12, v62
	v_mul_f32_e32 v11, v12, v11
	v_mul_f32_e32 v12, v53, v33
	v_fma_f32 v0, v4, v12, v0
	v_mul_f32_e32 v4, 0xbfb8aa3b, v0
	v_exp_f32_e32 v4, v4
	s_nop 0
	v_add_f32_e32 v4, 1.0, v4
	s_nop 0
	v_rcp_f32_e32 v4, v4
	s_nop 0
	s_nop 0
	v_mul_f32_e32 v0, v0, v4
	v_mul_f32_e32 v4, 0xbfb8aa3b, v61
	v_exp_f32_e32 v4, v4
	s_nop 0
	v_add_f32_e32 v4, 1.0, v4
	s_nop 0
	v_rcp_f32_e32 v4, v4
	s_nop 0
	s_nop 0
	v_mul_f32_e32 v4, v4, v61
	v_mul_f32_e32 v4, v4, v0
	v_mul_f32_e32 v0, v52, v33
	v_fma_f32 v0, v5, v0, v1
	v_mul_f32_e32 v1, 0xbfb8aa3b, v0
	v_exp_f32_e32 v1, v1
	s_nop 0
	v_add_f32_e32 v1, 1.0, v1
	s_nop 0
	v_rcp_f32_e32 v1, v1
	s_nop 0
	s_nop 0
	v_mul_f32_e32 v0, v0, v1
	v_mul_f32_e32 v1, 0xbfb8aa3b, v59
	v_exp_f32_e32 v1, v1
	s_nop 0
	v_add_f32_e32 v1, 1.0, v1
	s_nop 0
	v_rcp_f32_e32 v1, v1
	s_nop 0
	s_nop 0
	v_mul_f32_e32 v1, v1, v59
	v_mul_f32_e32 v5, v1, v0
	v_mul_f32_e32 v0, v51, v33
	v_fma_f32 v0, v6, v0, v2
	v_mul_f32_e32 v1, 0xbfb8aa3b, v0
	v_exp_f32_e32 v1, v1
	s_nop 0
	v_add_f32_e32 v1, 1.0, v1
	s_nop 0
	v_rcp_f32_e32 v1, v1
	s_nop 0
	s_nop 0
	v_mul_f32_e32 v0, v0, v1
	v_mul_f32_e32 v1, 0xbfb8aa3b, v57
	v_exp_f32_e32 v1, v1
	s_nop 0
	v_add_f32_e32 v1, 1.0, v1
	s_nop 0
	v_rcp_f32_e32 v1, v1
	s_nop 0
	s_nop 0
	v_mul_f32_e32 v1, v1, v57
	v_mul_f32_e32 v6, v1, v0
	v_mul_f32_e32 v0, v50, v33
	v_fmac_f32_e32 v3, v7, v0
	v_mul_f32_e32 v0, 0xbfb8aa3b, v3
	v_exp_f32_e32 v0, v0
	s_nop 0
	v_add_f32_e32 v0, 1.0, v0
	s_nop 0
	v_rcp_f32_e32 v0, v0
	s_nop 0
	v_mul_f32_e32 v1, 0xbfb8aa3b, v55
	v_exp_f32_e32 v1, v1
	v_mul_f32_e32 v0, v3, v0
	v_add_f32_e32 v1, 1.0, v1
	s_nop 0
	v_rcp_f32_e32 v1, v1
	s_nop 0
	s_nop 0
	v_mul_f32_e32 v1, v1, v55
	v_mul_f32_e32 v3, v1, v0
	v_cvt_pk_bf16_f32 v0, v8, v9
	v_cvt_pk_bf16_f32 v1, v10, v11
	v_cvt_pk_bf16_f32 v2, v4, v5
	v_cvt_pk_bf16_f32 v3, v6, v3
	global_store_dwordx4 v[44:45], v[0:3], off
	global_load_dwordx4 v[4:7], v82, s[60:61] offset:2064
	global_load_dwordx4 v[12:15], v82, s[60:61] offset:2048
	s_nop 0
	global_load_dwordx4 v[0:3], v82, s[62:63] offset:2064
	global_load_dwordx4 v[8:11], v82, s[62:63] offset:2048
	global_load_dwordx4 v[52:55], v[42:43], off nt
	s_waitcnt vmcnt(1)
	v_fma_f32 v8, v49, v12, v8
	v_mul_f32_e32 v12, 0xbfb8aa3b, v8
	v_exp_f32_e32 v12, v12
	s_waitcnt vmcnt(0)
	v_lshlrev_b32_e32 v56, 16, v52
	v_and_b32_e32 v57, 0xffff0000, v52
	v_lshlrev_b32_e32 v58, 16, v53
	v_add_f32_e32 v12, 1.0, v12
	v_and_b32_e32 v52, 0xffff0000, v53
	v_lshlrev_b32_e32 v51, 16, v54
	v_and_b32_e32 v50, 0xffff0000, v54
	v_lshlrev_b32_e32 v43, 16, v55
	v_and_b32_e32 v42, 0xffff0000, v55
	v_rcp_f32_e32 v12, v12
	s_nop 0
	s_nop 0
	v_mul_f32_e32 v8, v8, v12
	v_mul_f32_e32 v12, 0xbfb8aa3b, v56
	v_exp_f32_e32 v12, v12
	s_nop 0
	v_add_f32_e32 v12, 1.0, v12
	v_div_scale_f32 v49, s[4:5], v12, v12, 1.0
	v_rcp_f32_e32 v53, v49
	s_nop 0
	v_fma_f32 v54, -v49, v53, 1.0
	v_fmac_f32_e32 v53, v54, v53
	v_div_scale_f32 v54, vcc, 1.0, v12, 1.0
	v_mul_f32_e32 v55, v54, v53
	v_fma_f32 v59, -v49, v55, v54
	v_fmac_f32_e32 v55, v59, v53
	v_rcp_f32_e32 v12, v12
	s_nop 0
	s_nop 0
	v_mul_f32_e32 v12, v12, v56
	v_mul_f32_e32 v8, v8, v12
	v_mul_f32_e32 v12, v48, v33
	v_fma_f32 v9, v12, v13, v9
	v_mul_f32_e32 v12, 0xbfb8aa3b, v9
	v_exp_f32_e32 v12, v12
	s_nop 0
	v_add_f32_e32 v12, 1.0, v12
	s_nop 0
	v_rcp_f32_e32 v12, v12
	s_nop 0
	s_nop 0
	v_mul_f32_e32 v9, v9, v12
	v_mul_f32_e32 v12, 0xbfb8aa3b, v57
	v_exp_f32_e32 v12, v12
	s_nop 0
	v_add_f32_e32 v12, 1.0, v12
	v_div_scale_f32 v13, s[4:5], v12, v12, 1.0
	v_rcp_f32_e32 v48, v13
	s_nop 0
	v_fma_f32 v49, -v13, v48, 1.0
	v_fmac_f32_e32 v48, v49, v48
	v_div_scale_f32 v49, vcc, 1.0, v12, 1.0
	v_mul_f32_e32 v53, v49, v48
	v_fma_f32 v54, -v13, v53, v49
	v_fmac_f32_e32 v53, v54, v48
	v_rcp_f32_e32 v12, v12
	s_nop 0
	s_nop 0
	v_mul_f32_e32 v12, v12, v57
	v_mul_f32_e32 v9, v9, v12
	v_mul_f32_e32 v12, v47, v33
	v_fma_f32 v10, v12, v14, v10
	v_mul_f32_e32 v12, 0xbfb8aa3b, v10
	v_exp_f32_e32 v12, v12
	s_nop 0
	v_add_f32_e32 v12, 1.0, v12
	s_nop 0
	v_rcp_f32_e32 v12, v12
	s_nop 0
	s_nop 0
	v_mul_f32_e32 v10, v10, v12
	v_mul_f32_e32 v12, 0xbfb8aa3b, v58
	v_exp_f32_e32 v12, v12
	s_nop 0
	v_add_f32_e32 v12, 1.0, v12
	s_nop 0
	v_rcp_f32_e32 v12, v12
	s_nop 0
	s_nop 0
	v_mul_f32_e32 v12, v12, v58
	v_mul_f32_e32 v10, v10, v12
	v_mul_f32_e32 v12, v46, v33
	v_fmac_f32_e32 v11, v12, v15
	v_mul_f32_e32 v12, 0xbfb8aa3b, v11
	v_exp_f32_e32 v12, v12
	s_nop 0
	v_add_f32_e32 v12, 1.0, v12
	s_nop 0
	v_rcp_f32_e32 v12, v12
	s_nop 0
	s_nop 0
	v_mul_f32_e32 v11, v11, v12
	v_mul_f32_e32 v12, 0xbfb8aa3b, v52
	v_exp_f32_e32 v12, v12
	s_nop 0
	v_add_f32_e32 v12, 1.0, v12
	s_nop 0
	v_rcp_f32_e32 v12, v12
	s_nop 0
	s_nop 0
	v_mul_f32_e32 v12, v12, v52
	v_mul_f32_e32 v11, v11, v12
	v_mul_f32_e32 v12, v40, v33
	v_fma_f32 v0, v12, v4, v0
	v_mul_f32_e32 v4, 0xbfb8aa3b, v0
	v_exp_f32_e32 v4, v4
	s_nop 0
	v_add_f32_e32 v4, 1.0, v4
	s_nop 0
	v_rcp_f32_e32 v4, v4
	s_nop 0
	s_nop 0
	v_mul_f32_e32 v0, v0, v4
	v_mul_f32_e32 v4, 0xbfb8aa3b, v51
	v_exp_f32_e32 v4, v4
	s_nop 0
	v_add_f32_e32 v4, 1.0, v4
	s_nop 0
	v_rcp_f32_e32 v4, v4
	s_nop 0
	s_nop 0
	v_mul_f32_e32 v4, v4, v51
	v_mul_f32_e32 v4, v0, v4
	v_mul_f32_e32 v0, v41, v33
	v_fma_f32 v0, v0, v5, v1
	v_mul_f32_e32 v1, 0xbfb8aa3b, v0
	v_exp_f32_e32 v1, v1
	s_nop 0
	v_add_f32_e32 v1, 1.0, v1
	s_nop 0
	v_rcp_f32_e32 v1, v1
	s_nop 0
	s_nop 0
	v_mul_f32_e32 v0, v0, v1
	v_mul_f32_e32 v1, 0xbfb8aa3b, v50
	v_exp_f32_e32 v1, v1
	s_nop 0
	v_add_f32_e32 v1, 1.0, v1
	s_nop 0
	v_rcp_f32_e32 v1, v1
	s_nop 0
	s_nop 0
	v_mul_f32_e32 v1, v1, v50
	v_mul_f32_e32 v5, v0, v1
	v_mul_f32_e32 v0, v38, v33
	v_fma_f32 v0, v0, v6, v2
	v_mul_f32_e32 v1, 0xbfb8aa3b, v0
	v_exp_f32_e32 v1, v1
	s_nop 0
	v_add_f32_e32 v1, 1.0, v1
	s_nop 0
	v_rcp_f32_e32 v1, v1
	s_nop 0
	s_nop 0
	v_mul_f32_e32 v0, v0, v1
	v_mul_f32_e32 v1, 0xbfb8aa3b, v43
	v_exp_f32_e32 v1, v1
	s_nop 0
	v_add_f32_e32 v1, 1.0, v1
	s_nop 0
	v_rcp_f32_e32 v1, v1
	s_nop 0
	s_nop 0
	v_mul_f32_e32 v1, v1, v43
	v_mul_f32_e32 v6, v0, v1
	v_mul_f32_e32 v0, v39, v33
	v_fmac_f32_e32 v3, v0, v7
	v_mul_f32_e32 v0, 0xbfb8aa3b, v3
	v_exp_f32_e32 v0, v0
	s_nop 0
	v_add_f32_e32 v0, 1.0, v0
	s_nop 0
	v_rcp_f32_e32 v0, v0
	s_nop 0
	v_mul_f32_e32 v1, 0xbfb8aa3b, v42
	v_exp_f32_e32 v1, v1
	v_mul_f32_e32 v0, v3, v0
	v_add_f32_e32 v1, 1.0, v1
	s_nop 0
	v_rcp_f32_e32 v1, v1
	s_nop 0
	s_nop 0
	v_mul_f32_e32 v1, v1, v42
	v_mul_f32_e32 v3, v0, v1
	v_cvt_pk_bf16_f32 v0, v8, v9
	v_cvt_pk_bf16_f32 v1, v10, v11
	v_cvt_pk_bf16_f32 v2, v4, v5
	v_cvt_pk_bf16_f32 v3, v6, v3
	global_store_dwordx4 v[44:45], v[0:3], off offset:1024
	global_load_dwordx4 v[0:3], v82, s[58:59] offset:16
	s_nop 0
	global_load_dwordx4 v[4:7], v82, s[58:59]
	s_waitcnt vmcnt(1)
	v_add_f32_e32 v33, v26, v0
	s_waitcnt vmcnt(0)
	v_add_f32_e32 v41, v30, v4
	v_add_f32_e32 v4, 0, v41
	v_add_f32_e32 v40, v31, v5
	v_add_f32_e32 v4, v4, v40
	v_add_f32_e32 v39, v28, v6
	v_add_f32_e32 v4, v4, v39
	v_add_f32_e32 v38, v29, v7
	v_add_f32_e32 v4, v4, v38
	v_add_f32_e32 v0, v4, v33
	v_add_f32_e32 v31, v27, v1
	v_add_f32_e32 v0, v0, v31
	v_add_f32_e32 v30, v24, v2
	v_add_f32_e32 v0, v0, v30
	v_add_f32_e32 v29, v25, v3
	v_add_f32_e32 v8, v0, v29
	global_load_dwordx4 v[0:3], v82, s[58:59] offset:2048
	global_load_dwordx4 v[4:7], v82, s[58:59] offset:2064
	s_waitcnt vmcnt(1)
	v_add_f32_e32 v28, v22, v0
	v_add_f32_e32 v0, v8, v28
	v_add_f32_e32 v27, v23, v1
	v_add_f32_e32 v0, v0, v27
	v_add_f32_e32 v26, v20, v2
	v_add_f32_e32 v0, v0, v26
	v_add_f32_e32 v25, v21, v3
	v_add_f32_e32 v8, v0, v25
	s_waitcnt vmcnt(0)
	v_pk_add_f32 v[2:3], v[18:19], v[4:5]
	v_pk_add_f32 v[0:1], v[16:17], v[6:7]
	v_add_f32_e32 v4, v8, v2
	v_add_f32_e32 v4, v4, v3
	v_add_f32_e32 v4, v4, v0
	v_add_f32_e32 v4, v4, v1
	ds_bpermute_b32 v5, v121, v4
	s_waitcnt lgkmcnt(0)
	v_add_f32_e32 v4, v4, v5
	ds_bpermute_b32 v5, v119, v4
	s_waitcnt lgkmcnt(0)
	v_add_f32_e32 v4, v4, v5
	ds_bpermute_b32 v5, v78, v4
	s_waitcnt lgkmcnt(0)
	v_add_f32_e32 v4, v4, v5
	ds_bpermute_b32 v5, v79, v4
	s_waitcnt lgkmcnt(0)
	v_add_f32_e32 v4, v4, v5
	ds_bpermute_b32 v5, v80, v4
	s_waitcnt lgkmcnt(0)
	v_add_f32_e32 v4, v4, v5
	ds_bpermute_b32 v5, v81, v4
	s_waitcnt lgkmcnt(0)
	v_add_f32_e32 v5, v4, v5
	v_fmac_f32_e32 v40, 0xba800000, v5
	v_fmac_f32_e32 v41, 0xba800000, v5
	v_mul_f32_e32 v6, v40, v40
	v_fmac_f32_e32 v6, v41, v41
	v_fmac_f32_e32 v39, 0xba800000, v5
	v_fmac_f32_e32 v6, v39, v39
	v_fmac_f32_e32 v38, 0xba800000, v5
	v_fmac_f32_e32 v6, v38, v38
	v_fmac_f32_e32 v33, 0xba800000, v5
	v_fmac_f32_e32 v6, v33, v33
	v_fmac_f32_e32 v31, 0xba800000, v5
	v_fmac_f32_e32 v6, v31, v31
	v_fmac_f32_e32 v30, 0xba800000, v5
	v_fmac_f32_e32 v6, v30, v30
	v_fmac_f32_e32 v29, 0xba800000, v5
	v_fmac_f32_e32 v6, v29, v29
	v_fmac_f32_e32 v28, 0xba800000, v5
	v_fmac_f32_e32 v6, v28, v28
	v_fmac_f32_e32 v27, 0xba800000, v5
	v_mul_f32_e32 v4, 0x3a800000, v5
	v_fmac_f32_e32 v6, v27, v27
	v_fmac_f32_e32 v26, 0xba800000, v5
	v_fmac_f32_e32 v6, v26, v26
	v_fmac_f32_e32 v25, 0xba800000, v5
	v_pk_add_f32 v[18:19], v[2:3], v[4:5] op_sel_hi:[1,0] neg_lo:[0,1] neg_hi:[0,1]
	v_fmac_f32_e32 v6, v25, v25
	v_pk_mul_f32 v[2:3], v[18:19], v[18:19]
	v_pk_add_f32 v[16:17], v[0:1], v[4:5] op_sel_hi:[1,0] neg_lo:[0,1] neg_hi:[0,1]
	v_add_f32_e32 v2, v2, v6
	v_add_f32_e32 v2, v3, v2
	v_pk_mul_f32 v[0:1], v[16:17], v[16:17]
	s_nop 0
	v_add_f32_e32 v0, v0, v2
	v_add_f32_e32 v1, v1, v0
	ds_bpermute_b32 v2, v121, v1
	v_or_b32_e32 v0, 3, v32
	s_waitcnt lgkmcnt(0)
	v_add_f32_e32 v1, v1, v2
	ds_bpermute_b32 v2, v119, v1
	s_waitcnt lgkmcnt(0)
	v_add_f32_e32 v1, v1, v2
	ds_bpermute_b32 v2, v78, v1
	s_waitcnt lgkmcnt(0)
	v_add_f32_e32 v1, v1, v2
	ds_bpermute_b32 v2, v79, v1
	s_waitcnt lgkmcnt(0)
	v_add_f32_e32 v1, v1, v2
	ds_bpermute_b32 v2, v80, v1
	s_waitcnt lgkmcnt(0)
	v_add_f32_e32 v1, v1, v2
	ds_bpermute_b32 v2, v81, v1
	s_waitcnt lgkmcnt(0)
	v_add_f32_e32 v1, v1, v2
	v_fmamk_f32 v1, v1, 0x3a800000, v211
	v_cmp_gt_f32_e32 vcc, s80, v1
	v_mul_f32_e32 v2, 0x4b800000, v1
	s_nop 0
	v_cndmask_b32_e32 v1, v1, v2, vcc
	v_rsq_f32_e32 v1, v1
	s_nop 0
	v_mul_f32_e32 v2, 0x45800000, v1
	v_cndmask_b32_e32 v24, v1, v2, vcc
	v_ashrrev_i32_e32 v1, 31, v0
	v_mad_i64_i32 v[2:3], s[4:5], v0, s82, v[34:35]
	v_lshlrev_b64 v[0:1], 11, v[0:1]
	v_lshl_add_u64 v[20:21], v[2:3], 0, s[6:7]
	v_lshl_add_u64 v[22:23], s[56:57], 0, v[0:1]
	global_load_dwordx4 v[4:7], v82, s[60:61] offset:16
	global_load_dwordx4 v[12:15], v82, s[60:61]
	global_load_dwordx4 v[0:3], v82, s[62:63] offset:16
	global_load_dwordx4 v[8:11], v82, s[62:63]
	v_lshl_add_u64 v[34:35], v[20:21], 0, v[168:169]
	global_load_dwordx4 v[42:45], v[34:35], off nt
	v_mul_f32_e32 v41, v41, v24
	v_lshl_add_u64 v[22:23], v[22:23], 0, v[168:169]
	v_lshl_add_u64 v[20:21], v[20:21], 0, v[36:37]
	v_mul_f32_e32 v28, v28, v24
	s_waitcnt vmcnt(1)
	v_fma_f32 v8, v12, v41, v8
	v_mul_f32_e32 v12, 0xbfb8aa3b, v8
	v_exp_f32_e32 v12, v12
	s_waitcnt vmcnt(0)
	v_lshlrev_b32_e32 v46, 16, v42
	v_and_b32_e32 v47, 0xffff0000, v42
	v_lshlrev_b32_e32 v42, 16, v44
	v_add_f32_e32 v12, 1.0, v12
	v_and_b32_e32 v35, 0xffff0000, v44
	v_lshlrev_b32_e32 v34, 16, v45
	v_and_b32_e32 v32, 0xffff0000, v45
	v_lshlrev_b32_e32 v48, 16, v43
	v_rcp_f32_e32 v12, v12
	s_nop 0
	s_nop 0
	v_mul_f32_e32 v8, v8, v12
	v_mul_f32_e32 v12, 0xbfb8aa3b, v46
	v_exp_f32_e32 v12, v12
	v_and_b32_e32 v43, 0xffff0000, v43
	v_add_f32_e32 v12, 1.0, v12
	v_div_scale_f32 v41, s[4:5], v12, v12, 1.0
	v_rcp_f32_e32 v44, v41
	s_nop 0
	v_fma_f32 v45, -v41, v44, 1.0
	v_fmac_f32_e32 v44, v45, v44
	v_div_scale_f32 v45, vcc, 1.0, v12, 1.0
	v_mul_f32_e32 v49, v45, v44
	v_fma_f32 v50, -v41, v49, v45
	v_fmac_f32_e32 v49, v50, v44
	v_rcp_f32_e32 v12, v12
	s_nop 0
	s_nop 0
	v_mul_f32_e32 v12, v12, v46
	v_mul_f32_e32 v8, v12, v8
	v_mul_f32_e32 v12, v40, v24
	v_fma_f32 v9, v13, v12, v9
	v_mul_f32_e32 v12, 0xbfb8aa3b, v9
	v_exp_f32_e32 v12, v12
	s_nop 0
	v_add_f32_e32 v12, 1.0, v12
	s_nop 0
	v_rcp_f32_e32 v12, v12
	s_nop 0
	s_nop 0
	v_mul_f32_e32 v9, v9, v12
	v_mul_f32_e32 v12, 0xbfb8aa3b, v47
	v_exp_f32_e32 v12, v12
	s_nop 0
	v_add_f32_e32 v12, 1.0, v12
	v_div_scale_f32 v13, s[4:5], v12, v12, 1.0
	v_rcp_f32_e32 v40, v13
	s_nop 0
	v_fma_f32 v41, -v13, v40, 1.0
	v_fmac_f32_e32 v40, v41, v40
	v_div_scale_f32 v41, vcc, 1.0, v12, 1.0
	v_mul_f32_e32 v44, v41, v40
	v_fma_f32 v45, -v13, v44, v41
	v_fmac_f32_e32 v44, v45, v40
	v_rcp_f32_e32 v12, v12
	s_nop 0
	s_nop 0
	v_mul_f32_e32 v12, v12, v47
	v_mul_f32_e32 v9, v12, v9
	v_mul_f32_e32 v12, v39, v24
	v_fma_f32 v10, v14, v12, v10
	v_mul_f32_e32 v12, 0xbfb8aa3b, v10
	v_exp_f32_e32 v12, v12
	s_nop 0
	v_add_f32_e32 v12, 1.0, v12
	s_nop 0
	v_rcp_f32_e32 v12, v12
	s_nop 0
	s_nop 0
	v_mul_f32_e32 v10, v10, v12
	v_mul_f32_e32 v12, 0xbfb8aa3b, v48
	v_exp_f32_e32 v12, v12
	s_nop 0
	v_add_f32_e32 v12, 1.0, v12
	v_div_scale_f32 v13, s[4:5], v12, v12, 1.0
	v_rcp_f32_e32 v14, v13
	s_nop 0
	v_fma_f32 v39, -v13, v14, 1.0
	v_fmac_f32_e32 v14, v39, v14
	v_div_scale_f32 v39, vcc, 1.0, v12, 1.0
	v_mul_f32_e32 v40, v39, v14
	v_fma_f32 v41, -v13, v40, v39
	v_fmac_f32_e32 v40, v41, v14
	v_rcp_f32_e32 v12, v12
	s_nop 0
	s_nop 0
	v_mul_f32_e32 v12, v12, v48
	v_mul_f32_e32 v10, v12, v10
	v_mul_f32_e32 v12, v38, v24
	v_fmac_f32_e32 v11, v15, v12
	v_mul_f32_e32 v12, 0xbfb8aa3b, v11
	v_exp_f32_e32 v12, v12
	s_nop 0
	v_add_f32_e32 v12, 1.0, v12
	s_nop 0
	v_rcp_f32_e32 v12, v12
	s_nop 0
	s_nop 0
	v_mul_f32_e32 v11, v11, v12
	v_mul_f32_e32 v12, 0xbfb8aa3b, v43
	v_exp_f32_e32 v12, v12
	s_nop 0
	v_add_f32_e32 v12, 1.0, v12
	v_div_scale_f32 v13, s[4:5], v12, v12, 1.0
	v_rcp_f32_e32 v14, v13
	s_nop 0
	v_fma_f32 v15, -v13, v14, 1.0
	v_fmac_f32_e32 v14, v15, v14
	v_div_scale_f32 v15, vcc, 1.0, v12, 1.0
	v_mul_f32_e32 v38, v15, v14
	v_fma_f32 v39, -v13, v38, v15
	v_rcp_f32_e32 v12, v12
	s_nop 0
	s_nop 0
	v_mul_f32_e32 v12, v12, v43
	v_mul_f32_e32 v11, v12, v11
	v_mul_f32_e32 v12, v33, v24
	v_fma_f32 v0, v4, v12, v0
	v_mul_f32_e32 v4, 0xbfb8aa3b, v0
	v_exp_f32_e32 v4, v4
	s_nop 0
	v_add_f32_e32 v4, 1.0, v4
	s_nop 0
	v_rcp_f32_e32 v4, v4
	s_nop 0
	s_nop 0
	v_mul_f32_e32 v0, v0, v4
	v_mul_f32_e32 v4, 0xbfb8aa3b, v42
	v_exp_f32_e32 v4, v4
	s_nop 0
	v_add_f32_e32 v4, 1.0, v4
	s_nop 0
	v_rcp_f32_e32 v4, v4
	s_nop 0
	s_nop 0
	v_mul_f32_e32 v4, v4, v42
	v_mul_f32_e32 v4, v4, v0
	v_mul_f32_e32 v0, v31, v24
	v_fma_f32 v0, v5, v0, v1
	v_mul_f32_e32 v1, 0xbfb8aa3b, v0
	v_exp_f32_e32 v1, v1
	s_nop 0
	v_add_f32_e32 v1, 1.0, v1
	s_nop 0
	v_rcp_f32_e32 v1, v1
	s_nop 0
	s_nop 0
	v_mul_f32_e32 v0, v0, v1
	v_mul_f32_e32 v1, 0xbfb8aa3b, v35
	v_exp_f32_e32 v1, v1
	s_nop 0
	v_add_f32_e32 v1, 1.0, v1
	s_nop 0
	v_rcp_f32_e32 v1, v1
	s_nop 0
	s_nop 0
	v_mul_f32_e32 v1, v1, v35
	v_mul_f32_e32 v5, v1, v0
	v_mul_f32_e32 v0, v30, v24
	v_fma_f32 v0, v6, v0, v2
	v_mul_f32_e32 v1, 0xbfb8aa3b, v0
	v_exp_f32_e32 v1, v1
	s_nop 0
	v_add_f32_e32 v1, 1.0, v1
	s_nop 0
	v_rcp_f32_e32 v1, v1
	s_nop 0
	s_nop 0
	v_mul_f32_e32 v0, v0, v1
	v_mul_f32_e32 v1, 0xbfb8aa3b, v34
	v_exp_f32_e32 v1, v1
	s_nop 0
	v_add_f32_e32 v1, 1.0, v1
	s_nop 0
	v_rcp_f32_e32 v1, v1
	s_nop 0
	s_nop 0
	v_mul_f32_e32 v1, v1, v34
	v_mul_f32_e32 v6, v1, v0
	v_mul_f32_e32 v0, v29, v24
	v_fmac_f32_e32 v3, v7, v0
	v_mul_f32_e32 v0, 0xbfb8aa3b, v3
	v_exp_f32_e32 v0, v0
	s_nop 0
	v_add_f32_e32 v0, 1.0, v0
	s_nop 0
	v_rcp_f32_e32 v0, v0
	s_nop 0
	v_mul_f32_e32 v1, 0xbfb8aa3b, v32
	v_exp_f32_e32 v1, v1
	v_mul_f32_e32 v0, v3, v0
	v_add_f32_e32 v1, 1.0, v1
	s_nop 0
	v_rcp_f32_e32 v1, v1
	s_nop 0
	s_nop 0
	v_mul_f32_e32 v1, v1, v32
	v_mul_f32_e32 v3, v1, v0
	v_cvt_pk_bf16_f32 v0, v8, v9
	v_cvt_pk_bf16_f32 v1, v10, v11
	v_cvt_pk_bf16_f32 v2, v4, v5
	v_cvt_pk_bf16_f32 v3, v6, v3
	global_store_dwordx4 v[22:23], v[0:3], off
	global_load_dwordx4 v[4:7], v82, s[60:61] offset:2064
	global_load_dwordx4 v[12:15], v82, s[60:61] offset:2048
	s_nop 0
	global_load_dwordx4 v[0:3], v82, s[62:63] offset:2064
	global_load_dwordx4 v[8:11], v82, s[62:63] offset:2048
	global_load_dwordx4 v[30:33], v[20:21], off nt
	s_waitcnt vmcnt(1)
	v_fma_f32 v8, v28, v12, v8
	v_mul_f32_e32 v12, 0xbfb8aa3b, v8
	v_exp_f32_e32 v12, v12
	s_waitcnt vmcnt(0)
	v_lshlrev_b32_e32 v34, 16, v30
	v_and_b32_e32 v35, 0xffff0000, v30
	v_lshlrev_b32_e32 v30, 16, v32
	v_add_f32_e32 v12, 1.0, v12
	v_and_b32_e32 v29, 0xffff0000, v32
	v_lshlrev_b32_e32 v21, 16, v33
	v_and_b32_e32 v20, 0xffff0000, v33
	v_lshlrev_b32_e32 v36, 16, v31
	v_rcp_f32_e32 v12, v12
	s_nop 0
	s_nop 0
	v_mul_f32_e32 v8, v8, v12
	v_mul_f32_e32 v12, 0xbfb8aa3b, v34
	v_exp_f32_e32 v12, v12
	v_and_b32_e32 v31, 0xffff0000, v31
	v_add_f32_e32 v12, 1.0, v12
	v_div_scale_f32 v28, s[4:5], v12, v12, 1.0
	v_rcp_f32_e32 v32, v28
	s_nop 0
	v_fma_f32 v33, -v28, v32, 1.0
	v_fmac_f32_e32 v32, v33, v32
	v_div_scale_f32 v33, vcc, 1.0, v12, 1.0
	v_mul_f32_e32 v37, v33, v32
	v_fma_f32 v38, -v28, v37, v33
	v_fmac_f32_e32 v37, v38, v32
	v_rcp_f32_e32 v12, v12
	s_nop 0
	s_nop 0
	v_mul_f32_e32 v12, v12, v34
	v_mul_f32_e32 v8, v8, v12
	v_mul_f32_e32 v12, v27, v24
	v_fma_f32 v9, v12, v13, v9
	v_mul_f32_e32 v12, 0xbfb8aa3b, v9
	v_exp_f32_e32 v12, v12
	s_nop 0
	v_add_f32_e32 v12, 1.0, v12
	s_nop 0
	v_rcp_f32_e32 v12, v12
	s_nop 0
	s_nop 0
	v_mul_f32_e32 v9, v9, v12
	v_mul_f32_e32 v12, 0xbfb8aa3b, v35
	v_exp_f32_e32 v12, v12
	s_nop 0
	v_add_f32_e32 v12, 1.0, v12
	v_div_scale_f32 v13, s[4:5], v12, v12, 1.0
	v_rcp_f32_e32 v27, v13
	s_nop 0
	v_fma_f32 v28, -v13, v27, 1.0
	v_fmac_f32_e32 v27, v28, v27
	v_div_scale_f32 v28, vcc, 1.0, v12, 1.0
	v_mul_f32_e32 v32, v28, v27
	v_fma_f32 v33, -v13, v32, v28
	v_fmac_f32_e32 v32, v33, v27
	v_rcp_f32_e32 v12, v12
	s_nop 0
	s_nop 0
	v_mul_f32_e32 v12, v12, v35
	v_mul_f32_e32 v9, v9, v12
	v_mul_f32_e32 v12, v26, v24
	v_fma_f32 v10, v12, v14, v10
	v_mul_f32_e32 v12, 0xbfb8aa3b, v10
	v_exp_f32_e32 v12, v12
	s_nop 0
	v_add_f32_e32 v12, 1.0, v12
	s_nop 0
	v_rcp_f32_e32 v12, v12
	s_nop 0
	s_nop 0
	v_mul_f32_e32 v10, v10, v12
	v_mul_f32_e32 v12, 0xbfb8aa3b, v36
	v_exp_f32_e32 v12, v12
	s_nop 0
	v_add_f32_e32 v12, 1.0, v12
	v_div_scale_f32 v13, s[4:5], v12, v12, 1.0
	v_rcp_f32_e32 v14, v13
	s_nop 0
	v_fma_f32 v26, -v13, v14, 1.0
	v_fmac_f32_e32 v14, v26, v14
	v_div_scale_f32 v26, vcc, 1.0, v12, 1.0
	v_mul_f32_e32 v27, v26, v14
	v_fma_f32 v28, -v13, v27, v26
	v_fmac_f32_e32 v27, v28, v14
	v_rcp_f32_e32 v12, v12
	s_nop 0
	s_nop 0
	v_mul_f32_e32 v12, v12, v36
	v_mul_f32_e32 v10, v10, v12
	v_mul_f32_e32 v12, v25, v24
	v_fmac_f32_e32 v11, v12, v15
	v_mul_f32_e32 v12, 0xbfb8aa3b, v11
	v_exp_f32_e32 v12, v12
	s_nop 0
	v_add_f32_e32 v12, 1.0, v12
	s_nop 0
	v_rcp_f32_e32 v12, v12
	s_nop 0
	s_nop 0
	v_mul_f32_e32 v11, v11, v12
	v_mul_f32_e32 v12, 0xbfb8aa3b, v31
	v_exp_f32_e32 v12, v12
	s_nop 0
	v_add_f32_e32 v12, 1.0, v12
	v_div_scale_f32 v13, s[4:5], v12, v12, 1.0
	v_rcp_f32_e32 v14, v13
	s_nop 0
	v_fma_f32 v15, -v13, v14, 1.0
	v_fmac_f32_e32 v14, v15, v14
	v_div_scale_f32 v15, vcc, 1.0, v12, 1.0
	v_mul_f32_e32 v25, v15, v14
	v_fma_f32 v26, -v13, v25, v15
	v_fmac_f32_e32 v25, v26, v14
	v_rcp_f32_e32 v12, v12
	s_nop 0
	s_nop 0
	v_mul_f32_e32 v12, v12, v31
	v_mul_f32_e32 v11, v11, v12
	v_mul_f32_e32 v12, v18, v24
	v_fma_f32 v0, v12, v4, v0
	v_mul_f32_e32 v4, 0xbfb8aa3b, v0
	v_exp_f32_e32 v4, v4
	s_nop 0
	v_add_f32_e32 v4, 1.0, v4
	s_nop 0
	v_rcp_f32_e32 v4, v4
	s_nop 0
	s_nop 0
	v_mul_f32_e32 v0, v0, v4
	v_mul_f32_e32 v4, 0xbfb8aa3b, v30
	v_exp_f32_e32 v4, v4
	s_nop 0
	v_add_f32_e32 v4, 1.0, v4
	v_div_scale_f32 v12, s[4:5], v4, v4, 1.0
	v_rcp_f32_e32 v13, v12
	s_nop 0
	v_fma_f32 v14, -v12, v13, 1.0
	v_fmac_f32_e32 v13, v14, v13
	v_div_scale_f32 v14, vcc, 1.0, v4, 1.0
	v_mul_f32_e32 v15, v14, v13
	v_fma_f32 v18, -v12, v15, v14
	v_rcp_f32_e32 v4, v4
	s_nop 0
	s_nop 0
	v_mul_f32_e32 v4, v4, v30
	v_mul_f32_e32 v4, v0, v4
	v_mul_f32_e32 v0, v19, v24
	v_fma_f32 v0, v0, v5, v1
	v_mul_f32_e32 v1, 0xbfb8aa3b, v0
	v_exp_f32_e32 v1, v1
	s_nop 0
	v_add_f32_e32 v1, 1.0, v1
	s_nop 0
	v_rcp_f32_e32 v1, v1
	s_nop 0
	s_nop 0
	v_mul_f32_e32 v0, v0, v1
	v_mul_f32_e32 v1, 0xbfb8aa3b, v29
	v_exp_f32_e32 v1, v1
	s_nop 0
	v_add_f32_e32 v1, 1.0, v1
	v_div_scale_f32 v5, s[4:5], v1, v1, 1.0
	v_rcp_f32_e32 v12, v5
	s_nop 0
	v_fma_f32 v13, -v5, v12, 1.0
	v_fmac_f32_e32 v12, v13, v12
	v_div_scale_f32 v13, vcc, 1.0, v1, 1.0
	v_mul_f32_e32 v14, v13, v12
	v_fma_f32 v15, -v5, v14, v13
	v_rcp_f32_e32 v1, v1
	s_nop 0
	s_nop 0
	v_mul_f32_e32 v1, v1, v29
	v_mul_f32_e32 v5, v0, v1
	v_mul_f32_e32 v0, v16, v24
	v_fma_f32 v0, v0, v6, v2
	v_mul_f32_e32 v1, 0xbfb8aa3b, v0
	v_exp_f32_e32 v1, v1
	s_nop 0
	v_add_f32_e32 v1, 1.0, v1
	s_nop 0
	v_rcp_f32_e32 v1, v1
	s_nop 0
	s_nop 0
	v_mul_f32_e32 v0, v0, v1
	v_mul_f32_e32 v1, 0xbfb8aa3b, v21
	v_exp_f32_e32 v1, v1
	s_nop 0
	v_add_f32_e32 v1, 1.0, v1
	v_div_scale_f32 v2, s[4:5], v1, v1, 1.0
	v_rcp_f32_e32 v6, v2
	s_nop 0
	v_fma_f32 v12, -v2, v6, 1.0
	v_fmac_f32_e32 v6, v12, v6
	v_div_scale_f32 v12, vcc, 1.0, v1, 1.0
	v_mul_f32_e32 v13, v12, v6
	v_fma_f32 v14, -v2, v13, v12
	v_rcp_f32_e32 v1, v1
	s_nop 0
	s_nop 0
	v_mul_f32_e32 v1, v1, v21
	v_mul_f32_e32 v6, v0, v1
	v_mul_f32_e32 v0, v17, v24
	v_fmac_f32_e32 v3, v0, v7
	v_mul_f32_e32 v0, 0xbfb8aa3b, v3
	v_exp_f32_e32 v0, v0
	s_nop 0
	v_add_f32_e32 v0, 1.0, v0
	s_nop 0
	v_rcp_f32_e32 v0, v0
	s_nop 0
	v_mul_f32_e32 v1, 0xbfb8aa3b, v20
	v_exp_f32_e32 v1, v1
	v_mul_f32_e32 v0, v3, v0
	v_add_f32_e32 v1, 1.0, v1
	v_div_scale_f32 v2, s[4:5], v1, v1, 1.0
	v_rcp_f32_e32 v3, v2
	s_load_dwordx4 s[4:7], s[96:97], 0x118
	v_fma_f32 v7, -v2, v3, 1.0
	v_fmac_f32_e32 v3, v7, v3
	v_div_scale_f32 v7, vcc, 1.0, v1, 1.0
	v_mul_f32_e32 v12, v7, v3
	v_fma_f32 v13, -v2, v12, v7
	v_fmac_f32_e32 v12, v13, v3
	v_rcp_f32_e32 v1, v1
	s_nop 0
	s_nop 0
	v_mul_f32_e32 v1, v1, v20
	s_waitcnt lgkmcnt(0)
	s_add_i32 s52, s52, s6
	v_mul_f32_e32 v3, v0, v1
	s_cmpk_gt_i32 s52, 0x1ff
	v_cvt_pk_bf16_f32 v0, v8, v9
	v_cvt_pk_bf16_f32 v1, v10, v11
	v_cvt_pk_bf16_f32 v2, v4, v5
	v_cvt_pk_bf16_f32 v3, v6, v3
	global_store_dwordx4 v[22:23], v[0:3], off offset:1024
	s_cbranch_scc0 .LBB0_343

.LBB0_596:
	s_lshl_b32 s5, s40, 8
	s_and_b32 s5, s5, 0x3f00
	s_ashr_i32 s4, s40, 6
	v_add_u32_e32 v184, s5, v192
	s_lshl_b32 s5, s20, 8
	s_and_b32 s5, s5, 0x700
	s_lshl_b32 s56, s4, 11
	v_mov_b64_e32 v[116:117], s[24:25]
	v_or_b32_e32 v130, s5, v194
	s_ashr_i32 s57, s56, 31
	v_mad_i64_i32 v[116:117], s[6:7], v184, s82, v[116:117]
	v_lshl_add_u64 v[116:117], s[56:57], 1, v[116:117]
	v_lshlrev_b32_e32 v168, 1, v130
	v_lshl_add_u64 v[130:131], v[116:117], 0, v[168:169]
	v_add_co_u32_e32 v116, vcc, 0x5000, v130
	v_ashrrev_i32_e32 v185, 31, v184
	s_nop 0
	v_addc_co_u32_e32 v117, vcc, 0, v131, vcc
	global_load_dwordx4 v[158:161], v[116:117], off offset:2560 nt
	s_cmp_gt_i32 s4, 0
	v_lshlrev_b64 v[188:189], 12, v[184:185]
	s_cselect_b64 s[18:19], -1, 0
	s_cmp_lt_i32 s4, 1
	v_lshl_add_u64 v[116:117], s[42:43], 0, v[188:189]
	s_mov_b64 s[8:9], 0x5a00
	s_cbranch_scc1 .LBB0_598
	v_lshl_add_u64 v[132:133], v[116:117], 0, v[168:169]
	global_load_dwordx4 v[154:157], v[132:133], off
	s_branch .LBB0_599

.LBB0_599:
	v_lshl_add_u64 v[130:131], v[130:131], 0, s[8:9]
	global_load_dwordx4 v[150:153], v[130:131], off offset:256 nt
	v_cndmask_b32_e64 v130, 0, 1, s[18:19]
	v_mov_b32_e32 v140, 0
	v_cmp_ne_u32_e64 s[40:41], 1, v130
	s_andn2_b64 vcc, exec, s[18:19]
	v_mov_b32_e32 v148, 0
	v_mov_b32_e32 v149, 0
	v_mov_b32_e32 v146, 0
	v_mov_b32_e32 v147, 0
	s_cbranch_vccnz .LBB0_601
	v_lshl_add_u64 v[116:117], v[116:117], 0, v[168:169]
	global_load_dwordx4 v[146:149], v[116:117], off offset:256
.LBB0_601:
	v_or_b32_e32 v130, 16, v184
	v_mov_b64_e32 v[116:117], s[24:25]
	v_mad_i64_i32 v[116:117], s[6:7], v130, s82, v[116:117]
	v_lshl_add_u64 v[116:117], s[56:57], 1, v[116:117]
	v_lshl_add_u64 v[116:117], v[116:117], 0, v[168:169]
	v_add_co_u32_e32 v132, vcc, 0x5000, v116
	v_ashrrev_i32_e32 v131, 31, v130
	s_nop 0
	v_addc_co_u32_e32 v133, vcc, 0, v117, vcc
	global_load_dwordx4 v[142:145], v[132:133], off offset:2560 nt
	v_lshlrev_b64 v[186:187], 12, v[130:131]
	s_and_b64 vcc, exec, s[40:41]
	v_lshl_add_u64 v[190:191], s[42:43], 0, v[186:187]
	v_mov_b32_e32 v141, 0
	v_mov_b32_e32 v138, 0
	v_mov_b32_e32 v139, 0
	s_cbranch_vccnz .LBB0_603
	v_lshl_add_u64 v[130:131], v[190:191], 0, v[168:169]
	global_load_dwordx4 v[138:141], v[130:131], off
.LBB0_603:
	v_lshl_add_u64 v[116:117], v[116:117], 0, s[8:9]
	global_load_dwordx4 v[134:137], v[116:117], off offset:256 nt
	v_mov_b32_e32 v116, 0
	s_and_b64 vcc, exec, s[40:41]
	v_mov_b32_e32 v132, 0
	v_mov_b32_e32 v133, 0
	v_mov_b32_e32 v130, 0
	v_mov_b32_e32 v131, 0
	s_cbranch_vccnz .LBB0_605
	v_lshl_add_u64 v[130:131], v[190:191], 0, v[168:169]
	global_load_dwordx4 v[130:133], v[130:131], off offset:256
.LBB0_605:
	s_waitcnt vmcnt(0)
	v_lshlrev_b32_e32 v117, 16, v158
	v_mul_f32_e32 v117, 0xbfb8aa3b, v117
	v_exp_f32_e32 v117, v117
	s_cmp_lt_i32 s4, 2
	v_and_b32_e32 v158, 0xffff0000, v158
	v_mul_f32_e32 v158, 0xbfb8aa3b, v158
	v_add_f32_e32 v117, 1.0, v117
	v_div_scale_f32 v185, s[4:5], v117, v117, 1.0
	v_rcp_f32_e32 v190, v185
	v_div_scale_f32 v191, vcc, 1.0, v117, 1.0
	v_exp_f32_e32 v158, v158
	v_fma_f32 v196, -v185, v190, 1.0
	v_fmac_f32_e32 v190, v196, v190
	v_mul_f32_e32 v196, v191, v190
	v_fma_f32 v197, -v185, v196, v191
	v_add_f32_e32 v158, 1.0, v158
	v_rcp_f32_e32 v117, v117
	s_nop 0
	v_lshlrev_b32_e32 v185, 16, v154
	v_fmac_f32_e32 v185, v126, v117
	v_lshlrev_b32_e32 v196, 16, v159
	v_mul_f32_e32 v196, 0xbfb8aa3b, v196
	v_exp_f32_e32 v196, v196
	v_rcp_f32_e32 v117, v158
	s_nop 0
	v_add_f32_e32 v126, 1.0, v196
	v_div_scale_f32 v190, s[4:5], v126, v126, 1.0
	v_rcp_f32_e32 v191, v190
	v_and_b32_e32 v154, 0xffff0000, v154
	v_fmac_f32_e32 v154, v127, v117
	s_cselect_b32 s59, s43, s73
	v_fma_f32 v117, -v190, v191, 1.0
	v_fmac_f32_e32 v191, v117, v191
	v_and_b32_e32 v158, 0xffff0000, v159
	v_mul_f32_e32 v158, 0xbfb8aa3b, v158
	v_exp_f32_e32 v158, v158
	v_rcp_f32_e32 v117, v126
	s_nop 0
	v_add_f32_e32 v127, 1.0, v158
	v_lshlrev_b32_e32 v126, 16, v155
	v_fmac_f32_e32 v126, v128, v117
	s_cselect_b32 s58, s42, s72
	v_lshlrev_b32_e32 v190, 16, v160
	v_mul_f32_e32 v190, 0xbfb8aa3b, v190
	v_exp_f32_e32 v190, v190
	v_rcp_f32_e32 v117, v127
	s_nop 0
	v_add_f32_e32 v128, 1.0, v190
	v_and_b32_e32 v127, 0xffff0000, v155
	v_fmac_f32_e32 v127, v129, v117
	v_and_b32_e32 v155, 0xffff0000, v160
	v_mul_f32_e32 v155, 0xbfb8aa3b, v155
	v_exp_f32_e32 v155, v155
	v_rcp_f32_e32 v117, v128
	s_nop 0
	v_add_f32_e32 v129, 1.0, v155
	v_lshlrev_b32_e32 v128, 16, v156
	v_fmac_f32_e32 v128, v122, v117
	v_lshlrev_b32_e32 v159, 16, v161
	v_mul_f32_e32 v159, 0xbfb8aa3b, v159
	v_exp_f32_e32 v159, v159
	v_rcp_f32_e32 v117, v129
	s_nop 0
	v_add_f32_e32 v122, 1.0, v159
	v_and_b32_e32 v129, 0xffff0000, v156
	v_fmac_f32_e32 v129, v123, v117
	v_and_b32_e32 v156, 0xffff0000, v161
	v_mul_f32_e32 v156, 0xbfb8aa3b, v156
	v_exp_f32_e32 v156, v156
	v_rcp_f32_e32 v117, v122
	s_nop 0
	v_add_f32_e32 v123, 1.0, v156
	v_div_scale_f32 v155, s[4:5], v123, v123, 1.0
	v_rcp_f32_e32 v156, v155
	v_lshlrev_b32_e32 v158, 16, v157
	v_fmac_f32_e32 v158, v124, v117
	v_fma_f32 v117, -v155, v156, 1.0
	v_fmac_f32_e32 v156, v117, v156
	v_rcp_f32_e32 v117, v123
	s_nop 0
	v_and_b32_e32 v155, 0xffff0000, v157
	v_fmac_f32_e32 v155, v125, v117
	v_lshlrev_b32_e32 v117, 16, v150
	v_mul_f32_e32 v117, 0xbfb8aa3b, v117
	v_exp_f32_e32 v117, v117
	v_cvt_pk_bf16_f32 v124, v128, v129
	v_cvt_pk_bf16_f32 v122, v185, v154
	v_cvt_pk_bf16_f32 v125, v158, v155
	v_lshl_add_u64 v[154:155], s[58:59], 0, v[188:189]
	v_add_f32_e32 v117, 1.0, v117
	v_cvt_pk_bf16_f32 v123, v126, v127
	v_lshl_add_u64 v[126:127], v[154:155], 0, v[168:169]
	global_store_dwordx4 v[126:127], v[122:125], off
	s_nop 1
	v_and_b32_e32 v124, 0xffff0000, v150
	v_mul_f32_e32 v124, 0xbfb8aa3b, v124
	v_exp_f32_e32 v124, v124
	v_rcp_f32_e32 v117, v117
	s_nop 0
	v_add_f32_e32 v123, 1.0, v124
	v_lshlrev_b32_e32 v122, 16, v146
	v_fmac_f32_e32 v122, v118, v117
	v_lshlrev_b32_e32 v128, 16, v151
	v_mul_f32_e32 v128, 0xbfb8aa3b, v128
	v_exp_f32_e32 v128, v128
	v_rcp_f32_e32 v117, v123
	s_nop 0
	v_add_f32_e32 v118, 1.0, v128
	v_and_b32_e32 v123, 0xffff0000, v146
	v_fmac_f32_e32 v123, v119, v117
	v_and_b32_e32 v128, 0xffff0000, v151
	v_mul_f32_e32 v128, 0xbfb8aa3b, v128
	v_exp_f32_e32 v128, v128
	v_rcp_f32_e32 v117, v118
	s_nop 0
	v_add_f32_e32 v119, 1.0, v128
	v_lshlrev_b32_e32 v118, 16, v147
	v_fmac_f32_e32 v118, v120, v117
	v_lshlrev_b32_e32 v128, 16, v152
	v_mul_f32_e32 v128, 0xbfb8aa3b, v128
	v_exp_f32_e32 v128, v128
	v_rcp_f32_e32 v117, v119
	s_nop 0
	v_add_f32_e32 v120, 1.0, v128
	v_and_b32_e32 v119, 0xffff0000, v147
	v_fmac_f32_e32 v119, v121, v117
	v_and_b32_e32 v128, 0xffff0000, v152
	v_mul_f32_e32 v128, 0xbfb8aa3b, v128
	v_exp_f32_e32 v128, v128
	v_rcp_f32_e32 v117, v120
	s_nop 0
	v_add_f32_e32 v121, 1.0, v128
	v_lshlrev_b32_e32 v120, 16, v148
	v_fmac_f32_e32 v120, v112, v117
	v_lshlrev_b32_e32 v128, 16, v153
	v_mul_f32_e32 v128, 0xbfb8aa3b, v128
	v_exp_f32_e32 v128, v128
	v_rcp_f32_e32 v112, v121
	s_nop 0
	v_add_f32_e32 v117, 1.0, v128
	v_and_b32_e32 v121, 0xffff0000, v148
	v_fmac_f32_e32 v121, v113, v112
	v_and_b32_e32 v128, 0xffff0000, v153
	v_mul_f32_e32 v128, 0xbfb8aa3b, v128
	v_exp_f32_e32 v128, v128
	v_rcp_f32_e32 v112, v117
	s_nop 0
	v_add_f32_e32 v113, 1.0, v128
	v_div_scale_f32 v124, s[4:5], v113, v113, 1.0
	v_rcp_f32_e32 v125, v124
	v_lshlrev_b32_e32 v117, 16, v149
	v_fmac_f32_e32 v117, v114, v112
	v_fma_f32 v112, -v124, v125, 1.0
	v_fmac_f32_e32 v125, v112, v125
	v_rcp_f32_e32 v112, v113
	s_nop 0
	v_lshlrev_b32_e32 v113, 16, v142
	v_mul_f32_e32 v113, 0xbfb8aa3b, v113
	v_exp_f32_e32 v114, v113
	v_cvt_pk_bf16_f32 v113, v118, v119
	v_and_b32_e32 v124, 0xffff0000, v149
	v_fmac_f32_e32 v124, v115, v112
	v_add_f32_e32 v118, 1.0, v114
	v_div_scale_f32 v119, s[4:5], v118, v118, 1.0
	v_cvt_pk_bf16_f32 v112, v122, v123
	v_rcp_f32_e32 v122, v119
	v_cvt_pk_bf16_f32 v114, v120, v121
	v_cvt_pk_bf16_f32 v115, v117, v124
	global_store_dwordx4 v[126:127], v[112:115], off offset:256
	v_lshlrev_b32_e32 v117, 16, v138
	s_nop 0
	v_fma_f32 v112, -v119, v122, 1.0
	v_fmac_f32_e32 v122, v112, v122
	v_and_b32_e32 v114, 0xffff0000, v142
	v_mul_f32_e32 v114, 0xbfb8aa3b, v114
	v_exp_f32_e32 v114, v114
	v_rcp_f32_e32 v112, v118
	s_nop 0
	v_add_f32_e32 v113, 1.0, v114
	v_fmac_f32_e32 v117, v108, v112
	v_lshlrev_b32_e32 v118, 16, v143
	v_mul_f32_e32 v118, 0xbfb8aa3b, v118
	v_exp_f32_e32 v118, v118
	v_rcp_f32_e32 v108, v113
	s_nop 0
	v_add_f32_e32 v112, 1.0, v118
	v_and_b32_e32 v113, 0xffff0000, v138
	v_fmac_f32_e32 v113, v109, v108
	v_and_b32_e32 v118, 0xffff0000, v143
	v_mul_f32_e32 v118, 0xbfb8aa3b, v118
	v_exp_f32_e32 v118, v118
	v_rcp_f32_e32 v108, v112
	s_nop 0
	v_add_f32_e32 v109, 1.0, v118
	v_lshlrev_b32_e32 v112, 16, v139
	v_fmac_f32_e32 v112, v110, v108
	v_lshlrev_b32_e32 v118, 16, v144
	v_mul_f32_e32 v118, 0xbfb8aa3b, v118
	v_exp_f32_e32 v118, v118
	v_rcp_f32_e32 v108, v109
	s_nop 0
	v_add_f32_e32 v110, 1.0, v118
	v_and_b32_e32 v109, 0xffff0000, v139
	v_fmac_f32_e32 v109, v111, v108
	v_and_b32_e32 v118, 0xffff0000, v144
	v_mul_f32_e32 v118, 0xbfb8aa3b, v118
	v_exp_f32_e32 v118, v118
	v_rcp_f32_e32 v108, v110
	s_nop 0
	v_add_f32_e32 v111, 1.0, v118
	v_lshlrev_b32_e32 v110, 16, v140
	v_fmac_f32_e32 v110, v104, v108
	v_lshlrev_b32_e32 v118, 16, v145
	v_mul_f32_e32 v118, 0xbfb8aa3b, v118
	v_exp_f32_e32 v118, v118
	v_rcp_f32_e32 v104, v111
	s_nop 0
	v_add_f32_e32 v108, 1.0, v118
	v_and_b32_e32 v111, 0xffff0000, v140
	v_fmac_f32_e32 v111, v105, v104
	v_and_b32_e32 v118, 0xffff0000, v145
	v_mul_f32_e32 v118, 0xbfb8aa3b, v118
	v_exp_f32_e32 v118, v118
	v_rcp_f32_e32 v104, v108
	s_nop 0
	v_add_f32_e32 v105, 1.0, v118
	v_div_scale_f32 v114, s[4:5], v105, v105, 1.0
	v_rcp_f32_e32 v115, v114
	v_lshlrev_b32_e32 v108, 16, v141
	v_fmac_f32_e32 v108, v106, v104
	v_fma_f32 v104, -v114, v115, 1.0
	v_fmac_f32_e32 v115, v104, v115
	v_div_scale_f32 v104, vcc, 1.0, v105, 1.0
	v_mul_f32_e32 v106, v104, v115
	v_fma_f32 v118, -v114, v106, v104
	v_rcp_f32_e32 v104, v105
	s_nop 0
	v_lshlrev_b32_e32 v105, 16, v134
	v_and_b32_e32 v114, 0xffff0000, v141
	v_mul_f32_e32 v105, 0xbfb8aa3b, v105
	v_fmac_f32_e32 v114, v107, v104
	v_cvt_pk_bf16_f32 v104, v117, v113
	v_exp_f32_e32 v113, v105
	v_cvt_pk_bf16_f32 v106, v110, v111
	v_cvt_pk_bf16_f32 v105, v112, v109
	v_cvt_pk_bf16_f32 v107, v108, v114
	v_lshl_add_u64 v[108:109], s[58:59], 0, v[186:187]
	v_add_f32_e32 v110, 1.0, v113
	v_div_scale_f32 v111, s[4:5], v110, v110, 1.0
	v_rcp_f32_e32 v112, v111
	v_lshl_add_u64 v[108:109], v[108:109], 0, v[168:169]
	global_store_dwordx4 v[108:109], v[104:107], off
	v_mov_b32_e32 v117, 0
	v_mov_b32_e32 v114, 0
	v_fma_f32 v104, -v111, v112, 1.0
	v_fmac_f32_e32 v112, v104, v112
	v_and_b32_e32 v106, 0xffff0000, v134
	v_mul_f32_e32 v106, 0xbfb8aa3b, v106
	v_exp_f32_e32 v106, v106
	v_rcp_f32_e32 v104, v110
	s_nop 0
	v_add_f32_e32 v105, 1.0, v106
	v_lshlrev_b32_e32 v110, 16, v130
	v_fmac_f32_e32 v110, v100, v104
	v_mov_b32_e32 v115, 0
	v_lshlrev_b32_e32 v111, 16, v135
	v_mul_f32_e32 v111, 0xbfb8aa3b, v111
	v_exp_f32_e32 v111, v111
	v_rcp_f32_e32 v100, v105
	s_nop 0
	v_add_f32_e32 v104, 1.0, v111
	v_and_b32_e32 v105, 0xffff0000, v130
	v_fmac_f32_e32 v105, v101, v100
	v_and_b32_e32 v111, 0xffff0000, v135
	v_mul_f32_e32 v111, 0xbfb8aa3b, v111
	v_exp_f32_e32 v111, v111
	v_rcp_f32_e32 v100, v104
	s_nop 0
	v_add_f32_e32 v101, 1.0, v111
	v_lshlrev_b32_e32 v104, 16, v131
	v_fmac_f32_e32 v104, v102, v100
	v_lshlrev_b32_e32 v111, 16, v136
	v_mul_f32_e32 v111, 0xbfb8aa3b, v111
	v_exp_f32_e32 v111, v111
	v_rcp_f32_e32 v100, v101
	s_nop 0
	v_add_f32_e32 v102, 1.0, v111
	v_and_b32_e32 v101, 0xffff0000, v131
	v_fmac_f32_e32 v101, v103, v100
	v_and_b32_e32 v111, 0xffff0000, v136
	v_mul_f32_e32 v111, 0xbfb8aa3b, v111
	v_exp_f32_e32 v111, v111
	v_rcp_f32_e32 v100, v102
	s_nop 0
	v_add_f32_e32 v103, 1.0, v111
	v_lshlrev_b32_e32 v102, 16, v132
	v_fmac_f32_e32 v102, v96, v100
	v_lshlrev_b32_e32 v111, 16, v137
	v_mul_f32_e32 v111, 0xbfb8aa3b, v111
	v_exp_f32_e32 v111, v111
	v_rcp_f32_e32 v96, v103
	s_nop 0
	v_add_f32_e32 v100, 1.0, v111
	v_and_b32_e32 v103, 0xffff0000, v132
	v_fmac_f32_e32 v103, v97, v96
	v_and_b32_e32 v111, 0xffff0000, v137
	v_mul_f32_e32 v111, 0xbfb8aa3b, v111
	v_exp_f32_e32 v111, v111
	v_rcp_f32_e32 v96, v100
	s_nop 0
	v_add_f32_e32 v97, 1.0, v111
	v_div_scale_f32 v106, s[4:5], v97, v97, 1.0
	v_rcp_f32_e32 v107, v106
	v_lshlrev_b32_e32 v100, 16, v133
	v_fmac_f32_e32 v100, v98, v96
	v_fma_f32 v96, -v106, v107, 1.0
	v_fmac_f32_e32 v107, v96, v107
	v_div_scale_f32 v96, vcc, 1.0, v97, 1.0
	v_mul_f32_e32 v98, v96, v107
	v_fma_f32 v111, -v106, v98, v96
	v_rcp_f32_e32 v96, v97
	s_nop 0
	v_and_b32_e32 v106, 0xffff0000, v133
	v_fmac_f32_e32 v106, v99, v96
	v_cvt_pk_bf16_f32 v96, v110, v105
	v_cvt_pk_bf16_f32 v98, v102, v103
	v_cvt_pk_bf16_f32 v99, v100, v106
	v_cvt_pk_bf16_f32 v97, v104, v101
	global_store_dwordx4 v[108:109], v[96:99], off offset:256
	s_nop 1
	v_or_b32_e32 v96, 32, v184
	v_mov_b64_e32 v[98:99], s[24:25]
	v_mad_i64_i32 v[98:99], s[4:5], v96, s82, v[98:99]
	v_lshl_add_u64 v[98:99], s[56:57], 1, v[98:99]
	v_lshl_add_u64 v[98:99], v[98:99], 0, v[168:169]
	v_add_co_u32_e32 v100, vcc, 0x5000, v98
	v_ashrrev_i32_e32 v97, 31, v96
	s_nop 0
	v_addc_co_u32_e32 v101, vcc, 0, v99, vcc
	global_load_dwordx4 v[126:129], v[100:101], off offset:2560 nt
	v_lshlrev_b64 v[132:133], 12, v[96:97]
	s_and_b64 vcc, exec, s[40:41]
	v_lshl_add_u64 v[96:97], s[42:43], 0, v[132:133]
	s_cbranch_vccnz .LBB0_607
	v_lshl_add_u64 v[100:101], v[96:97], 0, v[168:169]
	global_load_dwordx4 v[114:117], v[100:101], off
.LBB0_607:
	v_lshl_add_u64 v[98:99], v[98:99], 0, s[8:9]
	global_load_dwordx4 v[122:125], v[98:99], off offset:256 nt
	v_mov_b32_e32 v108, 0
	s_and_b64 vcc, exec, s[40:41]
	v_mov_b32_e32 v120, 0
	v_mov_b32_e32 v121, 0
	v_mov_b32_e32 v118, 0
	v_mov_b32_e32 v119, 0
	s_cbranch_vccnz .LBB0_609
	v_lshl_add_u64 v[96:97], v[96:97], 0, v[168:169]
	global_load_dwordx4 v[118:121], v[96:97], off offset:256
.LBB0_609:
	v_or_b32_e32 v98, 48, v184
	v_mov_b64_e32 v[96:97], s[24:25]
	v_mad_i64_i32 v[96:97], s[4:5], v98, s82, v[96:97]
	v_lshl_add_u64 v[96:97], s[56:57], 1, v[96:97]
	v_lshl_add_u64 v[96:97], v[96:97], 0, v[168:169]
	v_add_co_u32_e32 v100, vcc, 0x5000, v96
	v_ashrrev_i32_e32 v99, 31, v98
	s_nop 0
	v_addc_co_u32_e32 v101, vcc, 0, v97, vcc
	global_load_dwordx4 v[110:113], v[100:101], off offset:2560 nt
	v_lshlrev_b64 v[130:131], 12, v[98:99]
	s_and_b64 vcc, exec, s[40:41]
	v_lshl_add_u64 v[134:135], s[42:43], 0, v[130:131]
	v_mov_b32_e32 v109, 0
	v_mov_b32_e32 v106, 0
	v_mov_b32_e32 v107, 0
	s_cbranch_vccnz .LBB0_611
	v_lshl_add_u64 v[98:99], v[134:135], 0, v[168:169]
	global_load_dwordx4 v[106:109], v[98:99], off
.LBB0_611:
	v_lshl_add_u64 v[96:97], v[96:97], 0, s[8:9]
	global_load_dwordx4 v[102:105], v[96:97], off offset:256 nt
	v_mov_b32_e32 v96, 0
	s_and_b64 vcc, exec, s[40:41]
	v_mov_b32_e32 v100, 0
	v_mov_b32_e32 v101, 0
	v_mov_b32_e32 v98, 0
	v_mov_b32_e32 v99, 0
	s_cbranch_vccnz .LBB0_613
	v_lshl_add_u64 v[98:99], v[134:135], 0, v[168:169]
	global_load_dwordx4 v[98:101], v[98:99], off offset:256
.LBB0_613:
	s_waitcnt vmcnt(3)
	v_lshlrev_b32_e32 v97, 16, v126
	v_mul_f32_e32 v97, 0xbfb8aa3b, v97
	v_exp_f32_e32 v97, v97
	v_and_b32_e32 v126, 0xffff0000, v126
	v_mul_f32_e32 v126, 0xbfb8aa3b, v126
	v_exp_f32_e32 v126, v126
	v_add_f32_e32 v97, 1.0, v97
	v_div_scale_f32 v134, s[4:5], v97, v97, 1.0
	v_rcp_f32_e32 v135, v134
	v_div_scale_f32 v136, vcc, 1.0, v97, 1.0
	v_add_f32_e32 v126, 1.0, v126
	v_fma_f32 v137, -v134, v135, 1.0
	v_fmac_f32_e32 v135, v137, v135
	v_mul_f32_e32 v137, v136, v135
	v_fma_f32 v138, -v134, v137, v136
	v_rcp_f32_e32 v97, v97
	s_nop 0
	v_lshlrev_b32_e32 v134, 16, v114
	v_fmac_f32_e32 v134, v92, v97
	v_lshlrev_b32_e32 v137, 16, v127
	v_mul_f32_e32 v137, 0xbfb8aa3b, v137
	v_exp_f32_e32 v137, v137
	v_rcp_f32_e32 v92, v126
	s_nop 0
	v_add_f32_e32 v97, 1.0, v137
	v_div_scale_f32 v135, s[4:5], v97, v97, 1.0
	v_rcp_f32_e32 v136, v135
	v_and_b32_e32 v114, 0xffff0000, v114
	v_fmac_f32_e32 v114, v93, v92
	v_fma_f32 v92, -v135, v136, 1.0
	v_fmac_f32_e32 v136, v92, v136
	v_and_b32_e32 v126, 0xffff0000, v127
	v_mul_f32_e32 v126, 0xbfb8aa3b, v126
	v_exp_f32_e32 v126, v126
	v_rcp_f32_e32 v92, v97
	s_nop 0
	v_add_f32_e32 v93, 1.0, v126
	v_lshlrev_b32_e32 v97, 16, v115
	v_fmac_f32_e32 v97, v94, v92
	v_lshlrev_b32_e32 v135, 16, v128
	v_mul_f32_e32 v135, 0xbfb8aa3b, v135
	v_exp_f32_e32 v135, v135
	v_rcp_f32_e32 v92, v93
	s_nop 0
	v_add_f32_e32 v94, 1.0, v135
	v_and_b32_e32 v93, 0xffff0000, v115
	v_fmac_f32_e32 v93, v95, v92
	v_and_b32_e32 v115, 0xffff0000, v128
	v_mul_f32_e32 v115, 0xbfb8aa3b, v115
	v_exp_f32_e32 v115, v115
	v_rcp_f32_e32 v92, v94
	s_nop 0
	v_add_f32_e32 v95, 1.0, v115
	v_lshlrev_b32_e32 v94, 16, v116
	v_fmac_f32_e32 v94, v88, v92
	v_lshlrev_b32_e32 v127, 16, v129
	v_mul_f32_e32 v127, 0xbfb8aa3b, v127
	v_exp_f32_e32 v127, v127
	v_rcp_f32_e32 v88, v95
	s_nop 0
	v_add_f32_e32 v92, 1.0, v127
	v_and_b32_e32 v95, 0xffff0000, v116
	v_fmac_f32_e32 v95, v89, v88
	v_and_b32_e32 v116, 0xffff0000, v129
	v_mul_f32_e32 v116, 0xbfb8aa3b, v116
	v_exp_f32_e32 v116, v116
	v_rcp_f32_e32 v88, v92
	s_nop 0
	v_add_f32_e32 v89, 1.0, v116
	v_div_scale_f32 v115, s[4:5], v89, v89, 1.0
	v_rcp_f32_e32 v116, v115
	v_lshlrev_b32_e32 v92, 16, v117
	v_fmac_f32_e32 v92, v90, v88
	v_fma_f32 v88, -v115, v116, 1.0
	v_fmac_f32_e32 v116, v88, v116
	v_div_scale_f32 v88, vcc, 1.0, v89, 1.0
	v_mul_f32_e32 v90, v88, v116
	v_fma_f32 v126, -v115, v90, v88
	v_rcp_f32_e32 v88, v89
	s_nop 0
	s_waitcnt vmcnt(2)
	v_lshlrev_b32_e32 v89, 16, v122
	v_and_b32_e32 v115, 0xffff0000, v117
	v_mul_f32_e32 v89, 0xbfb8aa3b, v89
	v_fmac_f32_e32 v115, v91, v88
	v_cvt_pk_bf16_f32 v88, v134, v114
	v_exp_f32_e32 v114, v89
	v_cvt_pk_bf16_f32 v90, v94, v95
	v_cvt_pk_bf16_f32 v89, v97, v93
	v_cvt_pk_bf16_f32 v91, v92, v115
	v_lshl_add_u64 v[92:93], s[58:59], 0, v[132:133]
	v_add_f32_e32 v94, 1.0, v114
	v_lshl_add_u64 v[92:93], v[92:93], 0, v[168:169]
	global_store_dwordx4 v[92:93], v[88:91], off
	s_nop 1
	v_and_b32_e32 v90, 0xffff0000, v122
	v_mul_f32_e32 v90, 0xbfb8aa3b, v90
	v_exp_f32_e32 v90, v90
	v_rcp_f32_e32 v88, v94
	s_nop 0
	v_add_f32_e32 v89, 1.0, v90
	v_lshlrev_b32_e32 v94, 16, v118
	v_fmac_f32_e32 v94, v84, v88
	v_mov_b32_e32 v97, 0
	v_lshlrev_b32_e32 v95, 16, v123
	v_mul_f32_e32 v95, 0xbfb8aa3b, v95
	v_exp_f32_e32 v95, v95
	v_rcp_f32_e32 v84, v89
	s_nop 0
	v_add_f32_e32 v88, 1.0, v95
	v_and_b32_e32 v89, 0xffff0000, v118
	v_fmac_f32_e32 v89, v85, v84
	v_and_b32_e32 v95, 0xffff0000, v123
	v_mul_f32_e32 v95, 0xbfb8aa3b, v95
	v_exp_f32_e32 v95, v95
	v_rcp_f32_e32 v84, v88
	s_nop 0
	v_add_f32_e32 v85, 1.0, v95
	v_lshlrev_b32_e32 v88, 16, v119
	v_fmac_f32_e32 v88, v86, v84
	v_lshlrev_b32_e32 v95, 16, v124
	v_mul_f32_e32 v95, 0xbfb8aa3b, v95
	v_exp_f32_e32 v95, v95
	v_rcp_f32_e32 v84, v85
	s_nop 0
	v_add_f32_e32 v86, 1.0, v95
	v_and_b32_e32 v85, 0xffff0000, v119
	v_fmac_f32_e32 v85, v87, v84
	v_and_b32_e32 v95, 0xffff0000, v124
	v_mul_f32_e32 v95, 0xbfb8aa3b, v95
	v_exp_f32_e32 v95, v95
	v_rcp_f32_e32 v84, v86
	s_nop 0
	v_add_f32_e32 v87, 1.0, v95
	v_lshlrev_b32_e32 v86, 16, v120
	v_fmac_f32_e32 v86, v80, v84
	v_lshlrev_b32_e32 v95, 16, v125
	v_mul_f32_e32 v95, 0xbfb8aa3b, v95
	v_exp_f32_e32 v95, v95
	v_rcp_f32_e32 v80, v87
	s_nop 0
	v_add_f32_e32 v84, 1.0, v95
	v_and_b32_e32 v87, 0xffff0000, v120
	v_fmac_f32_e32 v87, v81, v80
	v_and_b32_e32 v95, 0xffff0000, v125
	v_mul_f32_e32 v95, 0xbfb8aa3b, v95
	v_exp_f32_e32 v95, v95
	v_rcp_f32_e32 v80, v84
	s_nop 0
	v_add_f32_e32 v81, 1.0, v95
	v_lshlrev_b32_e32 v84, 16, v121
	v_fmac_f32_e32 v84, v82, v80
	v_rcp_f32_e32 v80, v81
	s_nop 0
	s_waitcnt vmcnt(2)
	v_lshlrev_b32_e32 v81, 16, v110
	v_mul_f32_e32 v81, 0xbfb8aa3b, v81
	v_exp_f32_e32 v82, v81
	v_cvt_pk_bf16_f32 v81, v88, v85
	v_and_b32_e32 v90, 0xffff0000, v121
	v_fmac_f32_e32 v90, v83, v80
	v_add_f32_e32 v85, 1.0, v82
	v_div_scale_f32 v88, s[4:5], v85, v85, 1.0
	v_cvt_pk_bf16_f32 v80, v94, v89
	v_rcp_f32_e32 v89, v88
	v_cvt_pk_bf16_f32 v82, v86, v87
	v_cvt_pk_bf16_f32 v83, v84, v90
	global_store_dwordx4 v[92:93], v[80:83], off offset:256
	v_lshlrev_b32_e32 v84, 16, v106
	v_mov_b32_e32 v94, 0
	v_fma_f32 v80, -v88, v89, 1.0
	v_fmac_f32_e32 v89, v80, v89
	v_and_b32_e32 v82, 0xffff0000, v110
	v_mul_f32_e32 v82, 0xbfb8aa3b, v82
	v_exp_f32_e32 v82, v82
	v_rcp_f32_e32 v80, v85
	s_nop 0
	v_add_f32_e32 v81, 1.0, v82
	v_fmac_f32_e32 v84, v76, v80
	v_mov_b32_e32 v95, 0
	v_lshlrev_b32_e32 v85, 16, v111
	v_mul_f32_e32 v85, 0xbfb8aa3b, v85
	v_exp_f32_e32 v85, v85
	v_rcp_f32_e32 v76, v81
	s_nop 0
	v_add_f32_e32 v80, 1.0, v85
	v_and_b32_e32 v81, 0xffff0000, v106
	v_fmac_f32_e32 v81, v77, v76
	v_and_b32_e32 v85, 0xffff0000, v111
	v_mul_f32_e32 v85, 0xbfb8aa3b, v85
	v_exp_f32_e32 v85, v85
	v_rcp_f32_e32 v76, v80
	s_nop 0
	v_add_f32_e32 v77, 1.0, v85
	v_lshlrev_b32_e32 v80, 16, v107
	v_fmac_f32_e32 v80, v78, v76
	v_lshlrev_b32_e32 v85, 16, v112
	v_mul_f32_e32 v85, 0xbfb8aa3b, v85
	v_exp_f32_e32 v85, v85
	v_rcp_f32_e32 v76, v77
	s_nop 0
	v_add_f32_e32 v78, 1.0, v85
	v_and_b32_e32 v77, 0xffff0000, v107
	v_fmac_f32_e32 v77, v79, v76
	v_and_b32_e32 v85, 0xffff0000, v112
	v_mul_f32_e32 v85, 0xbfb8aa3b, v85
	v_exp_f32_e32 v85, v85
	v_rcp_f32_e32 v76, v78
	s_nop 0
	v_add_f32_e32 v79, 1.0, v85
	v_lshlrev_b32_e32 v78, 16, v108
	v_fmac_f32_e32 v78, v72, v76
	v_lshlrev_b32_e32 v85, 16, v113
	v_mul_f32_e32 v85, 0xbfb8aa3b, v85
	v_exp_f32_e32 v85, v85
	v_rcp_f32_e32 v72, v79
	s_nop 0
	v_add_f32_e32 v76, 1.0, v85
	v_and_b32_e32 v79, 0xffff0000, v108
	v_fmac_f32_e32 v79, v73, v72
	v_and_b32_e32 v85, 0xffff0000, v113
	v_mul_f32_e32 v85, 0xbfb8aa3b, v85
	v_exp_f32_e32 v85, v85
	v_rcp_f32_e32 v72, v76
	s_nop 0
	v_add_f32_e32 v73, 1.0, v85
	v_div_scale_f32 v82, s[4:5], v73, v73, 1.0
	v_rcp_f32_e32 v83, v82
	v_lshlrev_b32_e32 v76, 16, v109
	v_fmac_f32_e32 v76, v74, v72
	v_fma_f32 v72, -v82, v83, 1.0
	v_fmac_f32_e32 v83, v72, v83
	v_div_scale_f32 v72, vcc, 1.0, v73, 1.0
	v_mul_f32_e32 v74, v72, v83
	v_fma_f32 v85, -v82, v74, v72
	v_rcp_f32_e32 v72, v73
	s_nop 0
	s_waitcnt vmcnt(2)
	v_lshlrev_b32_e32 v73, 16, v102
	v_and_b32_e32 v82, 0xffff0000, v109
	v_mul_f32_e32 v73, 0xbfb8aa3b, v73
	v_fmac_f32_e32 v82, v75, v72
	v_cvt_pk_bf16_f32 v72, v84, v81
	v_exp_f32_e32 v81, v73
	v_cvt_pk_bf16_f32 v74, v78, v79
	v_cvt_pk_bf16_f32 v73, v80, v77
	v_cvt_pk_bf16_f32 v75, v76, v82
	v_lshl_add_u64 v[76:77], s[58:59], 0, v[130:131]
	v_add_f32_e32 v78, 1.0, v81
	v_div_scale_f32 v79, s[4:5], v78, v78, 1.0
	v_rcp_f32_e32 v80, v79
	v_lshl_add_u64 v[76:77], v[76:77], 0, v[168:169]
	global_store_dwordx4 v[76:77], v[72:75], off
	s_nop 1
	v_fma_f32 v72, -v79, v80, 1.0
	v_fmac_f32_e32 v80, v72, v80
	v_and_b32_e32 v74, 0xffff0000, v102
	v_mul_f32_e32 v74, 0xbfb8aa3b, v74
	v_exp_f32_e32 v74, v74
	v_rcp_f32_e32 v72, v78
	s_nop 0
	v_add_f32_e32 v73, 1.0, v74
	v_lshlrev_b32_e32 v78, 16, v98
	v_fmac_f32_e32 v78, v68, v72
	v_lshlrev_b32_e32 v79, 16, v103
	v_mul_f32_e32 v79, 0xbfb8aa3b, v79
	v_exp_f32_e32 v79, v79
	v_rcp_f32_e32 v68, v73
	s_nop 0
	v_add_f32_e32 v72, 1.0, v79
	v_and_b32_e32 v73, 0xffff0000, v98
	v_fmac_f32_e32 v73, v69, v68
	v_and_b32_e32 v79, 0xffff0000, v103
	v_mul_f32_e32 v79, 0xbfb8aa3b, v79
	v_exp_f32_e32 v79, v79
	v_rcp_f32_e32 v68, v72
	s_nop 0
	v_add_f32_e32 v69, 1.0, v79
	v_lshlrev_b32_e32 v72, 16, v99
	v_fmac_f32_e32 v72, v70, v68
	v_lshlrev_b32_e32 v79, 16, v104
	v_mul_f32_e32 v79, 0xbfb8aa3b, v79
	v_exp_f32_e32 v79, v79
	v_rcp_f32_e32 v68, v69
	s_nop 0
	v_add_f32_e32 v70, 1.0, v79
	v_and_b32_e32 v69, 0xffff0000, v99
	v_fmac_f32_e32 v69, v71, v68
	v_and_b32_e32 v79, 0xffff0000, v104
	v_mul_f32_e32 v79, 0xbfb8aa3b, v79
	v_exp_f32_e32 v79, v79
	v_rcp_f32_e32 v68, v70
	s_nop 0
	v_add_f32_e32 v71, 1.0, v79
	v_lshlrev_b32_e32 v70, 16, v100
	v_fmac_f32_e32 v70, v64, v68
	v_lshlrev_b32_e32 v79, 16, v105
	v_mul_f32_e32 v79, 0xbfb8aa3b, v79
	v_exp_f32_e32 v79, v79
	v_rcp_f32_e32 v64, v71
	s_nop 0
	v_add_f32_e32 v68, 1.0, v79
	v_and_b32_e32 v71, 0xffff0000, v100
	v_fmac_f32_e32 v71, v65, v64
	v_and_b32_e32 v79, 0xffff0000, v105
	v_mul_f32_e32 v79, 0xbfb8aa3b, v79
	v_exp_f32_e32 v79, v79
	v_rcp_f32_e32 v64, v68
	s_nop 0
	v_add_f32_e32 v65, 1.0, v79
	v_div_scale_f32 v74, s[4:5], v65, v65, 1.0
	v_rcp_f32_e32 v75, v74
	v_lshlrev_b32_e32 v68, 16, v101
	v_fmac_f32_e32 v68, v66, v64
	v_fma_f32 v64, -v74, v75, 1.0
	v_fmac_f32_e32 v75, v64, v75
	v_div_scale_f32 v64, vcc, 1.0, v65, 1.0
	v_mul_f32_e32 v66, v64, v75
	v_fma_f32 v79, -v74, v66, v64
	v_rcp_f32_e32 v64, v65
	s_nop 0
	v_and_b32_e32 v74, 0xffff0000, v101
	v_fmac_f32_e32 v74, v67, v64
	v_cvt_pk_bf16_f32 v64, v78, v73
	v_cvt_pk_bf16_f32 v66, v70, v71
	v_cvt_pk_bf16_f32 v67, v68, v74
	v_cvt_pk_bf16_f32 v65, v72, v69
	global_store_dwordx4 v[76:77], v[64:67], off offset:256
	s_nop 1
	v_add_u32_e32 v64, 0x80, v184
	v_mov_b64_e32 v[66:67], s[24:25]
	v_mad_i64_i32 v[66:67], s[4:5], v64, s82, v[66:67]
	v_lshl_add_u64 v[66:67], s[56:57], 1, v[66:67]
	v_lshl_add_u64 v[68:69], v[66:67], 0, v[168:169]
	v_add_co_u32_e32 v66, vcc, 0x5000, v68
	v_ashrrev_i32_e32 v65, 31, v64
	s_nop 0
	v_addc_co_u32_e32 v67, vcc, 0, v69, vcc
	global_load_dwordx4 v[90:93], v[66:67], off offset:2560 nt
	v_lshlrev_b64 v[98:99], 12, v[64:65]
	s_and_b64 vcc, exec, s[40:41]
	v_lshl_add_u64 v[66:67], s[42:43], 0, v[98:99]
	s_cbranch_vccnz .LBB0_615
	v_lshl_add_u64 v[70:71], v[66:67], 0, v[168:169]
	global_load_dwordx4 v[94:97], v[70:71], off
.LBB0_615:
	v_lshl_add_u64 v[68:69], v[68:69], 0, s[8:9]
	global_load_dwordx4 v[86:89], v[68:69], off offset:256 nt
	v_mov_b32_e32 v76, 0
	s_and_b64 vcc, exec, s[40:41]
	v_mov_b32_e32 v84, 0
	v_mov_b32_e32 v85, 0
	v_mov_b32_e32 v82, 0
	v_mov_b32_e32 v83, 0
	s_cbranch_vccnz .LBB0_617
	v_lshl_add_u64 v[66:67], v[66:67], 0, v[168:169]
	global_load_dwordx4 v[82:85], v[66:67], off offset:256
.LBB0_617:
	v_or_b32_e32 v66, 16, v64
	v_mov_b64_e32 v[64:65], s[24:25]
	v_mad_i64_i32 v[64:65], s[4:5], v66, s82, v[64:65]
	v_lshl_add_u64 v[64:65], s[56:57], 1, v[64:65]
	v_lshl_add_u64 v[64:65], v[64:65], 0, v[168:169]
	v_add_co_u32_e32 v68, vcc, 0x5000, v64
	v_ashrrev_i32_e32 v67, 31, v66
	s_nop 0
	v_addc_co_u32_e32 v69, vcc, 0, v65, vcc
	global_load_dwordx4 v[78:81], v[68:69], off offset:2560 nt
	v_lshlrev_b64 v[66:67], 12, v[66:67]
	s_and_b64 vcc, exec, s[40:41]
	v_lshl_add_u64 v[100:101], s[42:43], 0, v[66:67]
	v_mov_b32_e32 v77, 0
	v_mov_b32_e32 v74, 0
	v_mov_b32_e32 v75, 0
	s_cbranch_vccnz .LBB0_619
	v_lshl_add_u64 v[66:67], v[100:101], 0, v[168:169]
	global_load_dwordx4 v[74:77], v[66:67], off
.LBB0_619:
	v_lshl_add_u64 v[64:65], v[64:65], 0, s[8:9]
	global_load_dwordx4 v[70:73], v[64:65], off offset:256 nt
	v_mov_b32_e32 v64, 0
	s_and_b64 vcc, exec, s[40:41]
	v_mov_b32_e32 v68, 0
	v_mov_b32_e32 v69, 0
	v_mov_b32_e32 v66, 0
	v_mov_b32_e32 v67, 0
	s_cbranch_vccnz .LBB0_621
	v_lshl_add_u64 v[66:67], v[100:101], 0, v[168:169]
	global_load_dwordx4 v[66:69], v[66:67], off offset:256
.LBB0_621:
	s_waitcnt vmcnt(3)
	v_lshlrev_b32_e32 v65, 16, v90
	v_mul_f32_e32 v65, 0xbfb8aa3b, v65
	v_exp_f32_e32 v65, v65
	v_and_b32_e32 v90, 0xffff0000, v90
	v_mul_f32_e32 v90, 0xbfb8aa3b, v90
	v_exp_f32_e32 v90, v90
	v_add_f32_e32 v65, 1.0, v65
	v_div_scale_f32 v100, s[4:5], v65, v65, 1.0
	v_rcp_f32_e32 v101, v100
	v_div_scale_f32 v102, vcc, 1.0, v65, 1.0
	v_add_f32_e32 v90, 1.0, v90
	v_fma_f32 v103, -v100, v101, 1.0
	v_fmac_f32_e32 v101, v103, v101
	v_mul_f32_e32 v103, v102, v101
	v_fma_f32 v104, -v100, v103, v102
	v_rcp_f32_e32 v65, v65
	s_nop 0
	v_lshlrev_b32_e32 v100, 16, v94
	v_fmac_f32_e32 v100, v60, v65
	v_lshlrev_b32_e32 v103, 16, v91
	v_mul_f32_e32 v103, 0xbfb8aa3b, v103
	v_exp_f32_e32 v103, v103
	v_rcp_f32_e32 v60, v90
	s_nop 0
	v_add_f32_e32 v65, 1.0, v103
	v_div_scale_f32 v101, s[4:5], v65, v65, 1.0
	v_rcp_f32_e32 v102, v101
	v_and_b32_e32 v90, 0xffff0000, v94
	v_fmac_f32_e32 v90, v61, v60
	v_and_b32_e32 v91, 0xffff0000, v91
	v_fma_f32 v60, -v101, v102, 1.0
	v_fmac_f32_e32 v102, v60, v102
	v_mul_f32_e32 v91, 0xbfb8aa3b, v91
	v_exp_f32_e32 v91, v91
	s_nop 0
	v_add_f32_e32 v61, 1.0, v91
	v_rcp_f32_e32 v60, v65
	s_nop 0
	v_lshlrev_b32_e32 v65, 16, v95
	v_fmac_f32_e32 v65, v62, v60
	v_lshlrev_b32_e32 v101, 16, v92
	v_mul_f32_e32 v101, 0xbfb8aa3b, v101
	v_exp_f32_e32 v101, v101
	v_rcp_f32_e32 v60, v61
	s_nop 0
	v_add_f32_e32 v62, 1.0, v101
	v_div_scale_f32 v91, s[4:5], v62, v62, 1.0
	v_rcp_f32_e32 v94, v91
	v_and_b32_e32 v61, 0xffff0000, v95
	v_fmac_f32_e32 v61, v63, v60
	v_and_b32_e32 v92, 0xffff0000, v92
	v_fma_f32 v60, -v91, v94, 1.0
	v_fmac_f32_e32 v94, v60, v94
	v_div_scale_f32 v60, vcc, 1.0, v62, 1.0
	v_mul_f32_e32 v92, 0xbfb8aa3b, v92
	v_mul_f32_e32 v63, v60, v94
	v_exp_f32_e32 v92, v92
	v_fma_f32 v95, -v91, v63, v60
	v_add_f32_e32 v63, 1.0, v92
	v_rcp_f32_e32 v60, v62
	s_nop 0
	v_lshlrev_b32_e32 v62, 16, v96
	v_fmac_f32_e32 v62, v56, v60
	v_lshlrev_b32_e32 v94, 16, v93
	v_mul_f32_e32 v94, 0xbfb8aa3b, v94
	v_exp_f32_e32 v94, v94
	v_rcp_f32_e32 v56, v63
	s_nop 0
	v_add_f32_e32 v60, 1.0, v94
	v_div_scale_f32 v91, s[4:5], v60, v60, 1.0
	v_rcp_f32_e32 v92, v91
	v_and_b32_e32 v63, 0xffff0000, v96
	v_fmac_f32_e32 v63, v57, v56
	v_and_b32_e32 v93, 0xffff0000, v93
	v_fma_f32 v56, -v91, v92, 1.0
	v_fmac_f32_e32 v92, v56, v92
	v_div_scale_f32 v56, vcc, 1.0, v60, 1.0
	v_mul_f32_e32 v93, 0xbfb8aa3b, v93
	v_mul_f32_e32 v57, v56, v92
	v_exp_f32_e32 v93, v93
	v_fma_f32 v94, -v91, v57, v56
	v_add_f32_e32 v57, 1.0, v93
	v_div_scale_f32 v91, s[4:5], v57, v57, 1.0
	v_rcp_f32_e32 v92, v91
	v_rcp_f32_e32 v56, v60
	s_nop 0
	v_lshlrev_b32_e32 v60, 16, v97
	v_fmac_f32_e32 v60, v58, v56
	v_fma_f32 v56, -v91, v92, 1.0
	v_fmac_f32_e32 v92, v56, v92
	v_div_scale_f32 v56, vcc, 1.0, v57, 1.0
	v_mul_f32_e32 v58, v56, v92
	v_fma_f32 v93, -v91, v58, v56
	v_rcp_f32_e32 v56, v57
	s_nop 0
	s_waitcnt vmcnt(2)
	v_lshlrev_b32_e32 v57, 16, v86
	v_and_b32_e32 v91, 0xffff0000, v97
	v_mul_f32_e32 v57, 0xbfb8aa3b, v57
	v_fmac_f32_e32 v91, v59, v56
	v_cvt_pk_bf16_f32 v56, v100, v90
	v_exp_f32_e32 v90, v57
	v_cvt_pk_bf16_f32 v58, v62, v63
	v_cvt_pk_bf16_f32 v57, v65, v61
	v_cvt_pk_bf16_f32 v59, v60, v91
	v_lshl_add_u64 v[60:61], s[58:59], 0, v[98:99]
	v_add_f32_e32 v62, 1.0, v90
	v_lshl_add_u64 v[60:61], v[60:61], 0, v[168:169]
	global_store_dwordx4 v[60:61], v[56:59], off
	s_nop 1
	v_and_b32_e32 v58, 0xffff0000, v86
	v_mul_f32_e32 v58, 0xbfb8aa3b, v58
	v_exp_f32_e32 v58, v58
	v_rcp_f32_e32 v56, v62
	s_nop 0
	v_add_f32_e32 v57, 1.0, v58
	v_lshlrev_b32_e32 v62, 16, v82
	v_fmac_f32_e32 v62, v52, v56
	v_mov_b32_e32 v65, 0
	v_lshlrev_b32_e32 v63, 16, v87
	v_mul_f32_e32 v63, 0xbfb8aa3b, v63
	v_exp_f32_e32 v63, v63
	v_rcp_f32_e32 v52, v57
	s_nop 0
	v_add_f32_e32 v56, 1.0, v63
	v_and_b32_e32 v57, 0xffff0000, v82
	v_fmac_f32_e32 v57, v53, v52
	v_and_b32_e32 v63, 0xffff0000, v87
	v_mul_f32_e32 v63, 0xbfb8aa3b, v63
	v_exp_f32_e32 v63, v63
	v_rcp_f32_e32 v52, v56
	s_nop 0
	v_add_f32_e32 v53, 1.0, v63
	v_lshlrev_b32_e32 v56, 16, v83
	v_fmac_f32_e32 v56, v54, v52
	v_lshlrev_b32_e32 v63, 16, v88
	v_mul_f32_e32 v63, 0xbfb8aa3b, v63
	v_exp_f32_e32 v63, v63
	v_rcp_f32_e32 v52, v53
	s_nop 0
	v_add_f32_e32 v54, 1.0, v63
	v_and_b32_e32 v53, 0xffff0000, v83
	v_fmac_f32_e32 v53, v55, v52
	v_and_b32_e32 v63, 0xffff0000, v88
	v_mul_f32_e32 v63, 0xbfb8aa3b, v63
	v_exp_f32_e32 v63, v63
	v_rcp_f32_e32 v52, v54
	s_nop 0
	v_add_f32_e32 v55, 1.0, v63
	v_lshlrev_b32_e32 v54, 16, v84
	v_fmac_f32_e32 v54, v48, v52
	v_lshlrev_b32_e32 v63, 16, v89
	v_mul_f32_e32 v63, 0xbfb8aa3b, v63
	v_exp_f32_e32 v63, v63
	v_rcp_f32_e32 v48, v55
	s_nop 0
	v_add_f32_e32 v52, 1.0, v63
	v_and_b32_e32 v55, 0xffff0000, v84
	v_fmac_f32_e32 v55, v49, v48
	v_and_b32_e32 v63, 0xffff0000, v89
	v_mul_f32_e32 v63, 0xbfb8aa3b, v63
	v_exp_f32_e32 v63, v63
	v_rcp_f32_e32 v48, v52
	s_nop 0
	v_add_f32_e32 v49, 1.0, v63
	v_lshlrev_b32_e32 v52, 16, v85
	v_fmac_f32_e32 v52, v50, v48
	v_rcp_f32_e32 v48, v49
	s_nop 0
	s_waitcnt vmcnt(2)
	v_lshlrev_b32_e32 v49, 16, v78
	v_mul_f32_e32 v49, 0xbfb8aa3b, v49
	v_exp_f32_e32 v50, v49
	v_cvt_pk_bf16_f32 v49, v56, v53
	v_and_b32_e32 v58, 0xffff0000, v85
	v_fmac_f32_e32 v58, v51, v48
	v_add_f32_e32 v53, 1.0, v50
	v_cvt_pk_bf16_f32 v48, v62, v57
	v_cvt_pk_bf16_f32 v50, v54, v55
	v_cvt_pk_bf16_f32 v51, v52, v58
	global_store_dwordx4 v[60:61], v[48:51], off offset:256
	v_lshlrev_b32_e32 v52, 16, v74
	v_mov_b32_e32 v62, 0
	v_and_b32_e32 v50, 0xffff0000, v78
	v_mul_f32_e32 v50, 0xbfb8aa3b, v50
	v_exp_f32_e32 v50, v50
	v_rcp_f32_e32 v48, v53
	s_nop 0
	v_add_f32_e32 v49, 1.0, v50
	v_fmac_f32_e32 v52, v44, v48
	v_mov_b32_e32 v63, 0
	v_lshlrev_b32_e32 v53, 16, v79
	v_mul_f32_e32 v53, 0xbfb8aa3b, v53
	v_exp_f32_e32 v53, v53
	v_rcp_f32_e32 v44, v49
	s_nop 0
	v_add_f32_e32 v48, 1.0, v53
	v_and_b32_e32 v49, 0xffff0000, v74
	v_fmac_f32_e32 v49, v45, v44
	v_and_b32_e32 v53, 0xffff0000, v79
	v_mul_f32_e32 v53, 0xbfb8aa3b, v53
	v_exp_f32_e32 v53, v53
	v_rcp_f32_e32 v44, v48
	s_nop 0
	v_add_f32_e32 v45, 1.0, v53
	v_lshlrev_b32_e32 v48, 16, v75
	v_fmac_f32_e32 v48, v46, v44
	v_lshlrev_b32_e32 v53, 16, v80
	v_mul_f32_e32 v53, 0xbfb8aa3b, v53
	v_exp_f32_e32 v53, v53
	v_rcp_f32_e32 v44, v45
	s_nop 0
	v_add_f32_e32 v46, 1.0, v53
	v_and_b32_e32 v45, 0xffff0000, v75
	v_fmac_f32_e32 v45, v47, v44
	v_and_b32_e32 v53, 0xffff0000, v80
	v_mul_f32_e32 v53, 0xbfb8aa3b, v53
	v_exp_f32_e32 v53, v53
	v_rcp_f32_e32 v44, v46
	s_nop 0
	v_add_f32_e32 v47, 1.0, v53
	v_lshlrev_b32_e32 v46, 16, v76
	v_fmac_f32_e32 v46, v40, v44
	v_lshlrev_b32_e32 v53, 16, v81
	v_mul_f32_e32 v53, 0xbfb8aa3b, v53
	v_exp_f32_e32 v53, v53
	v_rcp_f32_e32 v40, v47
	s_nop 0
	v_add_f32_e32 v44, 1.0, v53
	v_and_b32_e32 v47, 0xffff0000, v76
	v_fmac_f32_e32 v47, v41, v40
	v_and_b32_e32 v53, 0xffff0000, v81
	v_mul_f32_e32 v53, 0xbfb8aa3b, v53
	v_exp_f32_e32 v53, v53
	v_rcp_f32_e32 v40, v44
	s_nop 0
	v_add_f32_e32 v41, 1.0, v53
	v_div_scale_f32 v50, s[4:5], v41, v41, 1.0
	v_rcp_f32_e32 v51, v50
	v_lshlrev_b32_e32 v44, 16, v77
	v_fmac_f32_e32 v44, v42, v40
	s_mov_b64 s[4:5], 0x90000
	v_fma_f32 v40, -v50, v51, 1.0
	v_fmac_f32_e32 v51, v40, v51
	v_div_scale_f32 v40, vcc, 1.0, v41, 1.0
	v_mul_f32_e32 v42, v40, v51
	v_fma_f32 v53, -v50, v42, v40
	v_rcp_f32_e32 v40, v41
	s_nop 0
	v_and_b32_e32 v50, 0xffff0000, v77
	v_fmac_f32_e32 v50, v43, v40
	s_waitcnt vmcnt(2)
	v_lshlrev_b32_e32 v43, 16, v70
	v_mul_f32_e32 v43, 0xbfb8aa3b, v43
	v_cvt_pk_bf16_f32 v41, v48, v45
	v_exp_f32_e32 v48, v43
	v_cvt_pk_bf16_f32 v43, v44, v50
	v_lshl_add_u64 v[44:45], v[154:155], 0, v[168:169]
	v_cvt_pk_bf16_f32 v40, v52, v49
	v_add_f32_e32 v48, 1.0, v48
	v_cvt_pk_bf16_f32 v42, v46, v47
	v_lshl_add_u64 v[46:47], v[44:45], 0, s[4:5]
	v_div_scale_f32 v49, s[4:5], v48, v48, 1.0
	v_rcp_f32_e32 v50, v49
	s_mov_b32 s4, 0x90000
	v_add_co_u32_e32 v44, vcc, s4, v44
	s_nop 1
	v_addc_co_u32_e32 v45, vcc, 0, v45, vcc
	global_store_dwordx4 v[44:45], v[40:43], off
	v_lshlrev_b32_e32 v44, 16, v66
	s_nop 0
	v_fma_f32 v40, -v49, v50, 1.0
	v_fmac_f32_e32 v50, v40, v50
	v_and_b32_e32 v42, 0xffff0000, v70
	v_mul_f32_e32 v42, 0xbfb8aa3b, v42
	v_exp_f32_e32 v42, v42
	v_rcp_f32_e32 v40, v48
	s_nop 0
	v_add_f32_e32 v41, 1.0, v42
	v_fmac_f32_e32 v44, v36, v40
	v_lshlrev_b32_e32 v45, 16, v71
	v_mul_f32_e32 v45, 0xbfb8aa3b, v45
	v_exp_f32_e32 v45, v45
	v_rcp_f32_e32 v36, v41
	s_nop 0
	v_add_f32_e32 v40, 1.0, v45
	v_and_b32_e32 v41, 0xffff0000, v66
	v_fmac_f32_e32 v41, v37, v36
	v_and_b32_e32 v45, 0xffff0000, v71
	v_mul_f32_e32 v45, 0xbfb8aa3b, v45
	v_exp_f32_e32 v45, v45
	v_rcp_f32_e32 v36, v40
	s_nop 0
	v_add_f32_e32 v37, 1.0, v45
	v_lshlrev_b32_e32 v40, 16, v67
	v_fmac_f32_e32 v40, v38, v36
	v_lshlrev_b32_e32 v45, 16, v72
	v_mul_f32_e32 v45, 0xbfb8aa3b, v45
	v_exp_f32_e32 v45, v45
	v_rcp_f32_e32 v36, v37
	s_nop 0
	v_add_f32_e32 v38, 1.0, v45
	v_and_b32_e32 v37, 0xffff0000, v67
	v_fmac_f32_e32 v37, v39, v36
	v_and_b32_e32 v45, 0xffff0000, v72
	v_mul_f32_e32 v45, 0xbfb8aa3b, v45
	v_exp_f32_e32 v45, v45
	v_rcp_f32_e32 v36, v38
	s_nop 0
	v_add_f32_e32 v39, 1.0, v45
	v_lshlrev_b32_e32 v38, 16, v68
	v_fmac_f32_e32 v38, v32, v36
	v_lshlrev_b32_e32 v45, 16, v73
	v_mul_f32_e32 v45, 0xbfb8aa3b, v45
	v_exp_f32_e32 v45, v45
	v_rcp_f32_e32 v32, v39
	s_nop 0
	v_add_f32_e32 v36, 1.0, v45
	v_and_b32_e32 v39, 0xffff0000, v68
	v_fmac_f32_e32 v39, v33, v32
	v_and_b32_e32 v45, 0xffff0000, v73
	v_mul_f32_e32 v45, 0xbfb8aa3b, v45
	v_exp_f32_e32 v45, v45
	v_rcp_f32_e32 v32, v36
	s_nop 0
	v_add_f32_e32 v33, 1.0, v45
	v_div_scale_f32 v42, s[4:5], v33, v33, 1.0
	v_rcp_f32_e32 v43, v42
	v_lshlrev_b32_e32 v36, 16, v69
	v_fmac_f32_e32 v36, v34, v32
	v_fma_f32 v32, -v42, v43, 1.0
	v_fmac_f32_e32 v43, v32, v43
	v_div_scale_f32 v32, vcc, 1.0, v33, 1.0
	v_mul_f32_e32 v34, v32, v43
	v_fma_f32 v45, -v42, v34, v32
	v_rcp_f32_e32 v32, v33
	s_nop 0
	v_and_b32_e32 v42, 0xffff0000, v69
	v_fmac_f32_e32 v42, v35, v32
	v_cvt_pk_bf16_f32 v32, v44, v41
	v_cvt_pk_bf16_f32 v34, v38, v39
	v_cvt_pk_bf16_f32 v35, v36, v42
	v_cvt_pk_bf16_f32 v33, v40, v37
	global_store_dwordx4 v[46:47], v[32:35], off offset:256
	s_nop 1
	v_add_u32_e32 v32, 0xa0, v184
	v_mov_b64_e32 v[34:35], s[24:25]
	v_mad_i64_i32 v[34:35], s[4:5], v32, s82, v[34:35]
	v_lshl_add_u64 v[34:35], s[56:57], 1, v[34:35]
	v_lshl_add_u64 v[36:37], v[34:35], 0, v[168:169]
	v_add_co_u32_e32 v34, vcc, 0x5000, v36
	v_ashrrev_i32_e32 v33, 31, v32
	s_nop 0
	v_addc_co_u32_e32 v35, vcc, 0, v37, vcc
	global_load_dwordx4 v[56:59], v[34:35], off offset:2560 nt
	v_lshlrev_b64 v[60:61], 12, v[32:33]
	s_and_b64 vcc, exec, s[40:41]
	v_lshl_add_u64 v[34:35], s[42:43], 0, v[60:61]
	s_cbranch_vccnz .LBB0_623
	v_lshl_add_u64 v[38:39], v[34:35], 0, v[168:169]
	global_load_dwordx4 v[62:65], v[38:39], off
.LBB0_623:
	v_lshl_add_u64 v[36:37], v[36:37], 0, s[8:9]
	global_load_dwordx4 v[52:55], v[36:37], off offset:256 nt
	v_mov_b32_e32 v42, 0
	s_and_b64 vcc, exec, s[40:41]
	v_mov_b32_e32 v50, 0
	v_mov_b32_e32 v51, 0
	v_mov_b32_e32 v48, 0
	v_mov_b32_e32 v49, 0
	s_cbranch_vccnz .LBB0_625
	v_lshl_add_u64 v[34:35], v[34:35], 0, v[168:169]
	global_load_dwordx4 v[48:51], v[34:35], off offset:256
.LBB0_625:
	v_or_b32_e32 v34, 16, v32
	v_mov_b64_e32 v[32:33], s[24:25]
	v_mad_i64_i32 v[32:33], s[4:5], v34, s82, v[32:33]
	v_lshl_add_u64 v[32:33], s[56:57], 1, v[32:33]
	v_lshl_add_u64 v[32:33], v[32:33], 0, v[168:169]
	v_add_co_u32_e32 v36, vcc, 0x5000, v32
	v_ashrrev_i32_e32 v35, 31, v34
	s_nop 0
	v_addc_co_u32_e32 v37, vcc, 0, v33, vcc
	global_load_dwordx4 v[44:47], v[36:37], off offset:2560 nt
	v_lshlrev_b64 v[34:35], 12, v[34:35]
	s_and_b64 vcc, exec, s[40:41]
	v_lshl_add_u64 v[34:35], s[42:43], 0, v[34:35]
	v_mov_b32_e32 v43, 0
	v_mov_b32_e32 v40, 0
	v_mov_b32_e32 v41, 0
	s_cbranch_vccnz .LBB0_627
	v_lshl_add_u64 v[36:37], v[34:35], 0, v[168:169]
	global_load_dwordx4 v[40:43], v[36:37], off
.LBB0_627:
	v_lshl_add_u64 v[32:33], v[32:33], 0, s[8:9]
	global_load_dwordx4 v[36:39], v[32:33], off offset:256 nt
	s_and_b64 vcc, exec, s[40:41]
	s_cbranch_vccnz .LBB0_629
	v_lshl_add_u64 v[32:33], v[34:35], 0, v[168:169]
	global_load_dwordx4 v[32:35], v[32:33], off offset:256
	s_branch .LBB0_630

.LBB0_716:
	v_lshlrev_b64 v[144:145], 13, v[144:145]
	v_lshl_add_u64 v[144:145], v[146:147], 0, v[144:145]
	v_lshl_add_u64 v[144:145], v[188:189], 2, v[144:145]
	global_load_dwordx4 v[148:151], v[144:145], off nt
	s_nop 0
	global_load_dwordx4 v[144:147], v[144:145], off offset:64 nt
	v_cndmask_b32_e64 v152, 0, 1, s[2:3]
	v_cmp_ne_u32_e64 s[40:41], 1, v152
	s_andn2_b64 vcc, exec, s[2:3]
	s_mov_b64 s[18:19], -1
	s_cbranch_vccnz .LBB0_718
	s_mov_b64 s[18:19], 0
	v_mov_b64_e32 v[152:153], v[186:187]

.LBB0_724:
	v_lshlrev_b64 v[152:153], 13, v[152:153]
	v_lshl_add_u64 v[152:153], v[154:155], 0, v[152:153]
	v_lshl_add_u64 v[152:153], v[188:189], 2, v[152:153]
	global_load_dwordx4 v[156:159], v[152:153], off offset:512 nt
	s_nop 0
	global_load_dwordx4 v[152:155], v[152:153], off offset:576 nt
	v_or_b32_e32 v192, 16, v186
	s_and_b64 vcc, exec, s[40:41]
	s_mov_b64 s[18:19], -1
	s_cbranch_vccnz .LBB0_726
	v_ashrrev_i32_e32 v193, 31, v192
	s_mov_b64 s[18:19], 0
	v_mov_b64_e32 v[160:161], v[192:193]

.LBB0_732:
	v_lshlrev_b64 v[160:161], 13, v[160:161]
	v_lshl_add_u64 v[160:161], v[162:163], 0, v[160:161]
	v_lshl_add_u64 v[160:161], v[188:189], 2, v[160:161]
	global_load_dwordx4 v[164:167], v[160:161], off nt
	s_nop 0
	global_load_dwordx4 v[160:163], v[160:161], off offset:64 nt
	s_and_b64 vcc, exec, s[40:41]
	s_mov_b64 s[18:19], -1
	s_cbranch_vccnz .LBB0_734
	v_ashrrev_i32_e32 v193, 31, v192
	s_mov_b64 s[18:19], 0

.LBB0_740:
	v_lshlrev_b64 v[194:195], 13, v[194:195]
	v_lshl_add_u64 v[194:195], v[190:191], 0, v[194:195]
	v_lshlrev_b64 v[190:191], 2, v[188:189]
	v_lshl_add_u64 v[194:195], v[194:195], 0, v[190:191]
	global_load_dwordx4 v[222:225], v[194:195], off offset:512 nt
	global_load_dwordx4 v[226:229], v[194:195], off offset:576 nt
	s_waitcnt vmcnt(0)
	v_pk_fma_f32 v[140:141], v[140:141], v[76:77], v[148:149]
	v_lshlrev_b64 v[148:149], 13, v[186:187]
	v_pk_fma_f32 v[146:147], v[138:139], v[74:75], v[146:147]
	v_lshlrev_b64 v[138:139], 13, v[192:193]
	v_pk_fma_f32 v[144:145], v[136:137], v[72:73], v[144:145]
	v_or_b32_e32 v136, 32, v186
	v_lshl_add_u64 v[148:149], s[52:53], 0, v[148:149]
	v_lshl_add_u64 v[138:139], s[52:53], 0, v[138:139]
	v_pk_fma_f32 v[142:143], v[142:143], v[78:79], v[150:151]
	s_mov_b64 s[18:19], -1
	s_and_b64 vcc, exec, s[40:41]
	v_lshl_add_u64 v[148:149], v[148:149], 0, v[190:191]
	v_lshl_add_u64 v[138:139], v[138:139], 0, v[190:191]
	v_ashrrev_i32_e32 v137, 31, v136
	v_pk_fma_f32 v[130:131], v[130:131], v[66:67], v[158:159]
	v_pk_fma_f32 v[128:129], v[128:129], v[64:65], v[156:157]
	v_pk_fma_f32 v[126:127], v[126:127], v[70:71], v[154:155]
	v_pk_fma_f32 v[124:125], v[124:125], v[68:69], v[152:153]
	v_pk_fma_f32 v[134:135], v[134:135], v[78:79], v[166:167]
	v_pk_fma_f32 v[132:133], v[132:133], v[76:77], v[164:165]
	v_pk_fma_f32 v[122:123], v[122:123], v[74:75], v[162:163]
	v_pk_fma_f32 v[120:121], v[120:121], v[72:73], v[160:161]
	global_store_dwordx4 v[148:149], v[140:143], off
	global_store_dwordx4 v[148:149], v[144:147], off offset:64
	global_store_dwordx4 v[148:149], v[128:131], off offset:512
	global_store_dwordx4 v[148:149], v[124:127], off offset:576
	global_store_dwordx4 v[138:139], v[132:135], off
	global_store_dwordx4 v[138:139], v[120:123], off offset:64
	v_pk_fma_f32 v[118:119], v[118:119], v[66:67], v[224:225]
	v_pk_fma_f32 v[116:117], v[116:117], v[64:65], v[222:223]
	v_pk_fma_f32 v[112:113], v[112:113], v[68:69], v[226:227]
	v_pk_fma_f32 v[114:115], v[114:115], v[70:71], v[228:229]
	global_store_dwordx4 v[138:139], v[116:119], off offset:512
	global_store_dwordx4 v[138:139], v[112:115], off offset:576
	s_cbranch_vccnz .LBB0_742
	s_mov_b64 s[18:19], 0
	v_mov_b64_e32 v[112:113], v[136:137]

.LBB0_748:
	v_lshlrev_b64 v[112:113], 13, v[112:113]
	v_lshl_add_u64 v[112:113], v[114:115], 0, v[112:113]
	v_lshl_add_u64 v[112:113], v[188:189], 2, v[112:113]
	global_load_dwordx4 v[116:119], v[112:113], off nt
	s_nop 0
	global_load_dwordx4 v[112:115], v[112:113], off offset:64 nt
	s_and_b64 vcc, exec, s[40:41]
	s_mov_b64 s[18:19], -1
	s_cbranch_vccnz .LBB0_750
	s_mov_b64 s[18:19], 0
	v_mov_b64_e32 v[120:121], v[136:137]

.LBB0_756:
	v_lshlrev_b64 v[120:121], 13, v[120:121]
	v_lshl_add_u64 v[120:121], v[122:123], 0, v[120:121]
	v_lshl_add_u64 v[120:121], v[188:189], 2, v[120:121]
	global_load_dwordx4 v[124:127], v[120:121], off offset:512 nt
	s_nop 0
	global_load_dwordx4 v[120:123], v[120:121], off offset:576 nt
	v_or_b32_e32 v138, 48, v186
	s_and_b64 vcc, exec, s[40:41]
	s_mov_b64 s[18:19], -1
	s_cbranch_vccnz .LBB0_758
	v_ashrrev_i32_e32 v139, 31, v138
	s_mov_b64 s[18:19], 0
	v_mov_b64_e32 v[128:129], v[138:139]

.LBB0_764:
	v_lshlrev_b64 v[128:129], 13, v[128:129]
	v_lshl_add_u64 v[128:129], v[130:131], 0, v[128:129]
	v_lshl_add_u64 v[128:129], v[188:189], 2, v[128:129]
	global_load_dwordx4 v[132:135], v[128:129], off nt
	s_nop 0
	global_load_dwordx4 v[128:131], v[128:129], off offset:64 nt
	s_and_b64 vcc, exec, s[40:41]
	s_mov_b64 s[18:19], -1
	s_cbranch_vccnz .LBB0_766
	v_ashrrev_i32_e32 v139, 31, v138
	s_mov_b64 s[18:19], 0

.LBB0_772:
	v_lshlrev_b64 v[142:143], 13, v[142:143]
	v_lshl_add_u64 v[140:141], v[140:141], 0, v[142:143]
	v_lshl_add_u64 v[144:145], v[140:141], 0, v[190:191]
	global_load_dwordx4 v[140:143], v[144:145], off offset:512 nt
	s_nop 0
	global_load_dwordx4 v[144:147], v[144:145], off offset:576 nt
	s_waitcnt vmcnt(7)
	v_pk_fma_f32 v[108:109], v[108:109], v[76:77], v[116:117]
	v_lshlrev_b64 v[116:117], 13, v[136:137]
	s_waitcnt vmcnt(6)
	v_pk_fma_f32 v[114:115], v[106:107], v[74:75], v[114:115]
	v_lshlrev_b64 v[106:107], 13, v[138:139]
	v_pk_fma_f32 v[112:113], v[104:105], v[72:73], v[112:113]
	v_add_u32_e32 v104, 0x80, v186
	v_lshl_add_u64 v[116:117], s[52:53], 0, v[116:117]
	v_lshl_add_u64 v[106:107], s[52:53], 0, v[106:107]
	v_pk_fma_f32 v[110:111], v[110:111], v[78:79], v[118:119]
	s_mov_b64 s[18:19], -1
	s_and_b64 vcc, exec, s[40:41]
	v_lshl_add_u64 v[116:117], v[116:117], 0, v[190:191]
	v_lshl_add_u64 v[106:107], v[106:107], 0, v[190:191]
	v_ashrrev_i32_e32 v105, 31, v104
	s_waitcnt vmcnt(5)
	v_pk_fma_f32 v[98:99], v[98:99], v[66:67], v[126:127]
	v_pk_fma_f32 v[96:97], v[96:97], v[64:65], v[124:125]
	s_waitcnt vmcnt(4)
	v_pk_fma_f32 v[94:95], v[94:95], v[70:71], v[122:123]
	v_pk_fma_f32 v[92:93], v[92:93], v[68:69], v[120:121]
	s_waitcnt vmcnt(3)
	v_pk_fma_f32 v[102:103], v[102:103], v[78:79], v[134:135]
	v_pk_fma_f32 v[100:101], v[100:101], v[76:77], v[132:133]
	s_waitcnt vmcnt(2)
	v_pk_fma_f32 v[90:91], v[90:91], v[74:75], v[130:131]
	v_pk_fma_f32 v[88:89], v[88:89], v[72:73], v[128:129]
	global_store_dwordx4 v[116:117], v[108:111], off
	global_store_dwordx4 v[116:117], v[112:115], off offset:64
	global_store_dwordx4 v[116:117], v[96:99], off offset:512
	global_store_dwordx4 v[116:117], v[92:95], off offset:576
	global_store_dwordx4 v[106:107], v[100:103], off
	global_store_dwordx4 v[106:107], v[88:91], off offset:64
	s_waitcnt vmcnt(7)
	v_pk_fma_f32 v[86:87], v[86:87], v[66:67], v[142:143]
	v_pk_fma_f32 v[84:85], v[84:85], v[64:65], v[140:141]
	s_waitcnt vmcnt(6)
	v_pk_fma_f32 v[80:81], v[80:81], v[68:69], v[144:145]
	v_pk_fma_f32 v[82:83], v[82:83], v[70:71], v[146:147]
	global_store_dwordx4 v[106:107], v[84:87], off offset:512
	global_store_dwordx4 v[106:107], v[80:83], off offset:576
	s_cbranch_vccnz .LBB0_774
	s_mov_b64 s[18:19], 0
	v_mov_b64_e32 v[80:81], v[104:105]

.LBB0_780:
	v_lshlrev_b64 v[80:81], 13, v[80:81]
	v_lshl_add_u64 v[80:81], v[82:83], 0, v[80:81]
	v_lshl_add_u64 v[80:81], v[188:189], 2, v[80:81]
	global_load_dwordx4 v[84:87], v[80:81], off nt
	s_nop 0
	global_load_dwordx4 v[80:83], v[80:81], off offset:64 nt
	s_and_b64 vcc, exec, s[40:41]
	s_mov_b64 s[18:19], -1
	s_cbranch_vccnz .LBB0_782
	s_mov_b64 s[18:19], 0
	v_mov_b64_e32 v[88:89], v[104:105]

.LBB0_788:
	v_lshlrev_b64 v[88:89], 13, v[88:89]
	v_lshl_add_u64 v[88:89], v[90:91], 0, v[88:89]
	v_lshl_add_u64 v[88:89], v[188:189], 2, v[88:89]
	global_load_dwordx4 v[92:95], v[88:89], off offset:512 nt
	s_nop 0
	global_load_dwordx4 v[88:91], v[88:89], off offset:576 nt
	v_or_b32_e32 v106, 16, v104
	s_and_b64 vcc, exec, s[40:41]
	s_mov_b64 s[18:19], -1
	s_cbranch_vccnz .LBB0_790
	v_ashrrev_i32_e32 v107, 31, v106
	s_mov_b64 s[18:19], 0
	v_mov_b64_e32 v[96:97], v[106:107]

.LBB0_796:
	v_lshlrev_b64 v[96:97], 13, v[96:97]
	v_lshl_add_u64 v[96:97], v[98:99], 0, v[96:97]
	v_lshl_add_u64 v[96:97], v[188:189], 2, v[96:97]
	global_load_dwordx4 v[100:103], v[96:97], off nt
	s_nop 0
	global_load_dwordx4 v[96:99], v[96:97], off offset:64 nt
	s_and_b64 vcc, exec, s[40:41]
	s_mov_b64 s[18:19], -1
	s_cbranch_vccnz .LBB0_798
	v_ashrrev_i32_e32 v107, 31, v106
	s_mov_b64 s[18:19], 0

.LBB0_804:
	v_lshlrev_b64 v[106:107], 13, v[106:107]
	v_lshl_add_u64 v[106:107], v[108:109], 0, v[106:107]
	v_lshl_add_u64 v[110:111], v[106:107], 0, v[190:191]
	global_load_dwordx4 v[106:109], v[110:111], off offset:512 nt
	s_nop 0
	global_load_dwordx4 v[110:113], v[110:111], off offset:576 nt
	s_waitcnt vmcnt(7)
	v_pk_fma_f32 v[60:61], v[60:61], v[76:77], v[84:85]
	v_lshlrev_b64 v[84:85], 13, v[104:105]
	s_waitcnt vmcnt(6)
	v_pk_fma_f32 v[82:83], v[58:59], v[74:75], v[82:83]
	v_add_u32_e32 v58, 0x90, v186
	v_lshl_add_u64 v[84:85], s[52:53], 0, v[84:85]
	v_ashrrev_i32_e32 v59, 31, v58
	v_pk_fma_f32 v[62:63], v[62:63], v[78:79], v[86:87]
	s_waitcnt vmcnt(4)
	v_pk_fma_f32 v[44:45], v[44:45], v[68:69], v[88:89]
	v_lshl_add_u64 v[84:85], v[84:85], 0, v[190:191]
	v_lshlrev_b64 v[58:59], 13, v[58:59]
	v_pk_fma_f32 v[80:81], v[56:57], v[72:73], v[80:81]
	v_pk_fma_f32 v[54:55], v[54:55], v[66:67], v[94:95]
	v_pk_fma_f32 v[52:53], v[52:53], v[64:65], v[92:93]
	v_pk_fma_f32 v[46:47], v[46:47], v[70:71], v[90:91]
	v_add_u32_e32 v56, 0xa0, v186
	global_store_dwordx4 v[84:85], v[60:63], off
	global_store_dwordx4 v[84:85], v[80:83], off offset:64
	global_store_dwordx4 v[84:85], v[52:55], off offset:512
	global_store_dwordx4 v[84:85], v[44:47], off offset:576
	s_waitcnt vmcnt(7)
	v_pk_fma_f32 v[50:51], v[50:51], v[78:79], v[102:103]
	v_pk_fma_f32 v[48:49], v[48:49], v[76:77], v[100:101]
	v_lshl_add_u64 v[44:45], s[52:53], 0, v[58:59]
	s_mov_b64 s[18:19], -1
	s_and_b64 vcc, exec, s[40:41]
	v_lshl_add_u64 v[44:45], v[44:45], 0, v[190:191]
	v_ashrrev_i32_e32 v57, 31, v56
	s_waitcnt vmcnt(6)
	v_pk_fma_f32 v[42:43], v[42:43], v[74:75], v[98:99]
	v_pk_fma_f32 v[40:41], v[40:41], v[72:73], v[96:97]
	global_store_dwordx4 v[44:45], v[48:51], off
	global_store_dwordx4 v[44:45], v[40:43], off offset:64
	s_waitcnt vmcnt(7)
	v_pk_fma_f32 v[38:39], v[38:39], v[66:67], v[108:109]
	v_pk_fma_f32 v[36:37], v[36:37], v[64:65], v[106:107]
	s_waitcnt vmcnt(6)
	v_pk_fma_f32 v[32:33], v[32:33], v[68:69], v[110:111]
	v_pk_fma_f32 v[34:35], v[34:35], v[70:71], v[112:113]
	global_store_dwordx4 v[44:45], v[36:39], off offset:512
	global_store_dwordx4 v[44:45], v[32:35], off offset:576
	s_cbranch_vccnz .LBB0_806
	s_mov_b64 s[18:19], 0
	v_mov_b64_e32 v[32:33], v[56:57]

.LBB0_812:
	v_lshlrev_b64 v[32:33], 13, v[32:33]
	v_lshl_add_u64 v[32:33], v[34:35], 0, v[32:33]
	v_lshl_add_u64 v[32:33], v[188:189], 2, v[32:33]
	global_load_dwordx4 v[36:39], v[32:33], off nt
	s_nop 0
	global_load_dwordx4 v[32:35], v[32:33], off offset:64 nt
	s_and_b64 vcc, exec, s[40:41]
	s_mov_b64 s[18:19], -1
	s_cbranch_vccnz .LBB0_814
	s_mov_b64 s[18:19], 0
	v_mov_b64_e32 v[40:41], v[56:57]

.LBB0_820:
	v_lshlrev_b64 v[40:41], 13, v[40:41]
	v_lshl_add_u64 v[40:41], v[42:43], 0, v[40:41]
	v_lshl_add_u64 v[40:41], v[188:189], 2, v[40:41]
	global_load_dwordx4 v[44:47], v[40:41], off offset:512 nt
	s_nop 0
	global_load_dwordx4 v[40:43], v[40:41], off offset:576 nt
	v_or_b32_e32 v58, 16, v56
	s_and_b64 vcc, exec, s[40:41]
	s_mov_b64 s[18:19], -1
	s_cbranch_vccnz .LBB0_822
	v_ashrrev_i32_e32 v59, 31, v58
	s_mov_b64 s[18:19], 0
	v_mov_b64_e32 v[48:49], v[58:59]

.LBB0_828:
	v_lshlrev_b64 v[48:49], 13, v[48:49]
	v_lshl_add_u64 v[48:49], v[50:51], 0, v[48:49]
	v_lshl_add_u64 v[48:49], v[188:189], 2, v[48:49]
	global_load_dwordx4 v[52:55], v[48:49], off nt
	s_nop 0
	global_load_dwordx4 v[48:51], v[48:49], off offset:64 nt
	s_and_b64 vcc, exec, s[40:41]
	s_mov_b64 s[18:19], -1
	s_cbranch_vccnz .LBB0_830
	v_ashrrev_i32_e32 v59, 31, v58
	s_mov_b64 s[18:19], 0

.LBB0_836:
	v_lshlrev_b64 v[58:59], 13, v[58:59]
	v_lshl_add_u64 v[58:59], v[60:61], 0, v[58:59]
	v_lshl_add_u64 v[62:63], v[58:59], 0, v[190:191]
	global_load_dwordx4 v[58:61], v[62:63], off offset:512 nt
	global_load_dwordx4 v[80:83], v[62:63], off offset:576 nt
	s_waitcnt vmcnt(7)
	v_pk_fma_f32 v[28:29], v[28:29], v[76:77], v[36:37]
	v_lshlrev_b64 v[36:37], 13, v[56:57]
	s_waitcnt vmcnt(6)
	v_pk_fma_f32 v[24:25], v[24:25], v[72:73], v[32:33]
	v_add_u32_e32 v32, 0xb0, v186
	v_pk_fma_f32 v[26:27], v[26:27], v[74:75], v[34:35]
	v_lshl_add_u64 v[34:35], s[52:53], 0, v[36:37]
	v_ashrrev_i32_e32 v33, 31, v32
	v_pk_fma_f32 v[30:31], v[30:31], v[78:79], v[38:39]
	s_waitcnt vmcnt(4)
	v_pk_fma_f32 v[12:13], v[12:13], v[68:69], v[40:41]
	v_lshl_add_u64 v[34:35], v[34:35], 0, v[190:191]
	v_lshlrev_b64 v[32:33], 13, v[32:33]
	v_pk_fma_f32 v[22:23], v[22:23], v[66:67], v[46:47]
	v_pk_fma_f32 v[20:21], v[20:21], v[64:65], v[44:45]
	v_pk_fma_f32 v[14:15], v[14:15], v[70:71], v[42:43]
	global_store_dwordx4 v[34:35], v[28:31], off
	global_store_dwordx4 v[34:35], v[24:27], off offset:64
	global_store_dwordx4 v[34:35], v[20:23], off offset:512
	global_store_dwordx4 v[34:35], v[12:15], off offset:576
	s_waitcnt vmcnt(7)
	v_pk_fma_f32 v[18:19], v[18:19], v[78:79], v[54:55]
	v_pk_fma_f32 v[16:17], v[16:17], v[76:77], v[52:53]
	v_lshl_add_u64 v[12:13], s[52:53], 0, v[32:33]
	s_andn2_b64 vcc, exec, s[38:39]
	v_lshl_add_u64 v[12:13], v[12:13], 0, v[190:191]
	s_mov_b64 s[18:19], -1
	s_waitcnt vmcnt(6)
	v_pk_fma_f32 v[10:11], v[10:11], v[74:75], v[50:51]
	v_pk_fma_f32 v[8:9], v[8:9], v[72:73], v[48:49]
	global_store_dwordx4 v[12:13], v[16:19], off
	global_store_dwordx4 v[12:13], v[8:11], off offset:64
	s_waitcnt vmcnt(7)
	v_pk_fma_f32 v[6:7], v[6:7], v[66:67], v[60:61]
	v_pk_fma_f32 v[4:5], v[4:5], v[64:65], v[58:59]
	s_waitcnt vmcnt(6)
	v_pk_fma_f32 v[2:3], v[2:3], v[70:71], v[82:83]
	v_pk_fma_f32 v[0:1], v[0:1], v[68:69], v[80:81]
	global_store_dwordx4 v[12:13], v[4:7], off offset:512
	global_store_dwordx4 v[12:13], v[0:3], off offset:576
	s_cbranch_vccnz .LBB0_697
	s_andn2_b64 vcc, exec, s[0:1]
	s_cbranch_vccnz .LBB0_696
	s_barrier
	s_branch .LBB0_696
